# gate/up epilogue stores with sc0 sc1 (system scope write-through) instead of sc1
# speedup vs baseline: 1.0045x; 1.0045x over previous
.LBB0_140:
	s_lshl_b32 s19, s67, 11
	s_add_i32 s19, s19, 0
	s_add_i32 s21, s19, 0x20180
	s_lshl_b32 s19, s45, 2
	s_add_i32 s19, s21, s19
	v_lshl_add_u32 v154, v165, 2, s19
	ds_read_b128 v[146:149], v154 offset:1024
	ds_read_b128 v[150:153], v154 offset:1536
	ds_read_b128 v[182:185], v154 offset:1040
	ds_read_b128 v[186:189], v154 offset:1552
	v_cvt_f32_i32_e32 v127, v127
	v_cvt_f32_i32_e32 v126, v126
	s_waitcnt lgkmcnt(0)
	v_pk_mul_f32 v[154:155], v[148:149], v[152:153]
	v_pk_mul_f32 v[158:159], v[146:147], v[150:151]
	v_pk_mul_f32 v[152:153], v[182:183], s[16:17] op_sel_hi:[1,0]
	v_pk_mul_f32 v[150:151], v[182:183], v[186:187]
	v_lshl_add_u32 v182, v167, 2, s21
	ds_read_b32 v186, v182
	v_cvt_f32_i32_e32 v123, v123
	v_cvt_f32_i32_e32 v122, v122
	v_pk_mul_f32 v[160:161], v[146:147], s[16:17] op_sel_hi:[1,0]
	v_cvt_f32_i32_e32 v129, v129
	v_cvt_f32_i32_e32 v128, v128
	s_waitcnt lgkmcnt(0)
	v_pk_mul_f32 v[190:191], v[160:161], v[186:187] op_sel_hi:[1,0]
	v_mul_f32_e32 v192, v186, v186
	v_pk_mul_f32 v[156:157], v[148:149], s[16:17] op_sel_hi:[1,0]
	v_pk_mul_f32 v[190:191], v[190:191], v[126:127]
	v_pk_mul_f32 v[122:123], v[126:127], v[122:123]
	v_pk_mul_f32 v[126:127], v[158:159], v[192:193] op_sel_hi:[1,0]
	v_cvt_f32_i32_e32 v125, v125
	v_pk_mul_f32 v[122:123], v[122:123], v[126:127]
	v_pk_mul_f32 v[126:127], v[156:157], v[186:187] op_sel_hi:[1,0]
	v_cvt_f32_i32_e32 v124, v124
	v_pk_mul_f32 v[126:127], v[126:127], v[128:129]
	v_exp_f32_e32 v190, v190
	v_exp_f32_e32 v126, v126
	v_exp_f32_e32 v127, v127
	v_exp_f32_e32 v191, v191
	v_cvt_f32_i32_e32 v119, v119
	v_cvt_f32_i32_e32 v118, v118
	v_pk_add_f32 v[126:127], v[126:127], 1.0 op_sel_hi:[1,0]
	v_pk_mul_f32 v[124:125], v[128:129], v[124:125]
	v_rcp_f32_e32 v126, v126
	v_rcp_f32_e32 v127, v127
	v_pk_mul_f32 v[128:129], v[154:155], v[192:193] op_sel_hi:[1,0]
	v_pk_add_f32 v[190:191], v[190:191], 1.0 op_sel_hi:[1,0]
	v_pk_mul_f32 v[124:125], v[124:125], v[128:129]
	v_rcp_f32_e32 v190, v190
	v_pk_mul_f32 v[124:125], v[124:125], v[126:127]
	v_pk_mul_f32 v[126:127], v[152:153], v[186:187] op_sel_hi:[1,0]
	v_rcp_f32_e32 v191, v191
	v_pk_mul_f32 v[126:127], v[126:127], v[118:119]
	v_cvt_f32_i32_e32 v115, v115
	v_exp_f32_e32 v126, v126
	v_exp_f32_e32 v127, v127
	v_cvt_f32_i32_e32 v114, v114
	v_cvt_f32_i32_e32 v121, v121
	v_cvt_f32_i32_e32 v120, v120
	v_pk_mul_f32 v[122:123], v[122:123], v[190:191]
	v_pk_mul_f32 v[148:149], v[184:185], s[16:17] op_sel_hi:[1,0]
	v_cvt_pk_bf16_f32 v122, v122, v123
	v_cvt_pk_bf16_f32 v123, v124, v125
	v_pk_add_f32 v[124:125], v[126:127], 1.0 op_sel_hi:[1,0]
	v_pk_mul_f32 v[114:115], v[118:119], v[114:115]
	v_pk_mul_f32 v[118:119], v[150:151], v[192:193] op_sel_hi:[1,0]
	v_rcp_f32_e32 v124, v124
	v_rcp_f32_e32 v125, v125
	v_pk_mul_f32 v[114:115], v[114:115], v[118:119]
	v_pk_mul_f32 v[118:119], v[148:149], v[186:187] op_sel_hi:[1,0]
	v_pk_mul_f32 v[146:147], v[184:185], v[188:189]
	v_pk_mul_f32 v[118:119], v[118:119], v[120:121]
	v_pk_mul_f32 v[114:115], v[114:115], v[124:125]
	v_exp_f32_e32 v118, v118
	v_exp_f32_e32 v119, v119
	v_cvt_pk_bf16_f32 v124, v114, v115
	v_cvt_f32_i32_e32 v115, v117
	v_cvt_f32_i32_e32 v114, v116
	v_pk_add_f32 v[116:117], v[118:119], 1.0 op_sel_hi:[1,0]
	v_pk_mul_f32 v[118:119], v[146:147], v[192:193] op_sel_hi:[1,0]
	v_rcp_f32_e32 v116, v116
	v_rcp_f32_e32 v117, v117
	v_pk_mul_f32 v[114:115], v[120:121], v[114:115]
	v_lshl_or_b32 v184, s66, 7, v177
	s_lshl_b32 s19, s26, 8
	v_pk_mul_f32 v[114:115], v[114:115], v[118:119]
	v_ashrrev_i32_e32 v185, 31, v184
	v_add_u32_e32 v183, s19, v167
	v_mov_b64_e32 v[162:163], s[60:61]
	v_pk_mul_f32 v[114:115], v[114:115], v[116:117]
	v_mad_i64_i32 v[188:189], s[28:29], v183, s64, v[162:163]
	v_cvt_pk_bf16_f32 v125, v114, v115
	v_lshlrev_b64 v[114:115], 1, v[184:185]
	v_lshl_add_u64 v[116:117], v[188:189], 0, v[114:115]
	global_store_dwordx4 v[116:117], v[122:125], off sc0 sc1
	ds_read_b32 v116, v182 offset:64
	v_cvt_f32_i32_e32 v111, v111
	v_cvt_f32_i32_e32 v110, v110
	v_cvt_f32_i32_e32 v107, v107
	v_cvt_f32_i32_e32 v106, v106
	v_add_u32_e32 v117, s19, v170
	v_cvt_f32_i32_e32 v113, v113
	v_cvt_f32_i32_e32 v112, v112
	s_waitcnt lgkmcnt(0)
	v_pk_mul_f32 v[120:121], v[160:161], v[116:117] op_sel_hi:[1,0]
	v_mul_f32_e32 v122, v116, v116
	v_pk_mul_f32 v[120:121], v[120:121], v[110:111]
	v_pk_mul_f32 v[106:107], v[110:111], v[106:107]
	v_pk_mul_f32 v[110:111], v[158:159], v[122:123] op_sel_hi:[1,0]
	v_cvt_f32_i32_e32 v109, v109
	v_pk_mul_f32 v[106:107], v[106:107], v[110:111]
	v_pk_mul_f32 v[110:111], v[156:157], v[116:117] op_sel_hi:[1,0]
	v_cvt_f32_i32_e32 v108, v108
	v_pk_mul_f32 v[110:111], v[110:111], v[112:113]
	v_exp_f32_e32 v120, v120
	v_exp_f32_e32 v110, v110
	v_exp_f32_e32 v111, v111
	v_exp_f32_e32 v121, v121
	v_cvt_f32_i32_e32 v103, v103
	v_cvt_f32_i32_e32 v102, v102
	v_pk_add_f32 v[110:111], v[110:111], 1.0 op_sel_hi:[1,0]
	v_pk_mul_f32 v[108:109], v[112:113], v[108:109]
	v_rcp_f32_e32 v110, v110
	v_rcp_f32_e32 v111, v111
	v_pk_mul_f32 v[112:113], v[154:155], v[122:123] op_sel_hi:[1,0]
	v_pk_add_f32 v[120:121], v[120:121], 1.0 op_sel_hi:[1,0]
	v_pk_mul_f32 v[108:109], v[108:109], v[112:113]
	v_rcp_f32_e32 v120, v120
	v_pk_mul_f32 v[108:109], v[108:109], v[110:111]
	v_pk_mul_f32 v[110:111], v[152:153], v[116:117] op_sel_hi:[1,0]
	v_rcp_f32_e32 v121, v121
	v_pk_mul_f32 v[110:111], v[110:111], v[102:103]
	v_cvt_f32_i32_e32 v99, v99
	v_exp_f32_e32 v110, v110
	v_exp_f32_e32 v111, v111
	v_cvt_f32_i32_e32 v98, v98
	v_cvt_f32_i32_e32 v105, v105
	v_cvt_f32_i32_e32 v104, v104
	v_pk_mul_f32 v[106:107], v[106:107], v[120:121]
	v_pk_mul_f32 v[98:99], v[102:103], v[98:99]
	v_cvt_pk_bf16_f32 v106, v106, v107
	v_cvt_pk_bf16_f32 v107, v108, v109
	v_pk_add_f32 v[108:109], v[110:111], 1.0 op_sel_hi:[1,0]
	v_pk_mul_f32 v[102:103], v[150:151], v[122:123] op_sel_hi:[1,0]
	v_rcp_f32_e32 v108, v108
	v_rcp_f32_e32 v109, v109
	v_pk_mul_f32 v[98:99], v[98:99], v[102:103]
	v_pk_mul_f32 v[102:103], v[148:149], v[116:117] op_sel_hi:[1,0]
	v_mad_i64_i32 v[118:119], s[28:29], v117, s64, v[162:163]
	v_pk_mul_f32 v[102:103], v[102:103], v[104:105]
	v_pk_mul_f32 v[98:99], v[98:99], v[108:109]
	v_exp_f32_e32 v102, v102
	v_exp_f32_e32 v103, v103
	v_cvt_pk_bf16_f32 v108, v98, v99
	v_cvt_f32_i32_e32 v99, v101
	v_cvt_f32_i32_e32 v98, v100
	v_pk_add_f32 v[100:101], v[102:103], 1.0 op_sel_hi:[1,0]
	v_pk_mul_f32 v[102:103], v[146:147], v[122:123] op_sel_hi:[1,0]
	v_rcp_f32_e32 v100, v100
	v_rcp_f32_e32 v101, v101
	v_pk_mul_f32 v[98:99], v[104:105], v[98:99]
	v_cvt_f32_i32_e32 v95, v95
	v_pk_mul_f32 v[98:99], v[98:99], v[102:103]
	v_cvt_f32_i32_e32 v94, v94
	v_pk_mul_f32 v[98:99], v[98:99], v[100:101]
	v_cvt_f32_i32_e32 v91, v91
	v_cvt_pk_bf16_f32 v109, v98, v99
	v_lshl_add_u64 v[98:99], v[118:119], 0, v[114:115]
	global_store_dwordx4 v[98:99], v[106:109], off sc0 sc1
	ds_read_b32 v98, v182 offset:128
	v_cvt_f32_i32_e32 v90, v90
	v_add_u32_e32 v99, s19, v171
	v_cvt_f32_i32_e32 v97, v97
	v_cvt_f32_i32_e32 v96, v96
	s_waitcnt lgkmcnt(0)
	v_pk_mul_f32 v[102:103], v[160:161], v[98:99] op_sel_hi:[1,0]
	v_mul_f32_e32 v104, v98, v98
	v_pk_mul_f32 v[102:103], v[102:103], v[94:95]
	v_pk_mul_f32 v[90:91], v[94:95], v[90:91]
	v_pk_mul_f32 v[94:95], v[158:159], v[104:105] op_sel_hi:[1,0]
	v_cvt_f32_i32_e32 v93, v93
	v_pk_mul_f32 v[90:91], v[90:91], v[94:95]
	v_pk_mul_f32 v[94:95], v[156:157], v[98:99] op_sel_hi:[1,0]
	v_cvt_f32_i32_e32 v92, v92
	v_pk_mul_f32 v[94:95], v[94:95], v[96:97]
	v_exp_f32_e32 v102, v102
	v_exp_f32_e32 v94, v94
	v_exp_f32_e32 v95, v95
	v_exp_f32_e32 v103, v103
	v_cvt_f32_i32_e32 v87, v87
	v_cvt_f32_i32_e32 v86, v86
	v_pk_add_f32 v[94:95], v[94:95], 1.0 op_sel_hi:[1,0]
	v_pk_mul_f32 v[92:93], v[96:97], v[92:93]
	v_rcp_f32_e32 v94, v94
	v_rcp_f32_e32 v95, v95
	v_pk_mul_f32 v[96:97], v[154:155], v[104:105] op_sel_hi:[1,0]
	v_pk_add_f32 v[102:103], v[102:103], 1.0 op_sel_hi:[1,0]
	v_pk_mul_f32 v[92:93], v[92:93], v[96:97]
	v_rcp_f32_e32 v102, v102
	v_pk_mul_f32 v[92:93], v[92:93], v[94:95]
	v_pk_mul_f32 v[94:95], v[152:153], v[98:99] op_sel_hi:[1,0]
	v_rcp_f32_e32 v103, v103
	v_pk_mul_f32 v[94:95], v[94:95], v[86:87]
	v_cvt_f32_i32_e32 v83, v83
	v_exp_f32_e32 v94, v94
	v_exp_f32_e32 v95, v95
	v_cvt_f32_i32_e32 v82, v82
	v_cvt_f32_i32_e32 v89, v89
	v_cvt_f32_i32_e32 v88, v88
	v_pk_mul_f32 v[90:91], v[90:91], v[102:103]
	v_pk_mul_f32 v[82:83], v[86:87], v[82:83]
	v_cvt_pk_bf16_f32 v90, v90, v91
	v_cvt_pk_bf16_f32 v91, v92, v93
	v_pk_add_f32 v[92:93], v[94:95], 1.0 op_sel_hi:[1,0]
	v_pk_mul_f32 v[86:87], v[150:151], v[104:105] op_sel_hi:[1,0]
	v_rcp_f32_e32 v92, v92
	v_rcp_f32_e32 v93, v93
	v_pk_mul_f32 v[82:83], v[82:83], v[86:87]
	v_pk_mul_f32 v[86:87], v[148:149], v[98:99] op_sel_hi:[1,0]
	v_mad_i64_i32 v[100:101], s[28:29], v99, s64, v[162:163]
	v_pk_mul_f32 v[86:87], v[86:87], v[88:89]
	v_pk_mul_f32 v[82:83], v[82:83], v[92:93]
	v_exp_f32_e32 v86, v86
	v_exp_f32_e32 v87, v87
	v_cvt_pk_bf16_f32 v92, v82, v83
	v_cvt_f32_i32_e32 v83, v85
	v_cvt_f32_i32_e32 v82, v84
	v_pk_add_f32 v[84:85], v[86:87], 1.0 op_sel_hi:[1,0]
	v_pk_mul_f32 v[86:87], v[146:147], v[104:105] op_sel_hi:[1,0]
	v_rcp_f32_e32 v84, v84
	v_rcp_f32_e32 v85, v85
	v_pk_mul_f32 v[82:83], v[88:89], v[82:83]
	v_cvt_f32_i32_e32 v79, v79
	v_pk_mul_f32 v[82:83], v[82:83], v[86:87]
	v_cvt_f32_i32_e32 v78, v78
	v_pk_mul_f32 v[82:83], v[82:83], v[84:85]
	v_cvt_f32_i32_e32 v75, v75
	v_cvt_pk_bf16_f32 v93, v82, v83
	v_lshl_add_u64 v[82:83], v[100:101], 0, v[114:115]
	global_store_dwordx4 v[82:83], v[90:93], off sc0 sc1
	ds_read_b32 v82, v182 offset:192
	v_cvt_f32_i32_e32 v74, v74
	v_add_u32_e32 v83, s19, v172
	v_cvt_f32_i32_e32 v81, v81
	v_cvt_f32_i32_e32 v80, v80
	s_waitcnt lgkmcnt(0)
	v_pk_mul_f32 v[86:87], v[160:161], v[82:83] op_sel_hi:[1,0]
	v_mul_f32_e32 v88, v82, v82
	v_pk_mul_f32 v[86:87], v[86:87], v[78:79]
	v_pk_mul_f32 v[74:75], v[78:79], v[74:75]
	v_pk_mul_f32 v[78:79], v[158:159], v[88:89] op_sel_hi:[1,0]
	v_cvt_f32_i32_e32 v77, v77
	v_pk_mul_f32 v[74:75], v[74:75], v[78:79]
	v_pk_mul_f32 v[78:79], v[156:157], v[82:83] op_sel_hi:[1,0]
	v_cvt_f32_i32_e32 v76, v76
	v_pk_mul_f32 v[78:79], v[78:79], v[80:81]
	v_exp_f32_e32 v86, v86
	v_exp_f32_e32 v78, v78
	v_exp_f32_e32 v79, v79
	v_exp_f32_e32 v87, v87
	v_cvt_f32_i32_e32 v71, v71
	v_cvt_f32_i32_e32 v70, v70
	v_pk_add_f32 v[78:79], v[78:79], 1.0 op_sel_hi:[1,0]
	v_pk_mul_f32 v[76:77], v[80:81], v[76:77]
	v_rcp_f32_e32 v78, v78
	v_rcp_f32_e32 v79, v79
	v_pk_mul_f32 v[80:81], v[154:155], v[88:89] op_sel_hi:[1,0]
	v_pk_add_f32 v[86:87], v[86:87], 1.0 op_sel_hi:[1,0]
	v_pk_mul_f32 v[76:77], v[76:77], v[80:81]
	v_rcp_f32_e32 v86, v86
	v_pk_mul_f32 v[76:77], v[76:77], v[78:79]
	v_pk_mul_f32 v[78:79], v[152:153], v[82:83] op_sel_hi:[1,0]
	v_rcp_f32_e32 v87, v87
	v_pk_mul_f32 v[78:79], v[78:79], v[70:71]
	v_cvt_f32_i32_e32 v67, v67
	v_exp_f32_e32 v78, v78
	v_exp_f32_e32 v79, v79
	v_cvt_f32_i32_e32 v66, v66
	v_cvt_f32_i32_e32 v73, v73
	v_cvt_f32_i32_e32 v72, v72
	v_pk_mul_f32 v[74:75], v[74:75], v[86:87]
	v_pk_mul_f32 v[66:67], v[70:71], v[66:67]
	v_cvt_pk_bf16_f32 v74, v74, v75
	v_cvt_pk_bf16_f32 v75, v76, v77
	v_pk_add_f32 v[76:77], v[78:79], 1.0 op_sel_hi:[1,0]
	v_pk_mul_f32 v[70:71], v[150:151], v[88:89] op_sel_hi:[1,0]
	v_rcp_f32_e32 v76, v76
	v_rcp_f32_e32 v77, v77
	v_pk_mul_f32 v[66:67], v[66:67], v[70:71]
	v_pk_mul_f32 v[70:71], v[148:149], v[82:83] op_sel_hi:[1,0]
	v_mad_i64_i32 v[84:85], s[28:29], v83, s64, v[162:163]
	v_pk_mul_f32 v[70:71], v[70:71], v[72:73]
	v_pk_mul_f32 v[66:67], v[66:67], v[76:77]
	v_exp_f32_e32 v70, v70
	v_exp_f32_e32 v71, v71
	v_cvt_pk_bf16_f32 v76, v66, v67
	v_cvt_f32_i32_e32 v67, v69
	v_cvt_f32_i32_e32 v66, v68
	v_pk_add_f32 v[68:69], v[70:71], 1.0 op_sel_hi:[1,0]
	v_pk_mul_f32 v[70:71], v[146:147], v[88:89] op_sel_hi:[1,0]
	v_rcp_f32_e32 v68, v68
	v_rcp_f32_e32 v69, v69
	v_pk_mul_f32 v[66:67], v[72:73], v[66:67]
	v_cvt_f32_i32_e32 v63, v63
	v_pk_mul_f32 v[66:67], v[66:67], v[70:71]
	v_cvt_f32_i32_e32 v62, v62
	v_pk_mul_f32 v[66:67], v[66:67], v[68:69]
	v_cvt_f32_i32_e32 v59, v59
	v_cvt_pk_bf16_f32 v77, v66, v67
	v_lshl_add_u64 v[66:67], v[84:85], 0, v[114:115]
	global_store_dwordx4 v[66:67], v[74:77], off sc0 sc1
	ds_read_b32 v66, v182 offset:512
	v_cvt_f32_i32_e32 v58, v58
	v_add_u32_e32 v67, s19, v173
	v_cvt_f32_i32_e32 v65, v65
	v_cvt_f32_i32_e32 v64, v64
	s_waitcnt lgkmcnt(0)
	v_pk_mul_f32 v[70:71], v[160:161], v[66:67] op_sel_hi:[1,0]
	v_mul_f32_e32 v72, v66, v66
	v_pk_mul_f32 v[70:71], v[70:71], v[62:63]
	v_pk_mul_f32 v[58:59], v[62:63], v[58:59]
	v_pk_mul_f32 v[62:63], v[158:159], v[72:73] op_sel_hi:[1,0]
	v_cvt_f32_i32_e32 v61, v61
	v_pk_mul_f32 v[58:59], v[58:59], v[62:63]
	v_pk_mul_f32 v[62:63], v[156:157], v[66:67] op_sel_hi:[1,0]
	v_cvt_f32_i32_e32 v60, v60
	v_pk_mul_f32 v[62:63], v[62:63], v[64:65]
	v_exp_f32_e32 v70, v70
	v_exp_f32_e32 v62, v62
	v_exp_f32_e32 v63, v63
	v_exp_f32_e32 v71, v71
	v_cvt_f32_i32_e32 v55, v55
	v_cvt_f32_i32_e32 v54, v54
	v_pk_add_f32 v[62:63], v[62:63], 1.0 op_sel_hi:[1,0]
	v_pk_mul_f32 v[60:61], v[64:65], v[60:61]
	v_rcp_f32_e32 v62, v62
	v_rcp_f32_e32 v63, v63
	v_pk_mul_f32 v[64:65], v[154:155], v[72:73] op_sel_hi:[1,0]
	v_pk_add_f32 v[70:71], v[70:71], 1.0 op_sel_hi:[1,0]
	v_pk_mul_f32 v[60:61], v[60:61], v[64:65]
	v_rcp_f32_e32 v70, v70
	v_pk_mul_f32 v[60:61], v[60:61], v[62:63]
	v_pk_mul_f32 v[62:63], v[152:153], v[66:67] op_sel_hi:[1,0]
	v_rcp_f32_e32 v71, v71
	v_pk_mul_f32 v[62:63], v[62:63], v[54:55]
	v_cvt_f32_i32_e32 v51, v51
	v_exp_f32_e32 v62, v62
	v_exp_f32_e32 v63, v63
	v_cvt_f32_i32_e32 v50, v50
	v_cvt_f32_i32_e32 v57, v57
	v_cvt_f32_i32_e32 v56, v56
	v_pk_mul_f32 v[58:59], v[58:59], v[70:71]
	v_pk_mul_f32 v[50:51], v[54:55], v[50:51]
	v_cvt_pk_bf16_f32 v58, v58, v59
	v_cvt_pk_bf16_f32 v59, v60, v61
	v_pk_add_f32 v[60:61], v[62:63], 1.0 op_sel_hi:[1,0]
	v_pk_mul_f32 v[54:55], v[150:151], v[72:73] op_sel_hi:[1,0]
	v_rcp_f32_e32 v60, v60
	v_rcp_f32_e32 v61, v61
	v_pk_mul_f32 v[50:51], v[50:51], v[54:55]
	v_pk_mul_f32 v[54:55], v[148:149], v[66:67] op_sel_hi:[1,0]
	v_mad_i64_i32 v[68:69], s[28:29], v67, s64, v[162:163]
	v_pk_mul_f32 v[54:55], v[54:55], v[56:57]
	v_pk_mul_f32 v[50:51], v[50:51], v[60:61]
	v_exp_f32_e32 v54, v54
	v_exp_f32_e32 v55, v55
	v_cvt_pk_bf16_f32 v60, v50, v51
	v_cvt_f32_i32_e32 v51, v53
	v_cvt_f32_i32_e32 v50, v52
	v_pk_add_f32 v[52:53], v[54:55], 1.0 op_sel_hi:[1,0]
	v_pk_mul_f32 v[54:55], v[146:147], v[72:73] op_sel_hi:[1,0]
	v_rcp_f32_e32 v52, v52
	v_rcp_f32_e32 v53, v53
	v_pk_mul_f32 v[50:51], v[56:57], v[50:51]
	v_cvt_f32_i32_e32 v47, v47
	v_pk_mul_f32 v[50:51], v[50:51], v[54:55]
	v_cvt_f32_i32_e32 v46, v46
	v_pk_mul_f32 v[50:51], v[50:51], v[52:53]
	v_cvt_f32_i32_e32 v43, v43
	v_cvt_pk_bf16_f32 v61, v50, v51
	v_lshl_add_u64 v[50:51], v[68:69], 0, v[114:115]
	global_store_dwordx4 v[50:51], v[58:61], off sc0 sc1
	ds_read_b32 v50, v182 offset:576
	v_cvt_f32_i32_e32 v42, v42
	v_add_u32_e32 v51, s19, v174
	v_cvt_f32_i32_e32 v49, v49
	v_cvt_f32_i32_e32 v48, v48
	s_waitcnt lgkmcnt(0)
	v_pk_mul_f32 v[54:55], v[160:161], v[50:51] op_sel_hi:[1,0]
	v_mul_f32_e32 v56, v50, v50
	v_pk_mul_f32 v[54:55], v[54:55], v[46:47]
	v_pk_mul_f32 v[42:43], v[46:47], v[42:43]
	v_pk_mul_f32 v[46:47], v[158:159], v[56:57] op_sel_hi:[1,0]
	v_cvt_f32_i32_e32 v45, v45
	v_pk_mul_f32 v[42:43], v[42:43], v[46:47]
	v_pk_mul_f32 v[46:47], v[156:157], v[50:51] op_sel_hi:[1,0]
	v_cvt_f32_i32_e32 v44, v44
	v_pk_mul_f32 v[46:47], v[46:47], v[48:49]
	v_exp_f32_e32 v54, v54
	v_exp_f32_e32 v46, v46
	v_exp_f32_e32 v47, v47
	v_exp_f32_e32 v55, v55
	v_cvt_f32_i32_e32 v39, v39
	v_cvt_f32_i32_e32 v38, v38
	v_pk_add_f32 v[46:47], v[46:47], 1.0 op_sel_hi:[1,0]
	v_pk_mul_f32 v[44:45], v[48:49], v[44:45]
	v_rcp_f32_e32 v46, v46
	v_rcp_f32_e32 v47, v47
	v_pk_mul_f32 v[48:49], v[154:155], v[56:57] op_sel_hi:[1,0]
	v_pk_add_f32 v[54:55], v[54:55], 1.0 op_sel_hi:[1,0]
	v_pk_mul_f32 v[44:45], v[44:45], v[48:49]
	v_rcp_f32_e32 v54, v54
	v_pk_mul_f32 v[44:45], v[44:45], v[46:47]
	v_pk_mul_f32 v[46:47], v[152:153], v[50:51] op_sel_hi:[1,0]
	v_rcp_f32_e32 v55, v55
	v_pk_mul_f32 v[46:47], v[46:47], v[38:39]
	v_cvt_f32_i32_e32 v35, v35
	v_exp_f32_e32 v46, v46
	v_exp_f32_e32 v47, v47
	v_cvt_f32_i32_e32 v34, v34
	v_cvt_f32_i32_e32 v41, v41
	v_cvt_f32_i32_e32 v40, v40
	v_pk_mul_f32 v[42:43], v[42:43], v[54:55]
	v_pk_mul_f32 v[34:35], v[38:39], v[34:35]
	v_cvt_pk_bf16_f32 v42, v42, v43
	v_cvt_pk_bf16_f32 v43, v44, v45
	v_pk_add_f32 v[44:45], v[46:47], 1.0 op_sel_hi:[1,0]
	v_pk_mul_f32 v[38:39], v[150:151], v[56:57] op_sel_hi:[1,0]
	v_rcp_f32_e32 v44, v44
	v_rcp_f32_e32 v45, v45
	v_pk_mul_f32 v[34:35], v[34:35], v[38:39]
	v_pk_mul_f32 v[38:39], v[148:149], v[50:51] op_sel_hi:[1,0]
	v_mad_i64_i32 v[52:53], s[28:29], v51, s64, v[162:163]
	v_pk_mul_f32 v[38:39], v[38:39], v[40:41]
	v_pk_mul_f32 v[34:35], v[34:35], v[44:45]
	v_exp_f32_e32 v38, v38
	v_exp_f32_e32 v39, v39
	v_cvt_pk_bf16_f32 v44, v34, v35
	v_cvt_f32_i32_e32 v35, v37
	v_cvt_f32_i32_e32 v34, v36
	v_pk_add_f32 v[36:37], v[38:39], 1.0 op_sel_hi:[1,0]
	v_pk_mul_f32 v[38:39], v[146:147], v[56:57] op_sel_hi:[1,0]
	v_rcp_f32_e32 v36, v36
	v_rcp_f32_e32 v37, v37
	v_pk_mul_f32 v[34:35], v[40:41], v[34:35]
	v_cvt_f32_i32_e32 v31, v31
	v_pk_mul_f32 v[34:35], v[34:35], v[38:39]
	v_cvt_f32_i32_e32 v30, v30
	v_pk_mul_f32 v[34:35], v[34:35], v[36:37]
	v_cvt_f32_i32_e32 v27, v27
	v_cvt_pk_bf16_f32 v45, v34, v35
	v_lshl_add_u64 v[34:35], v[52:53], 0, v[114:115]
	global_store_dwordx4 v[34:35], v[42:45], off sc0 sc1
	ds_read_b32 v34, v182 offset:640
	v_cvt_f32_i32_e32 v26, v26
	v_add_u32_e32 v35, s19, v175
	v_cvt_f32_i32_e32 v33, v33
	v_cvt_f32_i32_e32 v32, v32
	s_waitcnt lgkmcnt(0)
	v_pk_mul_f32 v[38:39], v[160:161], v[34:35] op_sel_hi:[1,0]
	v_mul_f32_e32 v40, v34, v34
	v_pk_mul_f32 v[38:39], v[38:39], v[30:31]
	v_pk_mul_f32 v[26:27], v[30:31], v[26:27]
	v_pk_mul_f32 v[30:31], v[158:159], v[40:41] op_sel_hi:[1,0]
	v_cvt_f32_i32_e32 v29, v29
	v_pk_mul_f32 v[26:27], v[26:27], v[30:31]
	v_pk_mul_f32 v[30:31], v[156:157], v[34:35] op_sel_hi:[1,0]
	v_cvt_f32_i32_e32 v28, v28
	v_pk_mul_f32 v[30:31], v[30:31], v[32:33]
	v_exp_f32_e32 v38, v38
	v_exp_f32_e32 v30, v30
	v_exp_f32_e32 v31, v31
	v_exp_f32_e32 v39, v39
	v_cvt_f32_i32_e32 v23, v23
	v_cvt_f32_i32_e32 v22, v22
	v_pk_add_f32 v[30:31], v[30:31], 1.0 op_sel_hi:[1,0]
	v_pk_mul_f32 v[28:29], v[32:33], v[28:29]
	v_rcp_f32_e32 v30, v30
	v_rcp_f32_e32 v31, v31
	v_pk_mul_f32 v[32:33], v[154:155], v[40:41] op_sel_hi:[1,0]
	v_pk_add_f32 v[38:39], v[38:39], 1.0 op_sel_hi:[1,0]
	v_pk_mul_f32 v[28:29], v[28:29], v[32:33]
	v_rcp_f32_e32 v38, v38
	v_pk_mul_f32 v[28:29], v[28:29], v[30:31]
	v_pk_mul_f32 v[30:31], v[152:153], v[34:35] op_sel_hi:[1,0]
	v_rcp_f32_e32 v39, v39
	v_pk_mul_f32 v[30:31], v[30:31], v[22:23]
	v_cvt_f32_i32_e32 v19, v19
	v_exp_f32_e32 v30, v30
	v_exp_f32_e32 v31, v31
	v_cvt_f32_i32_e32 v18, v18
	v_cvt_f32_i32_e32 v25, v25
	v_cvt_f32_i32_e32 v24, v24
	v_pk_mul_f32 v[26:27], v[26:27], v[38:39]
	v_pk_mul_f32 v[18:19], v[22:23], v[18:19]
	v_cvt_pk_bf16_f32 v26, v26, v27
	v_cvt_pk_bf16_f32 v27, v28, v29
	v_pk_add_f32 v[28:29], v[30:31], 1.0 op_sel_hi:[1,0]
	v_pk_mul_f32 v[22:23], v[150:151], v[40:41] op_sel_hi:[1,0]
	v_rcp_f32_e32 v28, v28
	v_rcp_f32_e32 v29, v29
	v_pk_mul_f32 v[18:19], v[18:19], v[22:23]
	v_pk_mul_f32 v[22:23], v[148:149], v[34:35] op_sel_hi:[1,0]
	v_mad_i64_i32 v[36:37], s[28:29], v35, s64, v[162:163]
	v_pk_mul_f32 v[22:23], v[22:23], v[24:25]
	v_pk_mul_f32 v[18:19], v[18:19], v[28:29]
	v_exp_f32_e32 v22, v22
	v_exp_f32_e32 v23, v23
	v_cvt_pk_bf16_f32 v28, v18, v19
	v_cvt_f32_i32_e32 v19, v21
	v_cvt_f32_i32_e32 v18, v20
	v_pk_add_f32 v[20:21], v[22:23], 1.0 op_sel_hi:[1,0]
	v_pk_mul_f32 v[22:23], v[146:147], v[40:41] op_sel_hi:[1,0]
	v_rcp_f32_e32 v20, v20
	v_rcp_f32_e32 v21, v21
	v_pk_mul_f32 v[18:19], v[24:25], v[18:19]
	v_cvt_f32_i32_e32 v15, v15
	v_pk_mul_f32 v[18:19], v[18:19], v[22:23]
	v_cvt_f32_i32_e32 v14, v14
	v_pk_mul_f32 v[18:19], v[18:19], v[20:21]
	v_cvt_f32_i32_e32 v11, v11
	v_cvt_pk_bf16_f32 v29, v18, v19
	v_lshl_add_u64 v[18:19], v[36:37], 0, v[114:115]
	global_store_dwordx4 v[18:19], v[26:29], off sc0 sc1
	ds_read_b32 v18, v182 offset:704
	v_cvt_f32_i32_e32 v10, v10
	v_add_u32_e32 v19, s19, v176
	v_cvt_f32_i32_e32 v17, v17
	v_cvt_f32_i32_e32 v16, v16
	s_waitcnt lgkmcnt(0)
	v_pk_mul_f32 v[22:23], v[160:161], v[18:19] op_sel_hi:[1,0]
	v_mul_f32_e32 v24, v18, v18
	v_pk_mul_f32 v[22:23], v[22:23], v[14:15]
	v_pk_mul_f32 v[10:11], v[14:15], v[10:11]
	v_pk_mul_f32 v[14:15], v[158:159], v[24:25] op_sel_hi:[1,0]
	v_cvt_f32_i32_e32 v13, v13
	v_pk_mul_f32 v[10:11], v[10:11], v[14:15]
	v_pk_mul_f32 v[14:15], v[156:157], v[18:19] op_sel_hi:[1,0]
	v_cvt_f32_i32_e32 v12, v12
	v_pk_mul_f32 v[14:15], v[14:15], v[16:17]
	v_exp_f32_e32 v22, v22
	v_exp_f32_e32 v14, v14
	v_exp_f32_e32 v15, v15
	v_exp_f32_e32 v23, v23
	v_cvt_f32_i32_e32 v7, v7
	v_cvt_f32_i32_e32 v6, v6
	v_pk_add_f32 v[14:15], v[14:15], 1.0 op_sel_hi:[1,0]
	v_pk_mul_f32 v[12:13], v[16:17], v[12:13]
	v_rcp_f32_e32 v14, v14
	v_rcp_f32_e32 v15, v15
	v_pk_mul_f32 v[16:17], v[154:155], v[24:25] op_sel_hi:[1,0]
	v_pk_add_f32 v[22:23], v[22:23], 1.0 op_sel_hi:[1,0]
	v_pk_mul_f32 v[12:13], v[12:13], v[16:17]
	v_rcp_f32_e32 v22, v22
	v_pk_mul_f32 v[12:13], v[12:13], v[14:15]
	v_pk_mul_f32 v[14:15], v[152:153], v[18:19] op_sel_hi:[1,0]
	v_rcp_f32_e32 v23, v23
	v_pk_mul_f32 v[14:15], v[14:15], v[6:7]
	v_cvt_f32_i32_e32 v3, v3
	v_exp_f32_e32 v14, v14
	v_exp_f32_e32 v15, v15
	v_cvt_f32_i32_e32 v2, v2
	v_cvt_f32_i32_e32 v9, v9
	v_cvt_f32_i32_e32 v8, v8
	v_pk_mul_f32 v[10:11], v[10:11], v[22:23]
	v_pk_mul_f32 v[2:3], v[6:7], v[2:3]
	v_cvt_pk_bf16_f32 v10, v10, v11
	v_cvt_pk_bf16_f32 v11, v12, v13
	v_pk_add_f32 v[12:13], v[14:15], 1.0 op_sel_hi:[1,0]
	v_pk_mul_f32 v[6:7], v[150:151], v[24:25] op_sel_hi:[1,0]
	v_rcp_f32_e32 v12, v12
	v_rcp_f32_e32 v13, v13
	v_pk_mul_f32 v[2:3], v[2:3], v[6:7]
	v_pk_mul_f32 v[6:7], v[148:149], v[18:19] op_sel_hi:[1,0]
	v_mad_i64_i32 v[20:21], s[28:29], v19, s64, v[162:163]
	v_pk_mul_f32 v[6:7], v[6:7], v[8:9]
	v_pk_mul_f32 v[2:3], v[2:3], v[12:13]
	v_exp_f32_e32 v6, v6
	v_exp_f32_e32 v7, v7
	v_cvt_pk_bf16_f32 v12, v2, v3
	v_cvt_f32_i32_e32 v3, v5
	v_cvt_f32_i32_e32 v2, v4
	v_pk_add_f32 v[4:5], v[6:7], 1.0 op_sel_hi:[1,0]
	v_pk_mul_f32 v[6:7], v[146:147], v[24:25] op_sel_hi:[1,0]
	v_rcp_f32_e32 v4, v4
	v_rcp_f32_e32 v5, v5
	v_pk_mul_f32 v[2:3], v[8:9], v[2:3]
	s_andn2_b64 vcc, exec, s[4:5]
	v_pk_mul_f32 v[2:3], v[2:3], v[6:7]
	s_mov_b64 s[4:5], -1
	v_pk_mul_f32 v[2:3], v[2:3], v[4:5]
	s_nop 0
	v_cvt_pk_bf16_f32 v13, v2, v3
	v_lshl_add_u64 v[2:3], v[20:21], 0, v[114:115]
	global_store_dwordx4 v[2:3], v[10:13], off sc0 sc1
	s_cbranch_vccnz .LBB0_133
	s_andn2_b64 vcc, exec, s[12:13]
	s_cbranch_vccnz .LBB0_132
	s_barrier
	s_branch .LBB0_132

.LBB0_150:
	s_ashr_i32 s4, s8, 31
	s_lshr_b32 s4, s4, 26
	s_add_i32 s4, s8, s4
	s_lshl_b32 s5, s4, 5
	s_and_b32 s6, s4, 0xffffffc0
	s_and_b32 s4, s5, 0xfffff800
	v_or_b32_e32 v24, s6, v6
	s_sub_i32 s4, s10, s4
	v_or_b32_e32 v26, 8, v24
	v_or_b32_e32 v28, 16, v24
	v_or_b32_e32 v30, 24, v24
	v_or_b32_e32 v32, 32, v24
	v_or_b32_e32 v34, 40, v24
	v_or_b32_e32 v36, 48, v24
	v_or_b32_e32 v38, 56, v24
	v_ashrrev_i32_e32 v25, 31, v24
	s_ashr_i32 s5, s4, 31
	v_ashrrev_i32_e32 v27, 31, v26
	v_ashrrev_i32_e32 v29, 31, v28
	v_ashrrev_i32_e32 v31, 31, v30
	v_ashrrev_i32_e32 v33, 31, v32
	v_ashrrev_i32_e32 v35, 31, v34
	v_ashrrev_i32_e32 v37, 31, v36
	v_ashrrev_i32_e32 v39, 31, v38
	v_lshlrev_b64 v[24:25], 13, v[24:25]
	v_lshl_add_u64 v[40:41], s[4:5], 2, v[2:3]
	v_lshlrev_b64 v[26:27], 13, v[26:27]
	v_lshlrev_b64 v[28:29], 13, v[28:29]
	v_lshlrev_b64 v[30:31], 13, v[30:31]
	v_lshlrev_b64 v[32:33], 13, v[32:33]
	v_lshlrev_b64 v[34:35], 13, v[34:35]
	v_lshlrev_b64 v[36:37], 13, v[36:37]
	v_lshlrev_b64 v[38:39], 13, v[38:39]
	v_lshl_add_u64 v[24:25], v[40:41], 0, v[24:25]
	v_lshl_add_u64 v[42:43], v[40:41], 0, v[26:27]
	v_lshl_add_u64 v[44:45], v[40:41], 0, v[28:29]
	v_lshl_add_u64 v[46:47], v[40:41], 0, v[30:31]
	v_lshl_add_u64 v[48:49], v[40:41], 0, v[32:33]
	v_lshl_add_u64 v[50:51], v[40:41], 0, v[34:35]
	v_lshl_add_u64 v[52:53], v[40:41], 0, v[36:37]
	v_lshl_add_u64 v[54:55], v[40:41], 0, v[38:39]
	global_load_dwordx4 v[24:27], v[24:25], off nt
	s_nop 0
	global_load_dwordx4 v[28:31], v[42:43], off nt
	global_load_dwordx4 v[32:35], v[44:45], off nt
	global_load_dwordx4 v[36:39], v[46:47], off nt
	s_nop 0
	global_load_dwordx4 v[40:43], v[48:49], off nt
	global_load_dwordx4 v[44:47], v[50:51], off nt
	s_nop 0
	global_load_dwordx4 v[48:51], v[52:53], off nt
	s_nop 0
	global_load_dwordx4 v[52:55], v[54:55], off nt
	s_ashr_i32 s7, s6, 31
	v_lshl_add_u64 v[56:57], s[6:7], 1, v[4:5]
	v_add_u32_e32 v64, s4, v6
	v_mad_i64_i32 v[58:59], s[4:5], v64, s12, v[56:57]
	v_add_u32_e32 v60, 8, v64
	v_mad_i64_i32 v[60:61], s[4:5], v60, s12, v[56:57]
	v_add_u32_e32 v62, 16, v64
	v_mad_i64_i32 v[62:63], s[4:5], v62, s12, v[56:57]
	s_add_i32 s8, s8, s9
	s_add_i32 s10, s10, s11
	s_cmpk_lt_i32 s8, 0x1600
	s_waitcnt vmcnt(0)
	ds_write2_b32 v9, v24, v25 offset1:1
	ds_write2_b32 v9, v26, v27 offset0:2 offset1:3
	ds_write2_b32 v10, v28, v29 offset1:1
	ds_write2_b32 v11, v30, v31 offset1:1
	ds_write2_b32 v12, v32, v33 offset1:1
	ds_write2_b32 v13, v34, v35 offset1:1
	ds_write2_b32 v14, v36, v37 offset1:1
	ds_write2_b32 v15, v38, v39 offset1:1
	ds_write2_b32 v16, v40, v41 offset1:1
	ds_write2_b32 v17, v42, v43 offset1:1
	ds_write2_b32 v18, v44, v45 offset1:1
	ds_write2_b32 v19, v46, v47 offset1:1
	ds_write2_b32 v20, v48, v49 offset1:1
	ds_write2_b32 v21, v50, v51 offset1:1
	ds_write2_b32 v22, v52, v53 offset1:1
	ds_write2_b32 v23, v54, v55 offset1:1
	s_waitcnt lgkmcnt(0)
	ds_read2_b32 v[24:25], v1 offset1:33
	s_waitcnt lgkmcnt(0)
	v_cvt_pk_bf16_f32 v24, v24, v25
	ds_read2_b32 v[26:27], v1 offset0:66 offset1:99
	s_waitcnt lgkmcnt(0)
	v_cvt_pk_bf16_f32 v25, v26, v27
	ds_read2_b32 v[26:27], v1 offset0:132 offset1:165
	s_waitcnt lgkmcnt(0)
	v_cvt_pk_bf16_f32 v26, v26, v27
	ds_read2_b32 v[28:29], v1 offset0:198 offset1:231
	s_waitcnt lgkmcnt(0)
	v_cvt_pk_bf16_f32 v27, v28, v29
	ds_read2_b32 v[28:29], v1 offset0:8 offset1:41
	global_store_dwordx4 v[58:59], v[24:27], off sc0 sc1
	s_waitcnt lgkmcnt(0)
	s_nop 0
	v_cvt_pk_bf16_f32 v24, v28, v29
	ds_read2_b32 v[26:27], v1 offset0:74 offset1:107
	s_waitcnt lgkmcnt(0)
	v_cvt_pk_bf16_f32 v25, v26, v27
	ds_read2_b32 v[26:27], v1 offset0:140 offset1:173
	s_waitcnt lgkmcnt(0)
	v_cvt_pk_bf16_f32 v26, v26, v27
	ds_read2_b32 v[28:29], v1 offset0:206 offset1:239
	s_waitcnt lgkmcnt(0)
	v_cvt_pk_bf16_f32 v27, v28, v29
	ds_read2_b32 v[28:29], v1 offset0:16 offset1:49
	global_store_dwordx4 v[60:61], v[24:27], off sc0 sc1
	s_waitcnt lgkmcnt(0)
	s_nop 0
	v_cvt_pk_bf16_f32 v24, v28, v29
	ds_read2_b32 v[26:27], v1 offset0:82 offset1:115
	s_waitcnt lgkmcnt(0)
	v_cvt_pk_bf16_f32 v25, v26, v27
	ds_read2_b32 v[26:27], v1 offset0:148 offset1:181
	s_waitcnt lgkmcnt(0)
	v_cvt_pk_bf16_f32 v26, v26, v27
	ds_read2_b32 v[28:29], v1 offset0:214 offset1:247
	s_waitcnt lgkmcnt(0)
	v_cvt_pk_bf16_f32 v27, v28, v29
	ds_read2_b32 v[28:29], v1 offset0:24 offset1:57
	global_store_dwordx4 v[62:63], v[24:27], off sc0 sc1
	s_waitcnt lgkmcnt(0)
	s_nop 0
	v_cvt_pk_bf16_f32 v24, v28, v29
	ds_read2_b32 v[26:27], v1 offset0:90 offset1:123
	s_waitcnt lgkmcnt(0)
	v_cvt_pk_bf16_f32 v25, v26, v27
	ds_read2_b32 v[26:27], v1 offset0:156 offset1:189
	s_waitcnt lgkmcnt(0)
	v_cvt_pk_bf16_f32 v26, v26, v27
	v_add_u32_e32 v27, 24, v64
	v_mad_i64_i32 v[30:31], s[4:5], v27, s12, v[56:57]
	ds_read2_b32 v[28:29], v1 offset0:222 offset1:255
	s_waitcnt lgkmcnt(0)
	v_cvt_pk_bf16_f32 v27, v28, v29
	global_store_dwordx4 v[30:31], v[24:27], off sc0 sc1
	s_waitcnt lgkmcnt(0)
	s_cbranch_scc1 .LBB0_150

.LBB0_155:
	s_ashr_i32 s4, s8, 31
	s_lshr_b32 s4, s4, 26
	s_add_i32 s4, s8, s4
	s_lshl_b32 s5, s4, 5
	s_and_b32 s6, s4, 0xffffffc0
	s_and_b32 s4, s5, 0xfffff800
	v_or_b32_e32 v22, s6, v6
	s_sub_i32 s4, s10, s4
	v_or_b32_e32 v24, 8, v22
	v_or_b32_e32 v26, 16, v22
	v_or_b32_e32 v28, 24, v22
	v_or_b32_e32 v30, 32, v22
	v_or_b32_e32 v32, 40, v22
	v_or_b32_e32 v34, 48, v22
	v_or_b32_e32 v36, 56, v22
	v_ashrrev_i32_e32 v23, 31, v22
	s_ashr_i32 s5, s4, 31
	v_ashrrev_i32_e32 v25, 31, v24
	v_ashrrev_i32_e32 v27, 31, v26
	v_ashrrev_i32_e32 v29, 31, v28
	v_ashrrev_i32_e32 v31, 31, v30
	v_ashrrev_i32_e32 v33, 31, v32
	v_ashrrev_i32_e32 v35, 31, v34
	v_ashrrev_i32_e32 v37, 31, v36
	v_lshlrev_b64 v[22:23], 13, v[22:23]
	v_lshl_add_u64 v[38:39], s[4:5], 2, v[2:3]
	v_lshlrev_b64 v[24:25], 13, v[24:25]
	v_lshlrev_b64 v[26:27], 13, v[26:27]
	v_lshlrev_b64 v[28:29], 13, v[28:29]
	v_lshlrev_b64 v[30:31], 13, v[30:31]
	v_lshlrev_b64 v[32:33], 13, v[32:33]
	v_lshlrev_b64 v[34:35], 13, v[34:35]
	v_lshlrev_b64 v[36:37], 13, v[36:37]
	v_lshl_add_u64 v[22:23], v[38:39], 0, v[22:23]
	v_lshl_add_u64 v[40:41], v[38:39], 0, v[24:25]
	v_lshl_add_u64 v[42:43], v[38:39], 0, v[26:27]
	v_lshl_add_u64 v[44:45], v[38:39], 0, v[28:29]
	v_lshl_add_u64 v[46:47], v[38:39], 0, v[30:31]
	v_lshl_add_u64 v[48:49], v[38:39], 0, v[32:33]
	v_lshl_add_u64 v[50:51], v[38:39], 0, v[34:35]
	v_lshl_add_u64 v[52:53], v[38:39], 0, v[36:37]
	global_load_dwordx4 v[22:25], v[22:23], off nt
	s_nop 0
	global_load_dwordx4 v[26:29], v[40:41], off nt
	global_load_dwordx4 v[30:33], v[42:43], off nt
	global_load_dwordx4 v[34:37], v[44:45], off nt
	s_nop 0
	global_load_dwordx4 v[38:41], v[46:47], off nt
	global_load_dwordx4 v[42:45], v[48:49], off nt
	s_nop 0
	global_load_dwordx4 v[46:49], v[50:51], off nt
	s_nop 0
	global_load_dwordx4 v[50:53], v[52:53], off nt
	s_ashr_i32 s7, s6, 31
	v_lshl_add_u64 v[54:55], s[6:7], 1, v[4:5]
	v_add_u32_e32 v62, s4, v6
	v_mad_i64_i32 v[56:57], s[4:5], v62, s12, v[54:55]
	v_add_u32_e32 v58, 8, v62
	v_mad_i64_i32 v[58:59], s[4:5], v58, s12, v[54:55]
	v_add_u32_e32 v60, 16, v62
	v_mad_i64_i32 v[60:61], s[4:5], v60, s12, v[54:55]
	s_add_i32 s8, s8, s9
	s_add_i32 s10, s10, s11
	s_cmpk_gt_i32 s8, 0x15ff
	s_waitcnt vmcnt(0)
	ds_write2_b32 v7, v22, v23 offset1:1
	ds_write2_b32 v7, v24, v25 offset0:2 offset1:3
	ds_write2_b32 v8, v26, v27 offset1:1
	ds_write2_b32 v9, v28, v29 offset1:1
	ds_write2_b32 v10, v30, v31 offset1:1
	ds_write2_b32 v11, v32, v33 offset1:1
	ds_write2_b32 v12, v34, v35 offset1:1
	ds_write2_b32 v13, v36, v37 offset1:1
	ds_write2_b32 v14, v38, v39 offset1:1
	ds_write2_b32 v15, v40, v41 offset1:1
	ds_write2_b32 v16, v42, v43 offset1:1
	ds_write2_b32 v17, v44, v45 offset1:1
	ds_write2_b32 v18, v46, v47 offset1:1
	ds_write2_b32 v19, v48, v49 offset1:1
	ds_write2_b32 v20, v50, v51 offset1:1
	ds_write2_b32 v21, v52, v53 offset1:1
	s_waitcnt lgkmcnt(0)
	ds_read2_b32 v[22:23], v1 offset1:33
	s_waitcnt lgkmcnt(0)
	v_cvt_pk_bf16_f32 v22, v22, v23
	ds_read2_b32 v[24:25], v1 offset0:66 offset1:99
	s_waitcnt lgkmcnt(0)
	v_cvt_pk_bf16_f32 v23, v24, v25
	ds_read2_b32 v[24:25], v1 offset0:132 offset1:165
	s_waitcnt lgkmcnt(0)
	v_cvt_pk_bf16_f32 v24, v24, v25
	ds_read2_b32 v[26:27], v1 offset0:198 offset1:231
	s_waitcnt lgkmcnt(0)
	v_cvt_pk_bf16_f32 v25, v26, v27
	ds_read2_b32 v[26:27], v1 offset0:8 offset1:41
	global_store_dwordx4 v[56:57], v[22:25], off sc0 sc1
	s_waitcnt lgkmcnt(0)
	s_nop 0
	v_cvt_pk_bf16_f32 v22, v26, v27
	ds_read2_b32 v[24:25], v1 offset0:74 offset1:107
	s_waitcnt lgkmcnt(0)
	v_cvt_pk_bf16_f32 v23, v24, v25
	ds_read2_b32 v[24:25], v1 offset0:140 offset1:173
	s_waitcnt lgkmcnt(0)
	v_cvt_pk_bf16_f32 v24, v24, v25
	ds_read2_b32 v[26:27], v1 offset0:206 offset1:239
	s_waitcnt lgkmcnt(0)
	v_cvt_pk_bf16_f32 v25, v26, v27
	ds_read2_b32 v[26:27], v1 offset0:16 offset1:49
	global_store_dwordx4 v[58:59], v[22:25], off sc0 sc1
	s_waitcnt lgkmcnt(0)
	s_nop 0
	v_cvt_pk_bf16_f32 v22, v26, v27
	ds_read2_b32 v[24:25], v1 offset0:82 offset1:115
	s_waitcnt lgkmcnt(0)
	v_cvt_pk_bf16_f32 v23, v24, v25
	ds_read2_b32 v[24:25], v1 offset0:148 offset1:181
	s_waitcnt lgkmcnt(0)
	v_cvt_pk_bf16_f32 v24, v24, v25
	ds_read2_b32 v[26:27], v1 offset0:214 offset1:247
	s_waitcnt lgkmcnt(0)
	v_cvt_pk_bf16_f32 v25, v26, v27
	ds_read2_b32 v[26:27], v1 offset0:24 offset1:57
	global_store_dwordx4 v[60:61], v[22:25], off sc0 sc1
	s_waitcnt lgkmcnt(0)
	s_nop 0
	v_cvt_pk_bf16_f32 v22, v26, v27
	ds_read2_b32 v[24:25], v1 offset0:90 offset1:123
	s_waitcnt lgkmcnt(0)
	v_cvt_pk_bf16_f32 v23, v24, v25
	ds_read2_b32 v[24:25], v1 offset0:156 offset1:189
	s_waitcnt lgkmcnt(0)
	v_cvt_pk_bf16_f32 v24, v24, v25
	v_add_u32_e32 v25, 24, v62
	v_mad_i64_i32 v[28:29], s[4:5], v25, s12, v[54:55]
	ds_read2_b32 v[26:27], v1 offset0:222 offset1:255
	s_waitcnt lgkmcnt(0)
	v_cvt_pk_bf16_f32 v25, v26, v27
	global_store_dwordx4 v[28:29], v[22:25], off sc0 sc1
	s_waitcnt lgkmcnt(0)
	s_cbranch_scc0 .LBB0_155

.LBB0_740:
	s_lshl_b32 s19, s63, 11
	s_add_i32 s19, s19, 0
	s_add_i32 s21, s19, 0x20180
	s_lshl_b32 s19, s45, 2
	s_add_i32 s19, s21, s19
	v_lshl_add_u32 v154, v164, 2, s19
	ds_read_b128 v[146:149], v154 offset:1024
	ds_read_b128 v[150:153], v154 offset:1536
	ds_read_b128 v[182:185], v154 offset:1040
	ds_read_b128 v[186:189], v154 offset:1552
	v_cvt_f32_i32_e32 v127, v127
	v_cvt_f32_i32_e32 v126, v126
	s_waitcnt lgkmcnt(0)
	v_pk_mul_f32 v[154:155], v[148:149], v[152:153]
	v_pk_mul_f32 v[158:159], v[146:147], v[150:151]
	v_pk_mul_f32 v[152:153], v[182:183], s[16:17] op_sel_hi:[1,0]
	v_pk_mul_f32 v[150:151], v[182:183], v[186:187]
	v_lshl_add_u32 v182, v165, 2, s21
	ds_read_b32 v186, v182
	v_cvt_f32_i32_e32 v123, v123
	v_cvt_f32_i32_e32 v122, v122
	v_pk_mul_f32 v[160:161], v[146:147], s[16:17] op_sel_hi:[1,0]
	v_cvt_f32_i32_e32 v129, v129
	v_cvt_f32_i32_e32 v128, v128
	s_waitcnt lgkmcnt(0)
	v_pk_mul_f32 v[190:191], v[160:161], v[186:187] op_sel_hi:[1,0]
	v_mul_f32_e32 v192, v186, v186
	v_pk_mul_f32 v[156:157], v[148:149], s[16:17] op_sel_hi:[1,0]
	v_pk_mul_f32 v[190:191], v[190:191], v[126:127]
	v_pk_mul_f32 v[122:123], v[126:127], v[122:123]
	v_pk_mul_f32 v[126:127], v[158:159], v[192:193] op_sel_hi:[1,0]
	v_cvt_f32_i32_e32 v125, v125
	v_pk_mul_f32 v[122:123], v[122:123], v[126:127]
	v_pk_mul_f32 v[126:127], v[156:157], v[186:187] op_sel_hi:[1,0]
	v_cvt_f32_i32_e32 v124, v124
	v_pk_mul_f32 v[126:127], v[126:127], v[128:129]
	v_exp_f32_e32 v190, v190
	v_exp_f32_e32 v126, v126
	v_exp_f32_e32 v127, v127
	v_exp_f32_e32 v191, v191
	v_cvt_f32_i32_e32 v119, v119
	v_cvt_f32_i32_e32 v118, v118
	v_pk_add_f32 v[126:127], v[126:127], 1.0 op_sel_hi:[1,0]
	v_pk_mul_f32 v[124:125], v[128:129], v[124:125]
	v_rcp_f32_e32 v126, v126
	v_rcp_f32_e32 v127, v127
	v_pk_mul_f32 v[128:129], v[154:155], v[192:193] op_sel_hi:[1,0]
	v_pk_add_f32 v[190:191], v[190:191], 1.0 op_sel_hi:[1,0]
	v_pk_mul_f32 v[124:125], v[124:125], v[128:129]
	v_rcp_f32_e32 v190, v190
	v_pk_mul_f32 v[124:125], v[124:125], v[126:127]
	v_pk_mul_f32 v[126:127], v[152:153], v[186:187] op_sel_hi:[1,0]
	v_rcp_f32_e32 v191, v191
	v_pk_mul_f32 v[126:127], v[126:127], v[118:119]
	v_cvt_f32_i32_e32 v115, v115
	v_exp_f32_e32 v126, v126
	v_exp_f32_e32 v127, v127
	v_cvt_f32_i32_e32 v114, v114
	v_cvt_f32_i32_e32 v121, v121
	v_cvt_f32_i32_e32 v120, v120
	v_pk_mul_f32 v[122:123], v[122:123], v[190:191]
	v_pk_mul_f32 v[148:149], v[184:185], s[16:17] op_sel_hi:[1,0]
	v_cvt_pk_bf16_f32 v122, v122, v123
	v_cvt_pk_bf16_f32 v123, v124, v125
	v_pk_add_f32 v[124:125], v[126:127], 1.0 op_sel_hi:[1,0]
	v_pk_mul_f32 v[114:115], v[118:119], v[114:115]
	v_pk_mul_f32 v[118:119], v[150:151], v[192:193] op_sel_hi:[1,0]
	v_rcp_f32_e32 v124, v124
	v_rcp_f32_e32 v125, v125
	v_pk_mul_f32 v[114:115], v[114:115], v[118:119]
	v_pk_mul_f32 v[118:119], v[148:149], v[186:187] op_sel_hi:[1,0]
	v_pk_mul_f32 v[146:147], v[184:185], v[188:189]
	v_pk_mul_f32 v[118:119], v[118:119], v[120:121]
	v_pk_mul_f32 v[114:115], v[114:115], v[124:125]
	v_exp_f32_e32 v118, v118
	v_exp_f32_e32 v119, v119
	v_cvt_pk_bf16_f32 v124, v114, v115
	v_cvt_f32_i32_e32 v115, v117
	v_cvt_f32_i32_e32 v114, v116
	v_pk_add_f32 v[116:117], v[118:119], 1.0 op_sel_hi:[1,0]
	v_pk_mul_f32 v[118:119], v[146:147], v[192:193] op_sel_hi:[1,0]
	v_rcp_f32_e32 v116, v116
	v_rcp_f32_e32 v117, v117
	v_pk_mul_f32 v[114:115], v[120:121], v[114:115]
	v_lshl_or_b32 v184, s51, 7, v177
	s_lshl_b32 s19, s26, 8
	v_pk_mul_f32 v[114:115], v[114:115], v[118:119]
	v_ashrrev_i32_e32 v185, 31, v184
	v_add_u32_e32 v183, s19, v165
	v_mov_b64_e32 v[162:163], s[60:61]
	v_pk_mul_f32 v[114:115], v[114:115], v[116:117]
	v_mad_i64_i32 v[188:189], s[28:29], v183, s49, v[162:163]
	v_cvt_pk_bf16_f32 v125, v114, v115
	v_lshlrev_b64 v[114:115], 1, v[184:185]
	v_lshl_add_u64 v[116:117], v[188:189], 0, v[114:115]
	global_store_dwordx4 v[116:117], v[122:125], off sc0 sc1
	ds_read_b32 v116, v182 offset:64
	v_cvt_f32_i32_e32 v111, v111
	v_cvt_f32_i32_e32 v110, v110
	v_cvt_f32_i32_e32 v107, v107
	v_cvt_f32_i32_e32 v106, v106
	v_add_u32_e32 v117, s19, v170
	v_cvt_f32_i32_e32 v113, v113
	v_cvt_f32_i32_e32 v112, v112
	s_waitcnt lgkmcnt(0)
	v_pk_mul_f32 v[120:121], v[160:161], v[116:117] op_sel_hi:[1,0]
	v_mul_f32_e32 v122, v116, v116
	v_pk_mul_f32 v[120:121], v[120:121], v[110:111]
	v_pk_mul_f32 v[106:107], v[110:111], v[106:107]
	v_pk_mul_f32 v[110:111], v[158:159], v[122:123] op_sel_hi:[1,0]
	v_cvt_f32_i32_e32 v109, v109
	v_pk_mul_f32 v[106:107], v[106:107], v[110:111]
	v_pk_mul_f32 v[110:111], v[156:157], v[116:117] op_sel_hi:[1,0]
	v_cvt_f32_i32_e32 v108, v108
	v_pk_mul_f32 v[110:111], v[110:111], v[112:113]
	v_exp_f32_e32 v120, v120
	v_exp_f32_e32 v110, v110
	v_exp_f32_e32 v111, v111
	v_exp_f32_e32 v121, v121
	v_cvt_f32_i32_e32 v103, v103
	v_cvt_f32_i32_e32 v102, v102
	v_pk_add_f32 v[110:111], v[110:111], 1.0 op_sel_hi:[1,0]
	v_pk_mul_f32 v[108:109], v[112:113], v[108:109]
	v_rcp_f32_e32 v110, v110
	v_rcp_f32_e32 v111, v111
	v_pk_mul_f32 v[112:113], v[154:155], v[122:123] op_sel_hi:[1,0]
	v_pk_add_f32 v[120:121], v[120:121], 1.0 op_sel_hi:[1,0]
	v_pk_mul_f32 v[108:109], v[108:109], v[112:113]
	v_rcp_f32_e32 v120, v120
	v_pk_mul_f32 v[108:109], v[108:109], v[110:111]
	v_pk_mul_f32 v[110:111], v[152:153], v[116:117] op_sel_hi:[1,0]
	v_rcp_f32_e32 v121, v121
	v_pk_mul_f32 v[110:111], v[110:111], v[102:103]
	v_cvt_f32_i32_e32 v99, v99
	v_exp_f32_e32 v110, v110
	v_exp_f32_e32 v111, v111
	v_cvt_f32_i32_e32 v98, v98
	v_cvt_f32_i32_e32 v105, v105
	v_cvt_f32_i32_e32 v104, v104
	v_pk_mul_f32 v[106:107], v[106:107], v[120:121]
	v_pk_mul_f32 v[98:99], v[102:103], v[98:99]
	v_cvt_pk_bf16_f32 v106, v106, v107
	v_cvt_pk_bf16_f32 v107, v108, v109
	v_pk_add_f32 v[108:109], v[110:111], 1.0 op_sel_hi:[1,0]
	v_pk_mul_f32 v[102:103], v[150:151], v[122:123] op_sel_hi:[1,0]
	v_rcp_f32_e32 v108, v108
	v_rcp_f32_e32 v109, v109
	v_pk_mul_f32 v[98:99], v[98:99], v[102:103]
	v_pk_mul_f32 v[102:103], v[148:149], v[116:117] op_sel_hi:[1,0]
	v_mad_i64_i32 v[118:119], s[28:29], v117, s49, v[162:163]
	v_pk_mul_f32 v[102:103], v[102:103], v[104:105]
	v_pk_mul_f32 v[98:99], v[98:99], v[108:109]
	v_exp_f32_e32 v102, v102
	v_exp_f32_e32 v103, v103
	v_cvt_pk_bf16_f32 v108, v98, v99
	v_cvt_f32_i32_e32 v99, v101
	v_cvt_f32_i32_e32 v98, v100
	v_pk_add_f32 v[100:101], v[102:103], 1.0 op_sel_hi:[1,0]
	v_pk_mul_f32 v[102:103], v[146:147], v[122:123] op_sel_hi:[1,0]
	v_rcp_f32_e32 v100, v100
	v_rcp_f32_e32 v101, v101
	v_pk_mul_f32 v[98:99], v[104:105], v[98:99]
	v_cvt_f32_i32_e32 v95, v95
	v_pk_mul_f32 v[98:99], v[98:99], v[102:103]
	v_cvt_f32_i32_e32 v94, v94
	v_pk_mul_f32 v[98:99], v[98:99], v[100:101]
	v_cvt_f32_i32_e32 v91, v91
	v_cvt_pk_bf16_f32 v109, v98, v99
	v_lshl_add_u64 v[98:99], v[118:119], 0, v[114:115]
	global_store_dwordx4 v[98:99], v[106:109], off sc0 sc1
	ds_read_b32 v98, v182 offset:128
	v_cvt_f32_i32_e32 v90, v90
	v_add_u32_e32 v99, s19, v171
	v_cvt_f32_i32_e32 v97, v97
	v_cvt_f32_i32_e32 v96, v96
	s_waitcnt lgkmcnt(0)
	v_pk_mul_f32 v[102:103], v[160:161], v[98:99] op_sel_hi:[1,0]
	v_mul_f32_e32 v104, v98, v98
	v_pk_mul_f32 v[102:103], v[102:103], v[94:95]
	v_pk_mul_f32 v[90:91], v[94:95], v[90:91]
	v_pk_mul_f32 v[94:95], v[158:159], v[104:105] op_sel_hi:[1,0]
	v_cvt_f32_i32_e32 v93, v93
	v_pk_mul_f32 v[90:91], v[90:91], v[94:95]
	v_pk_mul_f32 v[94:95], v[156:157], v[98:99] op_sel_hi:[1,0]
	v_cvt_f32_i32_e32 v92, v92
	v_pk_mul_f32 v[94:95], v[94:95], v[96:97]
	v_exp_f32_e32 v102, v102
	v_exp_f32_e32 v94, v94
	v_exp_f32_e32 v95, v95
	v_exp_f32_e32 v103, v103
	v_cvt_f32_i32_e32 v87, v87
	v_cvt_f32_i32_e32 v86, v86
	v_pk_add_f32 v[94:95], v[94:95], 1.0 op_sel_hi:[1,0]
	v_pk_mul_f32 v[92:93], v[96:97], v[92:93]
	v_rcp_f32_e32 v94, v94
	v_rcp_f32_e32 v95, v95
	v_pk_mul_f32 v[96:97], v[154:155], v[104:105] op_sel_hi:[1,0]
	v_pk_add_f32 v[102:103], v[102:103], 1.0 op_sel_hi:[1,0]
	v_pk_mul_f32 v[92:93], v[92:93], v[96:97]
	v_rcp_f32_e32 v102, v102
	v_pk_mul_f32 v[92:93], v[92:93], v[94:95]
	v_pk_mul_f32 v[94:95], v[152:153], v[98:99] op_sel_hi:[1,0]
	v_rcp_f32_e32 v103, v103
	v_pk_mul_f32 v[94:95], v[94:95], v[86:87]
	v_cvt_f32_i32_e32 v83, v83
	v_exp_f32_e32 v94, v94
	v_exp_f32_e32 v95, v95
	v_cvt_f32_i32_e32 v82, v82
	v_cvt_f32_i32_e32 v89, v89
	v_cvt_f32_i32_e32 v88, v88
	v_pk_mul_f32 v[90:91], v[90:91], v[102:103]
	v_pk_mul_f32 v[82:83], v[86:87], v[82:83]
	v_cvt_pk_bf16_f32 v90, v90, v91
	v_cvt_pk_bf16_f32 v91, v92, v93
	v_pk_add_f32 v[92:93], v[94:95], 1.0 op_sel_hi:[1,0]
	v_pk_mul_f32 v[86:87], v[150:151], v[104:105] op_sel_hi:[1,0]
	v_rcp_f32_e32 v92, v92
	v_rcp_f32_e32 v93, v93
	v_pk_mul_f32 v[82:83], v[82:83], v[86:87]
	v_pk_mul_f32 v[86:87], v[148:149], v[98:99] op_sel_hi:[1,0]
	v_mad_i64_i32 v[100:101], s[28:29], v99, s49, v[162:163]
	v_pk_mul_f32 v[86:87], v[86:87], v[88:89]
	v_pk_mul_f32 v[82:83], v[82:83], v[92:93]
	v_exp_f32_e32 v86, v86
	v_exp_f32_e32 v87, v87
	v_cvt_pk_bf16_f32 v92, v82, v83
	v_cvt_f32_i32_e32 v83, v85
	v_cvt_f32_i32_e32 v82, v84
	v_pk_add_f32 v[84:85], v[86:87], 1.0 op_sel_hi:[1,0]
	v_pk_mul_f32 v[86:87], v[146:147], v[104:105] op_sel_hi:[1,0]
	v_rcp_f32_e32 v84, v84
	v_rcp_f32_e32 v85, v85
	v_pk_mul_f32 v[82:83], v[88:89], v[82:83]
	v_cvt_f32_i32_e32 v79, v79
	v_pk_mul_f32 v[82:83], v[82:83], v[86:87]
	v_cvt_f32_i32_e32 v78, v78
	v_pk_mul_f32 v[82:83], v[82:83], v[84:85]
	v_cvt_f32_i32_e32 v75, v75
	v_cvt_pk_bf16_f32 v93, v82, v83
	v_lshl_add_u64 v[82:83], v[100:101], 0, v[114:115]
	global_store_dwordx4 v[82:83], v[90:93], off sc0 sc1
	ds_read_b32 v82, v182 offset:192
	v_cvt_f32_i32_e32 v74, v74
	v_add_u32_e32 v83, s19, v172
	v_cvt_f32_i32_e32 v81, v81
	v_cvt_f32_i32_e32 v80, v80
	s_waitcnt lgkmcnt(0)
	v_pk_mul_f32 v[86:87], v[160:161], v[82:83] op_sel_hi:[1,0]
	v_mul_f32_e32 v88, v82, v82
	v_pk_mul_f32 v[86:87], v[86:87], v[78:79]
	v_pk_mul_f32 v[74:75], v[78:79], v[74:75]
	v_pk_mul_f32 v[78:79], v[158:159], v[88:89] op_sel_hi:[1,0]
	v_cvt_f32_i32_e32 v77, v77
	v_pk_mul_f32 v[74:75], v[74:75], v[78:79]
	v_pk_mul_f32 v[78:79], v[156:157], v[82:83] op_sel_hi:[1,0]
	v_cvt_f32_i32_e32 v76, v76
	v_pk_mul_f32 v[78:79], v[78:79], v[80:81]
	v_exp_f32_e32 v86, v86
	v_exp_f32_e32 v78, v78
	v_exp_f32_e32 v79, v79
	v_exp_f32_e32 v87, v87
	v_cvt_f32_i32_e32 v71, v71
	v_cvt_f32_i32_e32 v70, v70
	v_pk_add_f32 v[78:79], v[78:79], 1.0 op_sel_hi:[1,0]
	v_pk_mul_f32 v[76:77], v[80:81], v[76:77]
	v_rcp_f32_e32 v78, v78
	v_rcp_f32_e32 v79, v79
	v_pk_mul_f32 v[80:81], v[154:155], v[88:89] op_sel_hi:[1,0]
	v_pk_add_f32 v[86:87], v[86:87], 1.0 op_sel_hi:[1,0]
	v_pk_mul_f32 v[76:77], v[76:77], v[80:81]
	v_rcp_f32_e32 v86, v86
	v_pk_mul_f32 v[76:77], v[76:77], v[78:79]
	v_pk_mul_f32 v[78:79], v[152:153], v[82:83] op_sel_hi:[1,0]
	v_rcp_f32_e32 v87, v87
	v_pk_mul_f32 v[78:79], v[78:79], v[70:71]
	v_cvt_f32_i32_e32 v67, v67
	v_exp_f32_e32 v78, v78
	v_exp_f32_e32 v79, v79
	v_cvt_f32_i32_e32 v66, v66
	v_cvt_f32_i32_e32 v73, v73
	v_cvt_f32_i32_e32 v72, v72
	v_pk_mul_f32 v[74:75], v[74:75], v[86:87]
	v_pk_mul_f32 v[66:67], v[70:71], v[66:67]
	v_cvt_pk_bf16_f32 v74, v74, v75
	v_cvt_pk_bf16_f32 v75, v76, v77
	v_pk_add_f32 v[76:77], v[78:79], 1.0 op_sel_hi:[1,0]
	v_pk_mul_f32 v[70:71], v[150:151], v[88:89] op_sel_hi:[1,0]
	v_rcp_f32_e32 v76, v76
	v_rcp_f32_e32 v77, v77
	v_pk_mul_f32 v[66:67], v[66:67], v[70:71]
	v_pk_mul_f32 v[70:71], v[148:149], v[82:83] op_sel_hi:[1,0]
	v_mad_i64_i32 v[84:85], s[28:29], v83, s49, v[162:163]
	v_pk_mul_f32 v[70:71], v[70:71], v[72:73]
	v_pk_mul_f32 v[66:67], v[66:67], v[76:77]
	v_exp_f32_e32 v70, v70
	v_exp_f32_e32 v71, v71
	v_cvt_pk_bf16_f32 v76, v66, v67
	v_cvt_f32_i32_e32 v67, v69
	v_cvt_f32_i32_e32 v66, v68
	v_pk_add_f32 v[68:69], v[70:71], 1.0 op_sel_hi:[1,0]
	v_pk_mul_f32 v[70:71], v[146:147], v[88:89] op_sel_hi:[1,0]
	v_rcp_f32_e32 v68, v68
	v_rcp_f32_e32 v69, v69
	v_pk_mul_f32 v[66:67], v[72:73], v[66:67]
	v_cvt_f32_i32_e32 v63, v63
	v_pk_mul_f32 v[66:67], v[66:67], v[70:71]
	v_cvt_f32_i32_e32 v62, v62
	v_pk_mul_f32 v[66:67], v[66:67], v[68:69]
	v_cvt_f32_i32_e32 v59, v59
	v_cvt_pk_bf16_f32 v77, v66, v67
	v_lshl_add_u64 v[66:67], v[84:85], 0, v[114:115]
	global_store_dwordx4 v[66:67], v[74:77], off sc0 sc1
	ds_read_b32 v66, v182 offset:512
	v_cvt_f32_i32_e32 v58, v58
	v_add_u32_e32 v67, s19, v173
	v_cvt_f32_i32_e32 v65, v65
	v_cvt_f32_i32_e32 v64, v64
	s_waitcnt lgkmcnt(0)
	v_pk_mul_f32 v[70:71], v[160:161], v[66:67] op_sel_hi:[1,0]
	v_mul_f32_e32 v72, v66, v66
	v_pk_mul_f32 v[70:71], v[70:71], v[62:63]
	v_pk_mul_f32 v[58:59], v[62:63], v[58:59]
	v_pk_mul_f32 v[62:63], v[158:159], v[72:73] op_sel_hi:[1,0]
	v_cvt_f32_i32_e32 v61, v61
	v_pk_mul_f32 v[58:59], v[58:59], v[62:63]
	v_pk_mul_f32 v[62:63], v[156:157], v[66:67] op_sel_hi:[1,0]
	v_cvt_f32_i32_e32 v60, v60
	v_pk_mul_f32 v[62:63], v[62:63], v[64:65]
	v_exp_f32_e32 v70, v70
	v_exp_f32_e32 v62, v62
	v_exp_f32_e32 v63, v63
	v_exp_f32_e32 v71, v71
	v_cvt_f32_i32_e32 v55, v55
	v_cvt_f32_i32_e32 v54, v54
	v_pk_add_f32 v[62:63], v[62:63], 1.0 op_sel_hi:[1,0]
	v_pk_mul_f32 v[60:61], v[64:65], v[60:61]
	v_rcp_f32_e32 v62, v62
	v_rcp_f32_e32 v63, v63
	v_pk_mul_f32 v[64:65], v[154:155], v[72:73] op_sel_hi:[1,0]
	v_pk_add_f32 v[70:71], v[70:71], 1.0 op_sel_hi:[1,0]
	v_pk_mul_f32 v[60:61], v[60:61], v[64:65]
	v_rcp_f32_e32 v70, v70
	v_pk_mul_f32 v[60:61], v[60:61], v[62:63]
	v_pk_mul_f32 v[62:63], v[152:153], v[66:67] op_sel_hi:[1,0]
	v_rcp_f32_e32 v71, v71
	v_pk_mul_f32 v[62:63], v[62:63], v[54:55]
	v_cvt_f32_i32_e32 v51, v51
	v_exp_f32_e32 v62, v62
	v_exp_f32_e32 v63, v63
	v_cvt_f32_i32_e32 v50, v50
	v_cvt_f32_i32_e32 v57, v57
	v_cvt_f32_i32_e32 v56, v56
	v_pk_mul_f32 v[58:59], v[58:59], v[70:71]
	v_pk_mul_f32 v[50:51], v[54:55], v[50:51]
	v_cvt_pk_bf16_f32 v58, v58, v59
	v_cvt_pk_bf16_f32 v59, v60, v61
	v_pk_add_f32 v[60:61], v[62:63], 1.0 op_sel_hi:[1,0]
	v_pk_mul_f32 v[54:55], v[150:151], v[72:73] op_sel_hi:[1,0]
	v_rcp_f32_e32 v60, v60
	v_rcp_f32_e32 v61, v61
	v_pk_mul_f32 v[50:51], v[50:51], v[54:55]
	v_pk_mul_f32 v[54:55], v[148:149], v[66:67] op_sel_hi:[1,0]
	v_mad_i64_i32 v[68:69], s[28:29], v67, s49, v[162:163]
	v_pk_mul_f32 v[54:55], v[54:55], v[56:57]
	v_pk_mul_f32 v[50:51], v[50:51], v[60:61]
	v_exp_f32_e32 v54, v54
	v_exp_f32_e32 v55, v55
	v_cvt_pk_bf16_f32 v60, v50, v51
	v_cvt_f32_i32_e32 v51, v53
	v_cvt_f32_i32_e32 v50, v52
	v_pk_add_f32 v[52:53], v[54:55], 1.0 op_sel_hi:[1,0]
	v_pk_mul_f32 v[54:55], v[146:147], v[72:73] op_sel_hi:[1,0]
	v_rcp_f32_e32 v52, v52
	v_rcp_f32_e32 v53, v53
	v_pk_mul_f32 v[50:51], v[56:57], v[50:51]
	v_cvt_f32_i32_e32 v47, v47
	v_pk_mul_f32 v[50:51], v[50:51], v[54:55]
	v_cvt_f32_i32_e32 v46, v46
	v_pk_mul_f32 v[50:51], v[50:51], v[52:53]
	v_cvt_f32_i32_e32 v43, v43
	v_cvt_pk_bf16_f32 v61, v50, v51
	v_lshl_add_u64 v[50:51], v[68:69], 0, v[114:115]
	global_store_dwordx4 v[50:51], v[58:61], off sc0 sc1
	ds_read_b32 v50, v182 offset:576
	v_cvt_f32_i32_e32 v42, v42
	v_add_u32_e32 v51, s19, v174
	v_cvt_f32_i32_e32 v49, v49
	v_cvt_f32_i32_e32 v48, v48
	s_waitcnt lgkmcnt(0)
	v_pk_mul_f32 v[54:55], v[160:161], v[50:51] op_sel_hi:[1,0]
	v_mul_f32_e32 v56, v50, v50
	v_pk_mul_f32 v[54:55], v[54:55], v[46:47]
	v_pk_mul_f32 v[42:43], v[46:47], v[42:43]
	v_pk_mul_f32 v[46:47], v[158:159], v[56:57] op_sel_hi:[1,0]
	v_cvt_f32_i32_e32 v45, v45
	v_pk_mul_f32 v[42:43], v[42:43], v[46:47]
	v_pk_mul_f32 v[46:47], v[156:157], v[50:51] op_sel_hi:[1,0]
	v_cvt_f32_i32_e32 v44, v44
	v_pk_mul_f32 v[46:47], v[46:47], v[48:49]
	v_exp_f32_e32 v54, v54
	v_exp_f32_e32 v46, v46
	v_exp_f32_e32 v47, v47
	v_exp_f32_e32 v55, v55
	v_cvt_f32_i32_e32 v39, v39
	v_cvt_f32_i32_e32 v38, v38
	v_pk_add_f32 v[46:47], v[46:47], 1.0 op_sel_hi:[1,0]
	v_pk_mul_f32 v[44:45], v[48:49], v[44:45]
	v_rcp_f32_e32 v46, v46
	v_rcp_f32_e32 v47, v47
	v_pk_mul_f32 v[48:49], v[154:155], v[56:57] op_sel_hi:[1,0]
	v_pk_add_f32 v[54:55], v[54:55], 1.0 op_sel_hi:[1,0]
	v_pk_mul_f32 v[44:45], v[44:45], v[48:49]
	v_rcp_f32_e32 v54, v54
	v_pk_mul_f32 v[44:45], v[44:45], v[46:47]
	v_pk_mul_f32 v[46:47], v[152:153], v[50:51] op_sel_hi:[1,0]
	v_rcp_f32_e32 v55, v55
	v_pk_mul_f32 v[46:47], v[46:47], v[38:39]
	v_cvt_f32_i32_e32 v35, v35
	v_exp_f32_e32 v46, v46
	v_exp_f32_e32 v47, v47
	v_cvt_f32_i32_e32 v34, v34
	v_cvt_f32_i32_e32 v41, v41
	v_cvt_f32_i32_e32 v40, v40
	v_pk_mul_f32 v[42:43], v[42:43], v[54:55]
	v_pk_mul_f32 v[34:35], v[38:39], v[34:35]
	v_cvt_pk_bf16_f32 v42, v42, v43
	v_cvt_pk_bf16_f32 v43, v44, v45
	v_pk_add_f32 v[44:45], v[46:47], 1.0 op_sel_hi:[1,0]
	v_pk_mul_f32 v[38:39], v[150:151], v[56:57] op_sel_hi:[1,0]
	v_rcp_f32_e32 v44, v44
	v_rcp_f32_e32 v45, v45
	v_pk_mul_f32 v[34:35], v[34:35], v[38:39]
	v_pk_mul_f32 v[38:39], v[148:149], v[50:51] op_sel_hi:[1,0]
	v_mad_i64_i32 v[52:53], s[28:29], v51, s49, v[162:163]
	v_pk_mul_f32 v[38:39], v[38:39], v[40:41]
	v_pk_mul_f32 v[34:35], v[34:35], v[44:45]
	v_exp_f32_e32 v38, v38
	v_exp_f32_e32 v39, v39
	v_cvt_pk_bf16_f32 v44, v34, v35
	v_cvt_f32_i32_e32 v35, v37
	v_cvt_f32_i32_e32 v34, v36
	v_pk_add_f32 v[36:37], v[38:39], 1.0 op_sel_hi:[1,0]
	v_pk_mul_f32 v[38:39], v[146:147], v[56:57] op_sel_hi:[1,0]
	v_rcp_f32_e32 v36, v36
	v_rcp_f32_e32 v37, v37
	v_pk_mul_f32 v[34:35], v[40:41], v[34:35]
	v_cvt_f32_i32_e32 v31, v31
	v_pk_mul_f32 v[34:35], v[34:35], v[38:39]
	v_cvt_f32_i32_e32 v30, v30
	v_pk_mul_f32 v[34:35], v[34:35], v[36:37]
	v_cvt_f32_i32_e32 v27, v27
	v_cvt_pk_bf16_f32 v45, v34, v35
	v_lshl_add_u64 v[34:35], v[52:53], 0, v[114:115]
	global_store_dwordx4 v[34:35], v[42:45], off sc0 sc1
	ds_read_b32 v34, v182 offset:640
	v_cvt_f32_i32_e32 v26, v26
	v_add_u32_e32 v35, s19, v175
	v_cvt_f32_i32_e32 v33, v33
	v_cvt_f32_i32_e32 v32, v32
	s_waitcnt lgkmcnt(0)
	v_pk_mul_f32 v[38:39], v[160:161], v[34:35] op_sel_hi:[1,0]
	v_mul_f32_e32 v40, v34, v34
	v_pk_mul_f32 v[38:39], v[38:39], v[30:31]
	v_pk_mul_f32 v[26:27], v[30:31], v[26:27]
	v_pk_mul_f32 v[30:31], v[158:159], v[40:41] op_sel_hi:[1,0]
	v_cvt_f32_i32_e32 v29, v29
	v_pk_mul_f32 v[26:27], v[26:27], v[30:31]
	v_pk_mul_f32 v[30:31], v[156:157], v[34:35] op_sel_hi:[1,0]
	v_cvt_f32_i32_e32 v28, v28
	v_pk_mul_f32 v[30:31], v[30:31], v[32:33]
	v_exp_f32_e32 v38, v38
	v_exp_f32_e32 v30, v30
	v_exp_f32_e32 v31, v31
	v_exp_f32_e32 v39, v39
	v_cvt_f32_i32_e32 v23, v23
	v_cvt_f32_i32_e32 v22, v22
	v_pk_add_f32 v[30:31], v[30:31], 1.0 op_sel_hi:[1,0]
	v_pk_mul_f32 v[28:29], v[32:33], v[28:29]
	v_rcp_f32_e32 v30, v30
	v_rcp_f32_e32 v31, v31
	v_pk_mul_f32 v[32:33], v[154:155], v[40:41] op_sel_hi:[1,0]
	v_pk_add_f32 v[38:39], v[38:39], 1.0 op_sel_hi:[1,0]
	v_pk_mul_f32 v[28:29], v[28:29], v[32:33]
	v_rcp_f32_e32 v38, v38
	v_pk_mul_f32 v[28:29], v[28:29], v[30:31]
	v_pk_mul_f32 v[30:31], v[152:153], v[34:35] op_sel_hi:[1,0]
	v_rcp_f32_e32 v39, v39
	v_pk_mul_f32 v[30:31], v[30:31], v[22:23]
	v_cvt_f32_i32_e32 v19, v19
	v_exp_f32_e32 v30, v30
	v_exp_f32_e32 v31, v31
	v_cvt_f32_i32_e32 v18, v18
	v_cvt_f32_i32_e32 v25, v25
	v_cvt_f32_i32_e32 v24, v24
	v_pk_mul_f32 v[26:27], v[26:27], v[38:39]
	v_pk_mul_f32 v[18:19], v[22:23], v[18:19]
	v_cvt_pk_bf16_f32 v26, v26, v27
	v_cvt_pk_bf16_f32 v27, v28, v29
	v_pk_add_f32 v[28:29], v[30:31], 1.0 op_sel_hi:[1,0]
	v_pk_mul_f32 v[22:23], v[150:151], v[40:41] op_sel_hi:[1,0]
	v_rcp_f32_e32 v28, v28
	v_rcp_f32_e32 v29, v29
	v_pk_mul_f32 v[18:19], v[18:19], v[22:23]
	v_pk_mul_f32 v[22:23], v[148:149], v[34:35] op_sel_hi:[1,0]
	v_mad_i64_i32 v[36:37], s[28:29], v35, s49, v[162:163]
	v_pk_mul_f32 v[22:23], v[22:23], v[24:25]
	v_pk_mul_f32 v[18:19], v[18:19], v[28:29]
	v_exp_f32_e32 v22, v22
	v_exp_f32_e32 v23, v23
	v_cvt_pk_bf16_f32 v28, v18, v19
	v_cvt_f32_i32_e32 v19, v21
	v_cvt_f32_i32_e32 v18, v20
	v_pk_add_f32 v[20:21], v[22:23], 1.0 op_sel_hi:[1,0]
	v_pk_mul_f32 v[22:23], v[146:147], v[40:41] op_sel_hi:[1,0]
	v_rcp_f32_e32 v20, v20
	v_rcp_f32_e32 v21, v21
	v_pk_mul_f32 v[18:19], v[24:25], v[18:19]
	v_cvt_f32_i32_e32 v15, v15
	v_pk_mul_f32 v[18:19], v[18:19], v[22:23]
	v_cvt_f32_i32_e32 v14, v14
	v_pk_mul_f32 v[18:19], v[18:19], v[20:21]
	v_cvt_f32_i32_e32 v11, v11
	v_cvt_pk_bf16_f32 v29, v18, v19
	v_lshl_add_u64 v[18:19], v[36:37], 0, v[114:115]
	global_store_dwordx4 v[18:19], v[26:29], off sc0 sc1
	ds_read_b32 v18, v182 offset:704
	v_cvt_f32_i32_e32 v10, v10
	v_add_u32_e32 v19, s19, v176
	v_cvt_f32_i32_e32 v17, v17
	v_cvt_f32_i32_e32 v16, v16
	s_waitcnt lgkmcnt(0)
	v_pk_mul_f32 v[22:23], v[160:161], v[18:19] op_sel_hi:[1,0]
	v_mul_f32_e32 v24, v18, v18
	v_pk_mul_f32 v[22:23], v[22:23], v[14:15]
	v_pk_mul_f32 v[10:11], v[14:15], v[10:11]
	v_pk_mul_f32 v[14:15], v[158:159], v[24:25] op_sel_hi:[1,0]
	v_cvt_f32_i32_e32 v13, v13
	v_pk_mul_f32 v[10:11], v[10:11], v[14:15]
	v_pk_mul_f32 v[14:15], v[156:157], v[18:19] op_sel_hi:[1,0]
	v_cvt_f32_i32_e32 v12, v12
	v_pk_mul_f32 v[14:15], v[14:15], v[16:17]
	v_exp_f32_e32 v22, v22
	v_exp_f32_e32 v14, v14
	v_exp_f32_e32 v15, v15
	v_exp_f32_e32 v23, v23
	v_cvt_f32_i32_e32 v7, v7
	v_cvt_f32_i32_e32 v6, v6
	v_pk_add_f32 v[14:15], v[14:15], 1.0 op_sel_hi:[1,0]
	v_pk_mul_f32 v[12:13], v[16:17], v[12:13]
	v_rcp_f32_e32 v14, v14
	v_rcp_f32_e32 v15, v15
	v_pk_mul_f32 v[16:17], v[154:155], v[24:25] op_sel_hi:[1,0]
	v_pk_add_f32 v[22:23], v[22:23], 1.0 op_sel_hi:[1,0]
	v_pk_mul_f32 v[12:13], v[12:13], v[16:17]
	v_rcp_f32_e32 v22, v22
	v_pk_mul_f32 v[12:13], v[12:13], v[14:15]
	v_pk_mul_f32 v[14:15], v[152:153], v[18:19] op_sel_hi:[1,0]
	v_rcp_f32_e32 v23, v23
	v_pk_mul_f32 v[14:15], v[14:15], v[6:7]
	v_cvt_f32_i32_e32 v3, v3
	v_exp_f32_e32 v14, v14
	v_exp_f32_e32 v15, v15
	v_cvt_f32_i32_e32 v2, v2
	v_cvt_f32_i32_e32 v9, v9
	v_cvt_f32_i32_e32 v8, v8
	v_pk_mul_f32 v[10:11], v[10:11], v[22:23]
	v_pk_mul_f32 v[2:3], v[6:7], v[2:3]
	v_cvt_pk_bf16_f32 v10, v10, v11
	v_cvt_pk_bf16_f32 v11, v12, v13
	v_pk_add_f32 v[12:13], v[14:15], 1.0 op_sel_hi:[1,0]
	v_pk_mul_f32 v[6:7], v[150:151], v[24:25] op_sel_hi:[1,0]
	v_rcp_f32_e32 v12, v12
	v_rcp_f32_e32 v13, v13
	v_pk_mul_f32 v[2:3], v[2:3], v[6:7]
	v_pk_mul_f32 v[6:7], v[148:149], v[18:19] op_sel_hi:[1,0]
	v_mad_i64_i32 v[20:21], s[28:29], v19, s49, v[162:163]
	v_pk_mul_f32 v[6:7], v[6:7], v[8:9]
	v_pk_mul_f32 v[2:3], v[2:3], v[12:13]
	v_exp_f32_e32 v6, v6
	v_exp_f32_e32 v7, v7
	v_cvt_pk_bf16_f32 v12, v2, v3
	v_cvt_f32_i32_e32 v3, v5
	v_cvt_f32_i32_e32 v2, v4
	v_pk_add_f32 v[4:5], v[6:7], 1.0 op_sel_hi:[1,0]
	v_pk_mul_f32 v[6:7], v[146:147], v[24:25] op_sel_hi:[1,0]
	v_rcp_f32_e32 v4, v4
	v_rcp_f32_e32 v5, v5
	v_pk_mul_f32 v[2:3], v[8:9], v[2:3]
	s_andn2_b64 vcc, exec, s[4:5]
	v_pk_mul_f32 v[2:3], v[2:3], v[6:7]
	s_mov_b64 s[4:5], -1
	v_pk_mul_f32 v[2:3], v[2:3], v[4:5]
	s_nop 0
	v_cvt_pk_bf16_f32 v13, v2, v3
	v_lshl_add_u64 v[2:3], v[20:21], 0, v[114:115]
	global_store_dwordx4 v[2:3], v[10:13], off sc0 sc1
	s_cbranch_vccnz .LBB0_733
	s_andn2_b64 vcc, exec, s[12:13]
	s_cbranch_vccnz .LBB0_732
	s_barrier
	s_branch .LBB0_732

.LBB0_1598:
	s_lshl_b32 s21, s63, 11
	s_add_i32 s21, s21, 0
	s_add_i32 s23, s21, 0x20180
	s_lshl_b32 s21, s47, 2
	s_add_i32 s21, s23, s21
	v_lshl_add_u32 v154, v164, 2, s21
	ds_read_b128 v[146:149], v154 offset:1024
	ds_read_b128 v[150:153], v154 offset:1536
	ds_read_b128 v[182:185], v154 offset:1040
	ds_read_b128 v[186:189], v154 offset:1552
	v_cvt_f32_i32_e32 v127, v127
	v_cvt_f32_i32_e32 v126, v126
	s_waitcnt lgkmcnt(0)
	v_pk_mul_f32 v[154:155], v[148:149], v[152:153]
	v_pk_mul_f32 v[158:159], v[146:147], v[150:151]
	v_pk_mul_f32 v[152:153], v[182:183], s[16:17] op_sel_hi:[1,0]
	v_pk_mul_f32 v[150:151], v[182:183], v[186:187]
	v_lshl_add_u32 v182, v165, 2, s23
	ds_read_b32 v186, v182
	v_cvt_f32_i32_e32 v123, v123
	v_cvt_f32_i32_e32 v122, v122
	v_pk_mul_f32 v[160:161], v[146:147], s[16:17] op_sel_hi:[1,0]
	v_cvt_f32_i32_e32 v129, v129
	v_cvt_f32_i32_e32 v128, v128
	s_waitcnt lgkmcnt(0)
	v_pk_mul_f32 v[190:191], v[160:161], v[186:187] op_sel_hi:[1,0]
	v_mul_f32_e32 v192, v186, v186
	v_pk_mul_f32 v[156:157], v[148:149], s[16:17] op_sel_hi:[1,0]
	v_pk_mul_f32 v[190:191], v[190:191], v[126:127]
	v_pk_mul_f32 v[122:123], v[126:127], v[122:123]
	v_pk_mul_f32 v[126:127], v[158:159], v[192:193] op_sel_hi:[1,0]
	v_cvt_f32_i32_e32 v125, v125
	v_pk_mul_f32 v[122:123], v[122:123], v[126:127]
	v_pk_mul_f32 v[126:127], v[156:157], v[186:187] op_sel_hi:[1,0]
	v_cvt_f32_i32_e32 v124, v124
	v_pk_mul_f32 v[126:127], v[126:127], v[128:129]
	v_exp_f32_e32 v190, v190
	v_exp_f32_e32 v126, v126
	v_exp_f32_e32 v127, v127
	v_exp_f32_e32 v191, v191
	v_cvt_f32_i32_e32 v119, v119
	v_cvt_f32_i32_e32 v118, v118
	v_pk_add_f32 v[126:127], v[126:127], 1.0 op_sel_hi:[1,0]
	v_pk_mul_f32 v[124:125], v[128:129], v[124:125]
	v_rcp_f32_e32 v126, v126
	v_rcp_f32_e32 v127, v127
	v_pk_mul_f32 v[128:129], v[154:155], v[192:193] op_sel_hi:[1,0]
	v_pk_add_f32 v[190:191], v[190:191], 1.0 op_sel_hi:[1,0]
	v_pk_mul_f32 v[124:125], v[124:125], v[128:129]
	v_rcp_f32_e32 v190, v190
	v_pk_mul_f32 v[124:125], v[124:125], v[126:127]
	v_pk_mul_f32 v[126:127], v[152:153], v[186:187] op_sel_hi:[1,0]
	v_rcp_f32_e32 v191, v191
	v_pk_mul_f32 v[126:127], v[126:127], v[118:119]
	v_cvt_f32_i32_e32 v115, v115
	v_exp_f32_e32 v126, v126
	v_exp_f32_e32 v127, v127
	v_cvt_f32_i32_e32 v114, v114
	v_cvt_f32_i32_e32 v121, v121
	v_cvt_f32_i32_e32 v120, v120
	v_pk_mul_f32 v[122:123], v[122:123], v[190:191]
	v_pk_mul_f32 v[148:149], v[184:185], s[16:17] op_sel_hi:[1,0]
	v_cvt_pk_bf16_f32 v122, v122, v123
	v_cvt_pk_bf16_f32 v123, v124, v125
	v_pk_add_f32 v[124:125], v[126:127], 1.0 op_sel_hi:[1,0]
	v_pk_mul_f32 v[114:115], v[118:119], v[114:115]
	v_pk_mul_f32 v[118:119], v[150:151], v[192:193] op_sel_hi:[1,0]
	v_rcp_f32_e32 v124, v124
	v_rcp_f32_e32 v125, v125
	v_pk_mul_f32 v[114:115], v[114:115], v[118:119]
	v_pk_mul_f32 v[118:119], v[148:149], v[186:187] op_sel_hi:[1,0]
	v_pk_mul_f32 v[146:147], v[184:185], v[188:189]
	v_pk_mul_f32 v[118:119], v[118:119], v[120:121]
	v_pk_mul_f32 v[114:115], v[114:115], v[124:125]
	v_exp_f32_e32 v118, v118
	v_exp_f32_e32 v119, v119
	v_cvt_pk_bf16_f32 v124, v114, v115
	v_cvt_f32_i32_e32 v115, v117
	v_cvt_f32_i32_e32 v114, v116
	v_pk_add_f32 v[116:117], v[118:119], 1.0 op_sel_hi:[1,0]
	v_pk_mul_f32 v[118:119], v[146:147], v[192:193] op_sel_hi:[1,0]
	v_rcp_f32_e32 v116, v116
	v_rcp_f32_e32 v117, v117
	v_pk_mul_f32 v[114:115], v[120:121], v[114:115]
	v_lshl_or_b32 v184, s53, 7, v177
	s_lshl_b32 s21, s28, 8
	v_pk_mul_f32 v[114:115], v[114:115], v[118:119]
	v_ashrrev_i32_e32 v185, 31, v184
	v_add_u32_e32 v183, s21, v165
	v_mov_b64_e32 v[162:163], s[60:61]
	v_pk_mul_f32 v[114:115], v[114:115], v[116:117]
	v_mad_i64_i32 v[188:189], s[30:31], v183, s51, v[162:163]
	v_cvt_pk_bf16_f32 v125, v114, v115
	v_lshlrev_b64 v[114:115], 1, v[184:185]
	v_lshl_add_u64 v[116:117], v[188:189], 0, v[114:115]
	global_store_dwordx4 v[116:117], v[122:125], off sc0 sc1
	ds_read_b32 v116, v182 offset:64
	v_cvt_f32_i32_e32 v111, v111
	v_cvt_f32_i32_e32 v110, v110
	v_cvt_f32_i32_e32 v107, v107
	v_cvt_f32_i32_e32 v106, v106
	v_add_u32_e32 v117, s21, v170
	v_cvt_f32_i32_e32 v113, v113
	v_cvt_f32_i32_e32 v112, v112
	s_waitcnt lgkmcnt(0)
	v_pk_mul_f32 v[120:121], v[160:161], v[116:117] op_sel_hi:[1,0]
	v_mul_f32_e32 v122, v116, v116
	v_pk_mul_f32 v[120:121], v[120:121], v[110:111]
	v_pk_mul_f32 v[106:107], v[110:111], v[106:107]
	v_pk_mul_f32 v[110:111], v[158:159], v[122:123] op_sel_hi:[1,0]
	v_cvt_f32_i32_e32 v109, v109
	v_pk_mul_f32 v[106:107], v[106:107], v[110:111]
	v_pk_mul_f32 v[110:111], v[156:157], v[116:117] op_sel_hi:[1,0]
	v_cvt_f32_i32_e32 v108, v108
	v_pk_mul_f32 v[110:111], v[110:111], v[112:113]
	v_exp_f32_e32 v120, v120
	v_exp_f32_e32 v110, v110
	v_exp_f32_e32 v111, v111
	v_exp_f32_e32 v121, v121
	v_cvt_f32_i32_e32 v103, v103
	v_cvt_f32_i32_e32 v102, v102
	v_pk_add_f32 v[110:111], v[110:111], 1.0 op_sel_hi:[1,0]
	v_pk_mul_f32 v[108:109], v[112:113], v[108:109]
	v_rcp_f32_e32 v110, v110
	v_rcp_f32_e32 v111, v111
	v_pk_mul_f32 v[112:113], v[154:155], v[122:123] op_sel_hi:[1,0]
	v_pk_add_f32 v[120:121], v[120:121], 1.0 op_sel_hi:[1,0]
	v_pk_mul_f32 v[108:109], v[108:109], v[112:113]
	v_rcp_f32_e32 v120, v120
	v_pk_mul_f32 v[108:109], v[108:109], v[110:111]
	v_pk_mul_f32 v[110:111], v[152:153], v[116:117] op_sel_hi:[1,0]
	v_rcp_f32_e32 v121, v121
	v_pk_mul_f32 v[110:111], v[110:111], v[102:103]
	v_cvt_f32_i32_e32 v99, v99
	v_exp_f32_e32 v110, v110
	v_exp_f32_e32 v111, v111
	v_cvt_f32_i32_e32 v98, v98
	v_cvt_f32_i32_e32 v105, v105
	v_cvt_f32_i32_e32 v104, v104
	v_pk_mul_f32 v[106:107], v[106:107], v[120:121]
	v_pk_mul_f32 v[98:99], v[102:103], v[98:99]
	v_cvt_pk_bf16_f32 v106, v106, v107
	v_cvt_pk_bf16_f32 v107, v108, v109
	v_pk_add_f32 v[108:109], v[110:111], 1.0 op_sel_hi:[1,0]
	v_pk_mul_f32 v[102:103], v[150:151], v[122:123] op_sel_hi:[1,0]
	v_rcp_f32_e32 v108, v108
	v_rcp_f32_e32 v109, v109
	v_pk_mul_f32 v[98:99], v[98:99], v[102:103]
	v_pk_mul_f32 v[102:103], v[148:149], v[116:117] op_sel_hi:[1,0]
	v_mad_i64_i32 v[118:119], s[30:31], v117, s51, v[162:163]
	v_pk_mul_f32 v[102:103], v[102:103], v[104:105]
	v_pk_mul_f32 v[98:99], v[98:99], v[108:109]
	v_exp_f32_e32 v102, v102
	v_exp_f32_e32 v103, v103
	v_cvt_pk_bf16_f32 v108, v98, v99
	v_cvt_f32_i32_e32 v99, v101
	v_cvt_f32_i32_e32 v98, v100
	v_pk_add_f32 v[100:101], v[102:103], 1.0 op_sel_hi:[1,0]
	v_pk_mul_f32 v[102:103], v[146:147], v[122:123] op_sel_hi:[1,0]
	v_rcp_f32_e32 v100, v100
	v_rcp_f32_e32 v101, v101
	v_pk_mul_f32 v[98:99], v[104:105], v[98:99]
	v_cvt_f32_i32_e32 v95, v95
	v_pk_mul_f32 v[98:99], v[98:99], v[102:103]
	v_cvt_f32_i32_e32 v94, v94
	v_pk_mul_f32 v[98:99], v[98:99], v[100:101]
	v_cvt_f32_i32_e32 v91, v91
	v_cvt_pk_bf16_f32 v109, v98, v99
	v_lshl_add_u64 v[98:99], v[118:119], 0, v[114:115]
	global_store_dwordx4 v[98:99], v[106:109], off sc0 sc1
	ds_read_b32 v98, v182 offset:128
	v_cvt_f32_i32_e32 v90, v90
	v_add_u32_e32 v99, s21, v171
	v_cvt_f32_i32_e32 v97, v97
	v_cvt_f32_i32_e32 v96, v96
	s_waitcnt lgkmcnt(0)
	v_pk_mul_f32 v[102:103], v[160:161], v[98:99] op_sel_hi:[1,0]
	v_mul_f32_e32 v104, v98, v98
	v_pk_mul_f32 v[102:103], v[102:103], v[94:95]
	v_pk_mul_f32 v[90:91], v[94:95], v[90:91]
	v_pk_mul_f32 v[94:95], v[158:159], v[104:105] op_sel_hi:[1,0]
	v_cvt_f32_i32_e32 v93, v93
	v_pk_mul_f32 v[90:91], v[90:91], v[94:95]
	v_pk_mul_f32 v[94:95], v[156:157], v[98:99] op_sel_hi:[1,0]
	v_cvt_f32_i32_e32 v92, v92
	v_pk_mul_f32 v[94:95], v[94:95], v[96:97]
	v_exp_f32_e32 v102, v102
	v_exp_f32_e32 v94, v94
	v_exp_f32_e32 v95, v95
	v_exp_f32_e32 v103, v103
	v_cvt_f32_i32_e32 v87, v87
	v_cvt_f32_i32_e32 v86, v86
	v_pk_add_f32 v[94:95], v[94:95], 1.0 op_sel_hi:[1,0]
	v_pk_mul_f32 v[92:93], v[96:97], v[92:93]
	v_rcp_f32_e32 v94, v94
	v_rcp_f32_e32 v95, v95
	v_pk_mul_f32 v[96:97], v[154:155], v[104:105] op_sel_hi:[1,0]
	v_pk_add_f32 v[102:103], v[102:103], 1.0 op_sel_hi:[1,0]
	v_pk_mul_f32 v[92:93], v[92:93], v[96:97]
	v_rcp_f32_e32 v102, v102
	v_pk_mul_f32 v[92:93], v[92:93], v[94:95]
	v_pk_mul_f32 v[94:95], v[152:153], v[98:99] op_sel_hi:[1,0]
	v_rcp_f32_e32 v103, v103
	v_pk_mul_f32 v[94:95], v[94:95], v[86:87]
	v_cvt_f32_i32_e32 v83, v83
	v_exp_f32_e32 v94, v94
	v_exp_f32_e32 v95, v95
	v_cvt_f32_i32_e32 v82, v82
	v_cvt_f32_i32_e32 v89, v89
	v_cvt_f32_i32_e32 v88, v88
	v_pk_mul_f32 v[90:91], v[90:91], v[102:103]
	v_pk_mul_f32 v[82:83], v[86:87], v[82:83]
	v_cvt_pk_bf16_f32 v90, v90, v91
	v_cvt_pk_bf16_f32 v91, v92, v93
	v_pk_add_f32 v[92:93], v[94:95], 1.0 op_sel_hi:[1,0]
	v_pk_mul_f32 v[86:87], v[150:151], v[104:105] op_sel_hi:[1,0]
	v_rcp_f32_e32 v92, v92
	v_rcp_f32_e32 v93, v93
	v_pk_mul_f32 v[82:83], v[82:83], v[86:87]
	v_pk_mul_f32 v[86:87], v[148:149], v[98:99] op_sel_hi:[1,0]
	v_mad_i64_i32 v[100:101], s[30:31], v99, s51, v[162:163]
	v_pk_mul_f32 v[86:87], v[86:87], v[88:89]
	v_pk_mul_f32 v[82:83], v[82:83], v[92:93]
	v_exp_f32_e32 v86, v86
	v_exp_f32_e32 v87, v87
	v_cvt_pk_bf16_f32 v92, v82, v83
	v_cvt_f32_i32_e32 v83, v85
	v_cvt_f32_i32_e32 v82, v84
	v_pk_add_f32 v[84:85], v[86:87], 1.0 op_sel_hi:[1,0]
	v_pk_mul_f32 v[86:87], v[146:147], v[104:105] op_sel_hi:[1,0]
	v_rcp_f32_e32 v84, v84
	v_rcp_f32_e32 v85, v85
	v_pk_mul_f32 v[82:83], v[88:89], v[82:83]
	v_cvt_f32_i32_e32 v79, v79
	v_pk_mul_f32 v[82:83], v[82:83], v[86:87]
	v_cvt_f32_i32_e32 v78, v78
	v_pk_mul_f32 v[82:83], v[82:83], v[84:85]
	v_cvt_f32_i32_e32 v75, v75
	v_cvt_pk_bf16_f32 v93, v82, v83
	v_lshl_add_u64 v[82:83], v[100:101], 0, v[114:115]
	global_store_dwordx4 v[82:83], v[90:93], off sc0 sc1
	ds_read_b32 v82, v182 offset:192
	v_cvt_f32_i32_e32 v74, v74
	v_add_u32_e32 v83, s21, v172
	v_cvt_f32_i32_e32 v81, v81
	v_cvt_f32_i32_e32 v80, v80
	s_waitcnt lgkmcnt(0)
	v_pk_mul_f32 v[86:87], v[160:161], v[82:83] op_sel_hi:[1,0]
	v_mul_f32_e32 v88, v82, v82
	v_pk_mul_f32 v[86:87], v[86:87], v[78:79]
	v_pk_mul_f32 v[74:75], v[78:79], v[74:75]
	v_pk_mul_f32 v[78:79], v[158:159], v[88:89] op_sel_hi:[1,0]
	v_cvt_f32_i32_e32 v77, v77
	v_pk_mul_f32 v[74:75], v[74:75], v[78:79]
	v_pk_mul_f32 v[78:79], v[156:157], v[82:83] op_sel_hi:[1,0]
	v_cvt_f32_i32_e32 v76, v76
	v_pk_mul_f32 v[78:79], v[78:79], v[80:81]
	v_exp_f32_e32 v86, v86
	v_exp_f32_e32 v78, v78
	v_exp_f32_e32 v79, v79
	v_exp_f32_e32 v87, v87
	v_cvt_f32_i32_e32 v71, v71
	v_cvt_f32_i32_e32 v70, v70
	v_pk_add_f32 v[78:79], v[78:79], 1.0 op_sel_hi:[1,0]
	v_pk_mul_f32 v[76:77], v[80:81], v[76:77]
	v_rcp_f32_e32 v78, v78
	v_rcp_f32_e32 v79, v79
	v_pk_mul_f32 v[80:81], v[154:155], v[88:89] op_sel_hi:[1,0]
	v_pk_add_f32 v[86:87], v[86:87], 1.0 op_sel_hi:[1,0]
	v_pk_mul_f32 v[76:77], v[76:77], v[80:81]
	v_rcp_f32_e32 v86, v86
	v_pk_mul_f32 v[76:77], v[76:77], v[78:79]
	v_pk_mul_f32 v[78:79], v[152:153], v[82:83] op_sel_hi:[1,0]
	v_rcp_f32_e32 v87, v87
	v_pk_mul_f32 v[78:79], v[78:79], v[70:71]
	v_cvt_f32_i32_e32 v67, v67
	v_exp_f32_e32 v78, v78
	v_exp_f32_e32 v79, v79
	v_cvt_f32_i32_e32 v66, v66
	v_cvt_f32_i32_e32 v73, v73
	v_cvt_f32_i32_e32 v72, v72
	v_pk_mul_f32 v[74:75], v[74:75], v[86:87]
	v_pk_mul_f32 v[66:67], v[70:71], v[66:67]
	v_cvt_pk_bf16_f32 v74, v74, v75
	v_cvt_pk_bf16_f32 v75, v76, v77
	v_pk_add_f32 v[76:77], v[78:79], 1.0 op_sel_hi:[1,0]
	v_pk_mul_f32 v[70:71], v[150:151], v[88:89] op_sel_hi:[1,0]
	v_rcp_f32_e32 v76, v76
	v_rcp_f32_e32 v77, v77
	v_pk_mul_f32 v[66:67], v[66:67], v[70:71]
	v_pk_mul_f32 v[70:71], v[148:149], v[82:83] op_sel_hi:[1,0]
	v_mad_i64_i32 v[84:85], s[30:31], v83, s51, v[162:163]
	v_pk_mul_f32 v[70:71], v[70:71], v[72:73]
	v_pk_mul_f32 v[66:67], v[66:67], v[76:77]
	v_exp_f32_e32 v70, v70
	v_exp_f32_e32 v71, v71
	v_cvt_pk_bf16_f32 v76, v66, v67
	v_cvt_f32_i32_e32 v67, v69
	v_cvt_f32_i32_e32 v66, v68
	v_pk_add_f32 v[68:69], v[70:71], 1.0 op_sel_hi:[1,0]
	v_pk_mul_f32 v[70:71], v[146:147], v[88:89] op_sel_hi:[1,0]
	v_rcp_f32_e32 v68, v68
	v_rcp_f32_e32 v69, v69
	v_pk_mul_f32 v[66:67], v[72:73], v[66:67]
	v_cvt_f32_i32_e32 v63, v63
	v_pk_mul_f32 v[66:67], v[66:67], v[70:71]
	v_cvt_f32_i32_e32 v62, v62
	v_pk_mul_f32 v[66:67], v[66:67], v[68:69]
	v_cvt_f32_i32_e32 v59, v59
	v_cvt_pk_bf16_f32 v77, v66, v67
	v_lshl_add_u64 v[66:67], v[84:85], 0, v[114:115]
	global_store_dwordx4 v[66:67], v[74:77], off sc0 sc1
	ds_read_b32 v66, v182 offset:512
	v_cvt_f32_i32_e32 v58, v58
	v_add_u32_e32 v67, s21, v173
	v_cvt_f32_i32_e32 v65, v65
	v_cvt_f32_i32_e32 v64, v64
	s_waitcnt lgkmcnt(0)
	v_pk_mul_f32 v[70:71], v[160:161], v[66:67] op_sel_hi:[1,0]
	v_mul_f32_e32 v72, v66, v66
	v_pk_mul_f32 v[70:71], v[70:71], v[62:63]
	v_pk_mul_f32 v[58:59], v[62:63], v[58:59]
	v_pk_mul_f32 v[62:63], v[158:159], v[72:73] op_sel_hi:[1,0]
	v_cvt_f32_i32_e32 v61, v61
	v_pk_mul_f32 v[58:59], v[58:59], v[62:63]
	v_pk_mul_f32 v[62:63], v[156:157], v[66:67] op_sel_hi:[1,0]
	v_cvt_f32_i32_e32 v60, v60
	v_pk_mul_f32 v[62:63], v[62:63], v[64:65]
	v_exp_f32_e32 v70, v70
	v_exp_f32_e32 v62, v62
	v_exp_f32_e32 v63, v63
	v_exp_f32_e32 v71, v71
	v_cvt_f32_i32_e32 v55, v55
	v_cvt_f32_i32_e32 v54, v54
	v_pk_add_f32 v[62:63], v[62:63], 1.0 op_sel_hi:[1,0]
	v_pk_mul_f32 v[60:61], v[64:65], v[60:61]
	v_rcp_f32_e32 v62, v62
	v_rcp_f32_e32 v63, v63
	v_pk_mul_f32 v[64:65], v[154:155], v[72:73] op_sel_hi:[1,0]
	v_pk_add_f32 v[70:71], v[70:71], 1.0 op_sel_hi:[1,0]
	v_pk_mul_f32 v[60:61], v[60:61], v[64:65]
	v_rcp_f32_e32 v70, v70
	v_pk_mul_f32 v[60:61], v[60:61], v[62:63]
	v_pk_mul_f32 v[62:63], v[152:153], v[66:67] op_sel_hi:[1,0]
	v_rcp_f32_e32 v71, v71
	v_pk_mul_f32 v[62:63], v[62:63], v[54:55]
	v_cvt_f32_i32_e32 v51, v51
	v_exp_f32_e32 v62, v62
	v_exp_f32_e32 v63, v63
	v_cvt_f32_i32_e32 v50, v50
	v_cvt_f32_i32_e32 v57, v57
	v_cvt_f32_i32_e32 v56, v56
	v_pk_mul_f32 v[58:59], v[58:59], v[70:71]
	v_pk_mul_f32 v[50:51], v[54:55], v[50:51]
	v_cvt_pk_bf16_f32 v58, v58, v59
	v_cvt_pk_bf16_f32 v59, v60, v61
	v_pk_add_f32 v[60:61], v[62:63], 1.0 op_sel_hi:[1,0]
	v_pk_mul_f32 v[54:55], v[150:151], v[72:73] op_sel_hi:[1,0]
	v_rcp_f32_e32 v60, v60
	v_rcp_f32_e32 v61, v61
	v_pk_mul_f32 v[50:51], v[50:51], v[54:55]
	v_pk_mul_f32 v[54:55], v[148:149], v[66:67] op_sel_hi:[1,0]
	v_mad_i64_i32 v[68:69], s[30:31], v67, s51, v[162:163]
	v_pk_mul_f32 v[54:55], v[54:55], v[56:57]
	v_pk_mul_f32 v[50:51], v[50:51], v[60:61]
	v_exp_f32_e32 v54, v54
	v_exp_f32_e32 v55, v55
	v_cvt_pk_bf16_f32 v60, v50, v51
	v_cvt_f32_i32_e32 v51, v53
	v_cvt_f32_i32_e32 v50, v52
	v_pk_add_f32 v[52:53], v[54:55], 1.0 op_sel_hi:[1,0]
	v_pk_mul_f32 v[54:55], v[146:147], v[72:73] op_sel_hi:[1,0]
	v_rcp_f32_e32 v52, v52
	v_rcp_f32_e32 v53, v53
	v_pk_mul_f32 v[50:51], v[56:57], v[50:51]
	v_cvt_f32_i32_e32 v47, v47
	v_pk_mul_f32 v[50:51], v[50:51], v[54:55]
	v_cvt_f32_i32_e32 v46, v46
	v_pk_mul_f32 v[50:51], v[50:51], v[52:53]
	v_cvt_f32_i32_e32 v43, v43
	v_cvt_pk_bf16_f32 v61, v50, v51
	v_lshl_add_u64 v[50:51], v[68:69], 0, v[114:115]
	global_store_dwordx4 v[50:51], v[58:61], off sc0 sc1
	ds_read_b32 v50, v182 offset:576
	v_cvt_f32_i32_e32 v42, v42
	v_add_u32_e32 v51, s21, v174
	v_cvt_f32_i32_e32 v49, v49
	v_cvt_f32_i32_e32 v48, v48
	s_waitcnt lgkmcnt(0)
	v_pk_mul_f32 v[54:55], v[160:161], v[50:51] op_sel_hi:[1,0]
	v_mul_f32_e32 v56, v50, v50
	v_pk_mul_f32 v[54:55], v[54:55], v[46:47]
	v_pk_mul_f32 v[42:43], v[46:47], v[42:43]
	v_pk_mul_f32 v[46:47], v[158:159], v[56:57] op_sel_hi:[1,0]
	v_cvt_f32_i32_e32 v45, v45
	v_pk_mul_f32 v[42:43], v[42:43], v[46:47]
	v_pk_mul_f32 v[46:47], v[156:157], v[50:51] op_sel_hi:[1,0]
	v_cvt_f32_i32_e32 v44, v44
	v_pk_mul_f32 v[46:47], v[46:47], v[48:49]
	v_exp_f32_e32 v54, v54
	v_exp_f32_e32 v46, v46
	v_exp_f32_e32 v47, v47
	v_exp_f32_e32 v55, v55
	v_cvt_f32_i32_e32 v39, v39
	v_cvt_f32_i32_e32 v38, v38
	v_pk_add_f32 v[46:47], v[46:47], 1.0 op_sel_hi:[1,0]
	v_pk_mul_f32 v[44:45], v[48:49], v[44:45]
	v_rcp_f32_e32 v46, v46
	v_rcp_f32_e32 v47, v47
	v_pk_mul_f32 v[48:49], v[154:155], v[56:57] op_sel_hi:[1,0]
	v_pk_add_f32 v[54:55], v[54:55], 1.0 op_sel_hi:[1,0]
	v_pk_mul_f32 v[44:45], v[44:45], v[48:49]
	v_rcp_f32_e32 v54, v54
	v_pk_mul_f32 v[44:45], v[44:45], v[46:47]
	v_pk_mul_f32 v[46:47], v[152:153], v[50:51] op_sel_hi:[1,0]
	v_rcp_f32_e32 v55, v55
	v_pk_mul_f32 v[46:47], v[46:47], v[38:39]
	v_cvt_f32_i32_e32 v35, v35
	v_exp_f32_e32 v46, v46
	v_exp_f32_e32 v47, v47
	v_cvt_f32_i32_e32 v34, v34
	v_cvt_f32_i32_e32 v41, v41
	v_cvt_f32_i32_e32 v40, v40
	v_pk_mul_f32 v[42:43], v[42:43], v[54:55]
	v_pk_mul_f32 v[34:35], v[38:39], v[34:35]
	v_cvt_pk_bf16_f32 v42, v42, v43
	v_cvt_pk_bf16_f32 v43, v44, v45
	v_pk_add_f32 v[44:45], v[46:47], 1.0 op_sel_hi:[1,0]
	v_pk_mul_f32 v[38:39], v[150:151], v[56:57] op_sel_hi:[1,0]
	v_rcp_f32_e32 v44, v44
	v_rcp_f32_e32 v45, v45
	v_pk_mul_f32 v[34:35], v[34:35], v[38:39]
	v_pk_mul_f32 v[38:39], v[148:149], v[50:51] op_sel_hi:[1,0]
	v_mad_i64_i32 v[52:53], s[30:31], v51, s51, v[162:163]
	v_pk_mul_f32 v[38:39], v[38:39], v[40:41]
	v_pk_mul_f32 v[34:35], v[34:35], v[44:45]
	v_exp_f32_e32 v38, v38
	v_exp_f32_e32 v39, v39
	v_cvt_pk_bf16_f32 v44, v34, v35
	v_cvt_f32_i32_e32 v35, v37
	v_cvt_f32_i32_e32 v34, v36
	v_pk_add_f32 v[36:37], v[38:39], 1.0 op_sel_hi:[1,0]
	v_pk_mul_f32 v[38:39], v[146:147], v[56:57] op_sel_hi:[1,0]
	v_rcp_f32_e32 v36, v36
	v_rcp_f32_e32 v37, v37
	v_pk_mul_f32 v[34:35], v[40:41], v[34:35]
	v_cvt_f32_i32_e32 v31, v31
	v_pk_mul_f32 v[34:35], v[34:35], v[38:39]
	v_cvt_f32_i32_e32 v30, v30
	v_pk_mul_f32 v[34:35], v[34:35], v[36:37]
	v_cvt_f32_i32_e32 v27, v27
	v_cvt_pk_bf16_f32 v45, v34, v35
	v_lshl_add_u64 v[34:35], v[52:53], 0, v[114:115]
	global_store_dwordx4 v[34:35], v[42:45], off sc0 sc1
	ds_read_b32 v34, v182 offset:640
	v_cvt_f32_i32_e32 v26, v26
	v_add_u32_e32 v35, s21, v175
	v_cvt_f32_i32_e32 v33, v33
	v_cvt_f32_i32_e32 v32, v32
	s_waitcnt lgkmcnt(0)
	v_pk_mul_f32 v[38:39], v[160:161], v[34:35] op_sel_hi:[1,0]
	v_mul_f32_e32 v40, v34, v34
	v_pk_mul_f32 v[38:39], v[38:39], v[30:31]
	v_pk_mul_f32 v[26:27], v[30:31], v[26:27]
	v_pk_mul_f32 v[30:31], v[158:159], v[40:41] op_sel_hi:[1,0]
	v_cvt_f32_i32_e32 v29, v29
	v_pk_mul_f32 v[26:27], v[26:27], v[30:31]
	v_pk_mul_f32 v[30:31], v[156:157], v[34:35] op_sel_hi:[1,0]
	v_cvt_f32_i32_e32 v28, v28
	v_pk_mul_f32 v[30:31], v[30:31], v[32:33]
	v_exp_f32_e32 v38, v38
	v_exp_f32_e32 v30, v30
	v_exp_f32_e32 v31, v31
	v_exp_f32_e32 v39, v39
	v_cvt_f32_i32_e32 v23, v23
	v_cvt_f32_i32_e32 v22, v22
	v_pk_add_f32 v[30:31], v[30:31], 1.0 op_sel_hi:[1,0]
	v_pk_mul_f32 v[28:29], v[32:33], v[28:29]
	v_rcp_f32_e32 v30, v30
	v_rcp_f32_e32 v31, v31
	v_pk_mul_f32 v[32:33], v[154:155], v[40:41] op_sel_hi:[1,0]
	v_pk_add_f32 v[38:39], v[38:39], 1.0 op_sel_hi:[1,0]
	v_pk_mul_f32 v[28:29], v[28:29], v[32:33]
	v_rcp_f32_e32 v38, v38
	v_pk_mul_f32 v[28:29], v[28:29], v[30:31]
	v_pk_mul_f32 v[30:31], v[152:153], v[34:35] op_sel_hi:[1,0]
	v_rcp_f32_e32 v39, v39
	v_pk_mul_f32 v[30:31], v[30:31], v[22:23]
	v_cvt_f32_i32_e32 v19, v19
	v_exp_f32_e32 v30, v30
	v_exp_f32_e32 v31, v31
	v_cvt_f32_i32_e32 v18, v18
	v_cvt_f32_i32_e32 v25, v25
	v_cvt_f32_i32_e32 v24, v24
	v_pk_mul_f32 v[26:27], v[26:27], v[38:39]
	v_pk_mul_f32 v[18:19], v[22:23], v[18:19]
	v_cvt_pk_bf16_f32 v26, v26, v27
	v_cvt_pk_bf16_f32 v27, v28, v29
	v_pk_add_f32 v[28:29], v[30:31], 1.0 op_sel_hi:[1,0]
	v_pk_mul_f32 v[22:23], v[150:151], v[40:41] op_sel_hi:[1,0]
	v_rcp_f32_e32 v28, v28
	v_rcp_f32_e32 v29, v29
	v_pk_mul_f32 v[18:19], v[18:19], v[22:23]
	v_pk_mul_f32 v[22:23], v[148:149], v[34:35] op_sel_hi:[1,0]
	v_mad_i64_i32 v[36:37], s[30:31], v35, s51, v[162:163]
	v_pk_mul_f32 v[22:23], v[22:23], v[24:25]
	v_pk_mul_f32 v[18:19], v[18:19], v[28:29]
	v_exp_f32_e32 v22, v22
	v_exp_f32_e32 v23, v23
	v_cvt_pk_bf16_f32 v28, v18, v19
	v_cvt_f32_i32_e32 v19, v21
	v_cvt_f32_i32_e32 v18, v20
	v_pk_add_f32 v[20:21], v[22:23], 1.0 op_sel_hi:[1,0]
	v_pk_mul_f32 v[22:23], v[146:147], v[40:41] op_sel_hi:[1,0]
	v_rcp_f32_e32 v20, v20
	v_rcp_f32_e32 v21, v21
	v_pk_mul_f32 v[18:19], v[24:25], v[18:19]
	v_cvt_f32_i32_e32 v15, v15
	v_pk_mul_f32 v[18:19], v[18:19], v[22:23]
	v_cvt_f32_i32_e32 v14, v14
	v_pk_mul_f32 v[18:19], v[18:19], v[20:21]
	v_cvt_f32_i32_e32 v11, v11
	v_cvt_pk_bf16_f32 v29, v18, v19
	v_lshl_add_u64 v[18:19], v[36:37], 0, v[114:115]
	global_store_dwordx4 v[18:19], v[26:29], off sc0 sc1
	ds_read_b32 v18, v182 offset:704
	v_cvt_f32_i32_e32 v10, v10
	v_add_u32_e32 v19, s21, v176
	v_cvt_f32_i32_e32 v17, v17
	v_cvt_f32_i32_e32 v16, v16
	s_waitcnt lgkmcnt(0)
	v_pk_mul_f32 v[22:23], v[160:161], v[18:19] op_sel_hi:[1,0]
	v_mul_f32_e32 v24, v18, v18
	v_pk_mul_f32 v[22:23], v[22:23], v[14:15]
	v_pk_mul_f32 v[10:11], v[14:15], v[10:11]
	v_pk_mul_f32 v[14:15], v[158:159], v[24:25] op_sel_hi:[1,0]
	v_cvt_f32_i32_e32 v13, v13
	v_pk_mul_f32 v[10:11], v[10:11], v[14:15]
	v_pk_mul_f32 v[14:15], v[156:157], v[18:19] op_sel_hi:[1,0]
	v_cvt_f32_i32_e32 v12, v12
	v_pk_mul_f32 v[14:15], v[14:15], v[16:17]
	v_exp_f32_e32 v22, v22
	v_exp_f32_e32 v14, v14
	v_exp_f32_e32 v15, v15
	v_exp_f32_e32 v23, v23
	v_cvt_f32_i32_e32 v7, v7
	v_cvt_f32_i32_e32 v6, v6
	v_pk_add_f32 v[14:15], v[14:15], 1.0 op_sel_hi:[1,0]
	v_pk_mul_f32 v[12:13], v[16:17], v[12:13]
	v_rcp_f32_e32 v14, v14
	v_rcp_f32_e32 v15, v15
	v_pk_mul_f32 v[16:17], v[154:155], v[24:25] op_sel_hi:[1,0]
	v_pk_add_f32 v[22:23], v[22:23], 1.0 op_sel_hi:[1,0]
	v_pk_mul_f32 v[12:13], v[12:13], v[16:17]
	v_rcp_f32_e32 v22, v22
	v_pk_mul_f32 v[12:13], v[12:13], v[14:15]
	v_pk_mul_f32 v[14:15], v[152:153], v[18:19] op_sel_hi:[1,0]
	v_rcp_f32_e32 v23, v23
	v_pk_mul_f32 v[14:15], v[14:15], v[6:7]
	v_cvt_f32_i32_e32 v3, v3
	v_exp_f32_e32 v14, v14
	v_exp_f32_e32 v15, v15
	v_cvt_f32_i32_e32 v2, v2
	v_cvt_f32_i32_e32 v9, v9
	v_cvt_f32_i32_e32 v8, v8
	v_pk_mul_f32 v[10:11], v[10:11], v[22:23]
	v_pk_mul_f32 v[2:3], v[6:7], v[2:3]
	v_cvt_pk_bf16_f32 v10, v10, v11
	v_cvt_pk_bf16_f32 v11, v12, v13
	v_pk_add_f32 v[12:13], v[14:15], 1.0 op_sel_hi:[1,0]
	v_pk_mul_f32 v[6:7], v[150:151], v[24:25] op_sel_hi:[1,0]
	v_rcp_f32_e32 v12, v12
	v_rcp_f32_e32 v13, v13
	v_pk_mul_f32 v[2:3], v[2:3], v[6:7]
	v_pk_mul_f32 v[6:7], v[148:149], v[18:19] op_sel_hi:[1,0]
	v_mad_i64_i32 v[20:21], s[30:31], v19, s51, v[162:163]
	v_pk_mul_f32 v[6:7], v[6:7], v[8:9]
	v_pk_mul_f32 v[2:3], v[2:3], v[12:13]
	v_exp_f32_e32 v6, v6
	v_exp_f32_e32 v7, v7
	v_cvt_pk_bf16_f32 v12, v2, v3
	v_cvt_f32_i32_e32 v3, v5
	v_cvt_f32_i32_e32 v2, v4
	v_pk_add_f32 v[4:5], v[6:7], 1.0 op_sel_hi:[1,0]
	v_pk_mul_f32 v[6:7], v[146:147], v[24:25] op_sel_hi:[1,0]
	v_rcp_f32_e32 v4, v4
	v_rcp_f32_e32 v5, v5
	v_pk_mul_f32 v[2:3], v[8:9], v[2:3]
	s_andn2_b64 vcc, exec, s[4:5]
	v_pk_mul_f32 v[2:3], v[2:3], v[6:7]
	s_mov_b64 s[4:5], -1
	v_pk_mul_f32 v[2:3], v[2:3], v[4:5]
	s_nop 0
	v_cvt_pk_bf16_f32 v13, v2, v3
	v_lshl_add_u64 v[2:3], v[20:21], 0, v[114:115]
	global_store_dwordx4 v[2:3], v[10:13], off sc0 sc1
	s_cbranch_vccnz .LBB0_1591
	s_andn2_b64 vcc, exec, s[12:13]
	s_cbranch_vccnz .LBB0_1590
	s_barrier
	s_branch .LBB0_1590

.LBB0_2473:
	s_lshl_b32 s17, s52, 11
	s_add_i32 s17, s17, 0
	s_add_i32 s21, s17, 0x20180
	s_lshl_b32 s17, s45, 2
	s_add_i32 s17, s21, s17
	v_lshl_add_u32 v154, v164, 2, s17
	ds_read_b128 v[146:149], v154 offset:1024
	ds_read_b128 v[150:153], v154 offset:1536
	ds_read_b128 v[182:185], v154 offset:1040
	ds_read_b128 v[186:189], v154 offset:1552
	v_cvt_f32_i32_e32 v127, v127
	v_cvt_f32_i32_e32 v126, v126
	s_waitcnt lgkmcnt(0)
	v_pk_mul_f32 v[154:155], v[148:149], v[152:153]
	v_pk_mul_f32 v[158:159], v[146:147], v[150:151]
	v_pk_mul_f32 v[152:153], v[182:183], s[14:15] op_sel_hi:[1,0]
	v_pk_mul_f32 v[150:151], v[182:183], v[186:187]
	v_lshl_add_u32 v182, v165, 2, s21
	ds_read_b32 v186, v182
	v_cvt_f32_i32_e32 v123, v123
	v_cvt_f32_i32_e32 v122, v122
	v_pk_mul_f32 v[160:161], v[146:147], s[14:15] op_sel_hi:[1,0]
	v_cvt_f32_i32_e32 v129, v129
	v_cvt_f32_i32_e32 v128, v128
	s_waitcnt lgkmcnt(0)
	v_pk_mul_f32 v[190:191], v[160:161], v[186:187] op_sel_hi:[1,0]
	v_mul_f32_e32 v192, v186, v186
	v_pk_mul_f32 v[156:157], v[148:149], s[14:15] op_sel_hi:[1,0]
	v_pk_mul_f32 v[190:191], v[190:191], v[126:127]
	v_pk_mul_f32 v[122:123], v[126:127], v[122:123]
	v_pk_mul_f32 v[126:127], v[158:159], v[192:193] op_sel_hi:[1,0]
	v_cvt_f32_i32_e32 v125, v125
	v_pk_mul_f32 v[122:123], v[122:123], v[126:127]
	v_pk_mul_f32 v[126:127], v[156:157], v[186:187] op_sel_hi:[1,0]
	v_cvt_f32_i32_e32 v124, v124
	v_pk_mul_f32 v[126:127], v[126:127], v[128:129]
	v_exp_f32_e32 v190, v190
	v_exp_f32_e32 v126, v126
	v_exp_f32_e32 v127, v127
	v_exp_f32_e32 v191, v191
	v_cvt_f32_i32_e32 v119, v119
	v_cvt_f32_i32_e32 v118, v118
	v_pk_add_f32 v[126:127], v[126:127], 1.0 op_sel_hi:[1,0]
	v_pk_mul_f32 v[124:125], v[128:129], v[124:125]
	v_rcp_f32_e32 v126, v126
	v_rcp_f32_e32 v127, v127
	v_pk_mul_f32 v[128:129], v[154:155], v[192:193] op_sel_hi:[1,0]
	v_pk_add_f32 v[190:191], v[190:191], 1.0 op_sel_hi:[1,0]
	v_pk_mul_f32 v[124:125], v[124:125], v[128:129]
	v_rcp_f32_e32 v190, v190
	v_pk_mul_f32 v[124:125], v[124:125], v[126:127]
	v_pk_mul_f32 v[126:127], v[152:153], v[186:187] op_sel_hi:[1,0]
	v_rcp_f32_e32 v191, v191
	v_pk_mul_f32 v[126:127], v[126:127], v[118:119]
	v_cvt_f32_i32_e32 v115, v115
	v_exp_f32_e32 v126, v126
	v_exp_f32_e32 v127, v127
	v_cvt_f32_i32_e32 v114, v114
	v_cvt_f32_i32_e32 v121, v121
	v_cvt_f32_i32_e32 v120, v120
	v_pk_mul_f32 v[122:123], v[122:123], v[190:191]
	v_pk_mul_f32 v[148:149], v[184:185], s[14:15] op_sel_hi:[1,0]
	v_cvt_pk_bf16_f32 v122, v122, v123
	v_cvt_pk_bf16_f32 v123, v124, v125
	v_pk_add_f32 v[124:125], v[126:127], 1.0 op_sel_hi:[1,0]
	v_pk_mul_f32 v[114:115], v[118:119], v[114:115]
	v_pk_mul_f32 v[118:119], v[150:151], v[192:193] op_sel_hi:[1,0]
	v_rcp_f32_e32 v124, v124
	v_rcp_f32_e32 v125, v125
	v_pk_mul_f32 v[114:115], v[114:115], v[118:119]
	v_pk_mul_f32 v[118:119], v[148:149], v[186:187] op_sel_hi:[1,0]
	v_pk_mul_f32 v[146:147], v[184:185], v[188:189]
	v_pk_mul_f32 v[118:119], v[118:119], v[120:121]
	v_pk_mul_f32 v[114:115], v[114:115], v[124:125]
	v_exp_f32_e32 v118, v118
	v_exp_f32_e32 v119, v119
	v_cvt_pk_bf16_f32 v124, v114, v115
	v_cvt_f32_i32_e32 v115, v117
	v_cvt_f32_i32_e32 v114, v116
	v_pk_add_f32 v[116:117], v[118:119], 1.0 op_sel_hi:[1,0]
	v_pk_mul_f32 v[118:119], v[146:147], v[192:193] op_sel_hi:[1,0]
	v_rcp_f32_e32 v116, v116
	v_rcp_f32_e32 v117, v117
	v_pk_mul_f32 v[114:115], v[120:121], v[114:115]
	v_lshl_or_b32 v184, s51, 7, v177
	s_lshl_b32 s17, s26, 8
	v_pk_mul_f32 v[114:115], v[114:115], v[118:119]
	v_ashrrev_i32_e32 v185, 31, v184
	v_add_u32_e32 v183, s17, v165
	v_mov_b64_e32 v[162:163], s[60:61]
	v_pk_mul_f32 v[114:115], v[114:115], v[116:117]
	v_mad_i64_i32 v[188:189], s[28:29], v183, s49, v[162:163]
	v_cvt_pk_bf16_f32 v125, v114, v115
	v_lshlrev_b64 v[114:115], 1, v[184:185]
	v_lshl_add_u64 v[116:117], v[188:189], 0, v[114:115]
	global_store_dwordx4 v[116:117], v[122:125], off sc0 sc1
	ds_read_b32 v116, v182 offset:64
	v_cvt_f32_i32_e32 v111, v111
	v_cvt_f32_i32_e32 v110, v110
	v_cvt_f32_i32_e32 v107, v107
	v_cvt_f32_i32_e32 v106, v106
	v_add_u32_e32 v117, s17, v170
	v_cvt_f32_i32_e32 v113, v113
	v_cvt_f32_i32_e32 v112, v112
	s_waitcnt lgkmcnt(0)
	v_pk_mul_f32 v[120:121], v[160:161], v[116:117] op_sel_hi:[1,0]
	v_mul_f32_e32 v122, v116, v116
	v_pk_mul_f32 v[120:121], v[120:121], v[110:111]
	v_pk_mul_f32 v[106:107], v[110:111], v[106:107]
	v_pk_mul_f32 v[110:111], v[158:159], v[122:123] op_sel_hi:[1,0]
	v_cvt_f32_i32_e32 v109, v109
	v_pk_mul_f32 v[106:107], v[106:107], v[110:111]
	v_pk_mul_f32 v[110:111], v[156:157], v[116:117] op_sel_hi:[1,0]
	v_cvt_f32_i32_e32 v108, v108
	v_pk_mul_f32 v[110:111], v[110:111], v[112:113]
	v_exp_f32_e32 v120, v120
	v_exp_f32_e32 v110, v110
	v_exp_f32_e32 v111, v111
	v_exp_f32_e32 v121, v121
	v_cvt_f32_i32_e32 v103, v103
	v_cvt_f32_i32_e32 v102, v102
	v_pk_add_f32 v[110:111], v[110:111], 1.0 op_sel_hi:[1,0]
	v_pk_mul_f32 v[108:109], v[112:113], v[108:109]
	v_rcp_f32_e32 v110, v110
	v_rcp_f32_e32 v111, v111
	v_pk_mul_f32 v[112:113], v[154:155], v[122:123] op_sel_hi:[1,0]
	v_pk_add_f32 v[120:121], v[120:121], 1.0 op_sel_hi:[1,0]
	v_pk_mul_f32 v[108:109], v[108:109], v[112:113]
	v_rcp_f32_e32 v120, v120
	v_pk_mul_f32 v[108:109], v[108:109], v[110:111]
	v_pk_mul_f32 v[110:111], v[152:153], v[116:117] op_sel_hi:[1,0]
	v_rcp_f32_e32 v121, v121
	v_pk_mul_f32 v[110:111], v[110:111], v[102:103]
	v_cvt_f32_i32_e32 v99, v99
	v_exp_f32_e32 v110, v110
	v_exp_f32_e32 v111, v111
	v_cvt_f32_i32_e32 v98, v98
	v_cvt_f32_i32_e32 v105, v105
	v_cvt_f32_i32_e32 v104, v104
	v_pk_mul_f32 v[106:107], v[106:107], v[120:121]
	v_pk_mul_f32 v[98:99], v[102:103], v[98:99]
	v_cvt_pk_bf16_f32 v106, v106, v107
	v_cvt_pk_bf16_f32 v107, v108, v109
	v_pk_add_f32 v[108:109], v[110:111], 1.0 op_sel_hi:[1,0]
	v_pk_mul_f32 v[102:103], v[150:151], v[122:123] op_sel_hi:[1,0]
	v_rcp_f32_e32 v108, v108
	v_rcp_f32_e32 v109, v109
	v_pk_mul_f32 v[98:99], v[98:99], v[102:103]
	v_pk_mul_f32 v[102:103], v[148:149], v[116:117] op_sel_hi:[1,0]
	v_mad_i64_i32 v[118:119], s[28:29], v117, s49, v[162:163]
	v_pk_mul_f32 v[102:103], v[102:103], v[104:105]
	v_pk_mul_f32 v[98:99], v[98:99], v[108:109]
	v_exp_f32_e32 v102, v102
	v_exp_f32_e32 v103, v103
	v_cvt_pk_bf16_f32 v108, v98, v99
	v_cvt_f32_i32_e32 v99, v101
	v_cvt_f32_i32_e32 v98, v100
	v_pk_add_f32 v[100:101], v[102:103], 1.0 op_sel_hi:[1,0]
	v_pk_mul_f32 v[102:103], v[146:147], v[122:123] op_sel_hi:[1,0]
	v_rcp_f32_e32 v100, v100
	v_rcp_f32_e32 v101, v101
	v_pk_mul_f32 v[98:99], v[104:105], v[98:99]
	v_cvt_f32_i32_e32 v95, v95
	v_pk_mul_f32 v[98:99], v[98:99], v[102:103]
	v_cvt_f32_i32_e32 v94, v94
	v_pk_mul_f32 v[98:99], v[98:99], v[100:101]
	v_cvt_f32_i32_e32 v91, v91
	v_cvt_pk_bf16_f32 v109, v98, v99
	v_lshl_add_u64 v[98:99], v[118:119], 0, v[114:115]
	global_store_dwordx4 v[98:99], v[106:109], off sc0 sc1
	ds_read_b32 v98, v182 offset:128
	v_cvt_f32_i32_e32 v90, v90
	v_add_u32_e32 v99, s17, v171
	v_cvt_f32_i32_e32 v97, v97
	v_cvt_f32_i32_e32 v96, v96
	s_waitcnt lgkmcnt(0)
	v_pk_mul_f32 v[102:103], v[160:161], v[98:99] op_sel_hi:[1,0]
	v_mul_f32_e32 v104, v98, v98
	v_pk_mul_f32 v[102:103], v[102:103], v[94:95]
	v_pk_mul_f32 v[90:91], v[94:95], v[90:91]
	v_pk_mul_f32 v[94:95], v[158:159], v[104:105] op_sel_hi:[1,0]
	v_cvt_f32_i32_e32 v93, v93
	v_pk_mul_f32 v[90:91], v[90:91], v[94:95]
	v_pk_mul_f32 v[94:95], v[156:157], v[98:99] op_sel_hi:[1,0]
	v_cvt_f32_i32_e32 v92, v92
	v_pk_mul_f32 v[94:95], v[94:95], v[96:97]
	v_exp_f32_e32 v102, v102
	v_exp_f32_e32 v94, v94
	v_exp_f32_e32 v95, v95
	v_exp_f32_e32 v103, v103
	v_cvt_f32_i32_e32 v87, v87
	v_cvt_f32_i32_e32 v86, v86
	v_pk_add_f32 v[94:95], v[94:95], 1.0 op_sel_hi:[1,0]
	v_pk_mul_f32 v[92:93], v[96:97], v[92:93]
	v_rcp_f32_e32 v94, v94
	v_rcp_f32_e32 v95, v95
	v_pk_mul_f32 v[96:97], v[154:155], v[104:105] op_sel_hi:[1,0]
	v_pk_add_f32 v[102:103], v[102:103], 1.0 op_sel_hi:[1,0]
	v_pk_mul_f32 v[92:93], v[92:93], v[96:97]
	v_rcp_f32_e32 v102, v102
	v_pk_mul_f32 v[92:93], v[92:93], v[94:95]
	v_pk_mul_f32 v[94:95], v[152:153], v[98:99] op_sel_hi:[1,0]
	v_rcp_f32_e32 v103, v103
	v_pk_mul_f32 v[94:95], v[94:95], v[86:87]
	v_cvt_f32_i32_e32 v83, v83
	v_exp_f32_e32 v94, v94
	v_exp_f32_e32 v95, v95
	v_cvt_f32_i32_e32 v82, v82
	v_cvt_f32_i32_e32 v89, v89
	v_cvt_f32_i32_e32 v88, v88
	v_pk_mul_f32 v[90:91], v[90:91], v[102:103]
	v_pk_mul_f32 v[82:83], v[86:87], v[82:83]
	v_cvt_pk_bf16_f32 v90, v90, v91
	v_cvt_pk_bf16_f32 v91, v92, v93
	v_pk_add_f32 v[92:93], v[94:95], 1.0 op_sel_hi:[1,0]
	v_pk_mul_f32 v[86:87], v[150:151], v[104:105] op_sel_hi:[1,0]
	v_rcp_f32_e32 v92, v92
	v_rcp_f32_e32 v93, v93
	v_pk_mul_f32 v[82:83], v[82:83], v[86:87]
	v_pk_mul_f32 v[86:87], v[148:149], v[98:99] op_sel_hi:[1,0]
	v_mad_i64_i32 v[100:101], s[28:29], v99, s49, v[162:163]
	v_pk_mul_f32 v[86:87], v[86:87], v[88:89]
	v_pk_mul_f32 v[82:83], v[82:83], v[92:93]
	v_exp_f32_e32 v86, v86
	v_exp_f32_e32 v87, v87
	v_cvt_pk_bf16_f32 v92, v82, v83
	v_cvt_f32_i32_e32 v83, v85
	v_cvt_f32_i32_e32 v82, v84
	v_pk_add_f32 v[84:85], v[86:87], 1.0 op_sel_hi:[1,0]
	v_pk_mul_f32 v[86:87], v[146:147], v[104:105] op_sel_hi:[1,0]
	v_rcp_f32_e32 v84, v84
	v_rcp_f32_e32 v85, v85
	v_pk_mul_f32 v[82:83], v[88:89], v[82:83]
	v_cvt_f32_i32_e32 v79, v79
	v_pk_mul_f32 v[82:83], v[82:83], v[86:87]
	v_cvt_f32_i32_e32 v78, v78
	v_pk_mul_f32 v[82:83], v[82:83], v[84:85]
	v_cvt_f32_i32_e32 v75, v75
	v_cvt_pk_bf16_f32 v93, v82, v83
	v_lshl_add_u64 v[82:83], v[100:101], 0, v[114:115]
	global_store_dwordx4 v[82:83], v[90:93], off sc0 sc1
	ds_read_b32 v82, v182 offset:192
	v_cvt_f32_i32_e32 v74, v74
	v_add_u32_e32 v83, s17, v172
	v_cvt_f32_i32_e32 v81, v81
	v_cvt_f32_i32_e32 v80, v80
	s_waitcnt lgkmcnt(0)
	v_pk_mul_f32 v[86:87], v[160:161], v[82:83] op_sel_hi:[1,0]
	v_mul_f32_e32 v88, v82, v82
	v_pk_mul_f32 v[86:87], v[86:87], v[78:79]
	v_pk_mul_f32 v[74:75], v[78:79], v[74:75]
	v_pk_mul_f32 v[78:79], v[158:159], v[88:89] op_sel_hi:[1,0]
	v_cvt_f32_i32_e32 v77, v77
	v_pk_mul_f32 v[74:75], v[74:75], v[78:79]
	v_pk_mul_f32 v[78:79], v[156:157], v[82:83] op_sel_hi:[1,0]
	v_cvt_f32_i32_e32 v76, v76
	v_pk_mul_f32 v[78:79], v[78:79], v[80:81]
	v_exp_f32_e32 v86, v86
	v_exp_f32_e32 v78, v78
	v_exp_f32_e32 v79, v79
	v_exp_f32_e32 v87, v87
	v_cvt_f32_i32_e32 v71, v71
	v_cvt_f32_i32_e32 v70, v70
	v_pk_add_f32 v[78:79], v[78:79], 1.0 op_sel_hi:[1,0]
	v_pk_mul_f32 v[76:77], v[80:81], v[76:77]
	v_rcp_f32_e32 v78, v78
	v_rcp_f32_e32 v79, v79
	v_pk_mul_f32 v[80:81], v[154:155], v[88:89] op_sel_hi:[1,0]
	v_pk_add_f32 v[86:87], v[86:87], 1.0 op_sel_hi:[1,0]
	v_pk_mul_f32 v[76:77], v[76:77], v[80:81]
	v_rcp_f32_e32 v86, v86
	v_pk_mul_f32 v[76:77], v[76:77], v[78:79]
	v_pk_mul_f32 v[78:79], v[152:153], v[82:83] op_sel_hi:[1,0]
	v_rcp_f32_e32 v87, v87
	v_pk_mul_f32 v[78:79], v[78:79], v[70:71]
	v_cvt_f32_i32_e32 v67, v67
	v_exp_f32_e32 v78, v78
	v_exp_f32_e32 v79, v79
	v_cvt_f32_i32_e32 v66, v66
	v_cvt_f32_i32_e32 v73, v73
	v_cvt_f32_i32_e32 v72, v72
	v_pk_mul_f32 v[74:75], v[74:75], v[86:87]
	v_pk_mul_f32 v[66:67], v[70:71], v[66:67]
	v_cvt_pk_bf16_f32 v74, v74, v75
	v_cvt_pk_bf16_f32 v75, v76, v77
	v_pk_add_f32 v[76:77], v[78:79], 1.0 op_sel_hi:[1,0]
	v_pk_mul_f32 v[70:71], v[150:151], v[88:89] op_sel_hi:[1,0]
	v_rcp_f32_e32 v76, v76
	v_rcp_f32_e32 v77, v77
	v_pk_mul_f32 v[66:67], v[66:67], v[70:71]
	v_pk_mul_f32 v[70:71], v[148:149], v[82:83] op_sel_hi:[1,0]
	v_mad_i64_i32 v[84:85], s[28:29], v83, s49, v[162:163]
	v_pk_mul_f32 v[70:71], v[70:71], v[72:73]
	v_pk_mul_f32 v[66:67], v[66:67], v[76:77]
	v_exp_f32_e32 v70, v70
	v_exp_f32_e32 v71, v71
	v_cvt_pk_bf16_f32 v76, v66, v67
	v_cvt_f32_i32_e32 v67, v69
	v_cvt_f32_i32_e32 v66, v68
	v_pk_add_f32 v[68:69], v[70:71], 1.0 op_sel_hi:[1,0]
	v_pk_mul_f32 v[70:71], v[146:147], v[88:89] op_sel_hi:[1,0]
	v_rcp_f32_e32 v68, v68
	v_rcp_f32_e32 v69, v69
	v_pk_mul_f32 v[66:67], v[72:73], v[66:67]
	v_cvt_f32_i32_e32 v63, v63
	v_pk_mul_f32 v[66:67], v[66:67], v[70:71]
	v_cvt_f32_i32_e32 v62, v62
	v_pk_mul_f32 v[66:67], v[66:67], v[68:69]
	v_cvt_f32_i32_e32 v59, v59
	v_cvt_pk_bf16_f32 v77, v66, v67
	v_lshl_add_u64 v[66:67], v[84:85], 0, v[114:115]
	global_store_dwordx4 v[66:67], v[74:77], off sc0 sc1
	ds_read_b32 v66, v182 offset:512
	v_cvt_f32_i32_e32 v58, v58
	v_add_u32_e32 v67, s17, v173
	v_cvt_f32_i32_e32 v65, v65
	v_cvt_f32_i32_e32 v64, v64
	s_waitcnt lgkmcnt(0)
	v_pk_mul_f32 v[70:71], v[160:161], v[66:67] op_sel_hi:[1,0]
	v_mul_f32_e32 v72, v66, v66
	v_pk_mul_f32 v[70:71], v[70:71], v[62:63]
	v_pk_mul_f32 v[58:59], v[62:63], v[58:59]
	v_pk_mul_f32 v[62:63], v[158:159], v[72:73] op_sel_hi:[1,0]
	v_cvt_f32_i32_e32 v61, v61
	v_pk_mul_f32 v[58:59], v[58:59], v[62:63]
	v_pk_mul_f32 v[62:63], v[156:157], v[66:67] op_sel_hi:[1,0]
	v_cvt_f32_i32_e32 v60, v60
	v_pk_mul_f32 v[62:63], v[62:63], v[64:65]
	v_exp_f32_e32 v70, v70
	v_exp_f32_e32 v62, v62
	v_exp_f32_e32 v63, v63
	v_exp_f32_e32 v71, v71
	v_cvt_f32_i32_e32 v55, v55
	v_cvt_f32_i32_e32 v54, v54
	v_pk_add_f32 v[62:63], v[62:63], 1.0 op_sel_hi:[1,0]
	v_pk_mul_f32 v[60:61], v[64:65], v[60:61]
	v_rcp_f32_e32 v62, v62
	v_rcp_f32_e32 v63, v63
	v_pk_mul_f32 v[64:65], v[154:155], v[72:73] op_sel_hi:[1,0]
	v_pk_add_f32 v[70:71], v[70:71], 1.0 op_sel_hi:[1,0]
	v_pk_mul_f32 v[60:61], v[60:61], v[64:65]
	v_rcp_f32_e32 v70, v70
	v_pk_mul_f32 v[60:61], v[60:61], v[62:63]
	v_pk_mul_f32 v[62:63], v[152:153], v[66:67] op_sel_hi:[1,0]
	v_rcp_f32_e32 v71, v71
	v_pk_mul_f32 v[62:63], v[62:63], v[54:55]
	v_cvt_f32_i32_e32 v51, v51
	v_exp_f32_e32 v62, v62
	v_exp_f32_e32 v63, v63
	v_cvt_f32_i32_e32 v50, v50
	v_cvt_f32_i32_e32 v57, v57
	v_cvt_f32_i32_e32 v56, v56
	v_pk_mul_f32 v[58:59], v[58:59], v[70:71]
	v_pk_mul_f32 v[50:51], v[54:55], v[50:51]
	v_cvt_pk_bf16_f32 v58, v58, v59
	v_cvt_pk_bf16_f32 v59, v60, v61
	v_pk_add_f32 v[60:61], v[62:63], 1.0 op_sel_hi:[1,0]
	v_pk_mul_f32 v[54:55], v[150:151], v[72:73] op_sel_hi:[1,0]
	v_rcp_f32_e32 v60, v60
	v_rcp_f32_e32 v61, v61
	v_pk_mul_f32 v[50:51], v[50:51], v[54:55]
	v_pk_mul_f32 v[54:55], v[148:149], v[66:67] op_sel_hi:[1,0]
	v_mad_i64_i32 v[68:69], s[28:29], v67, s49, v[162:163]
	v_pk_mul_f32 v[54:55], v[54:55], v[56:57]
	v_pk_mul_f32 v[50:51], v[50:51], v[60:61]
	v_exp_f32_e32 v54, v54
	v_exp_f32_e32 v55, v55
	v_cvt_pk_bf16_f32 v60, v50, v51
	v_cvt_f32_i32_e32 v51, v53
	v_cvt_f32_i32_e32 v50, v52
	v_pk_add_f32 v[52:53], v[54:55], 1.0 op_sel_hi:[1,0]
	v_pk_mul_f32 v[54:55], v[146:147], v[72:73] op_sel_hi:[1,0]
	v_rcp_f32_e32 v52, v52
	v_rcp_f32_e32 v53, v53
	v_pk_mul_f32 v[50:51], v[56:57], v[50:51]
	v_cvt_f32_i32_e32 v47, v47
	v_pk_mul_f32 v[50:51], v[50:51], v[54:55]
	v_cvt_f32_i32_e32 v46, v46
	v_pk_mul_f32 v[50:51], v[50:51], v[52:53]
	v_cvt_f32_i32_e32 v43, v43
	v_cvt_pk_bf16_f32 v61, v50, v51
	v_lshl_add_u64 v[50:51], v[68:69], 0, v[114:115]
	global_store_dwordx4 v[50:51], v[58:61], off sc0 sc1
	ds_read_b32 v50, v182 offset:576
	v_cvt_f32_i32_e32 v42, v42
	v_add_u32_e32 v51, s17, v174
	v_cvt_f32_i32_e32 v49, v49
	v_cvt_f32_i32_e32 v48, v48
	s_waitcnt lgkmcnt(0)
	v_pk_mul_f32 v[54:55], v[160:161], v[50:51] op_sel_hi:[1,0]
	v_mul_f32_e32 v56, v50, v50
	v_pk_mul_f32 v[54:55], v[54:55], v[46:47]
	v_pk_mul_f32 v[42:43], v[46:47], v[42:43]
	v_pk_mul_f32 v[46:47], v[158:159], v[56:57] op_sel_hi:[1,0]
	v_cvt_f32_i32_e32 v45, v45
	v_pk_mul_f32 v[42:43], v[42:43], v[46:47]
	v_pk_mul_f32 v[46:47], v[156:157], v[50:51] op_sel_hi:[1,0]
	v_cvt_f32_i32_e32 v44, v44
	v_pk_mul_f32 v[46:47], v[46:47], v[48:49]
	v_exp_f32_e32 v54, v54
	v_exp_f32_e32 v46, v46
	v_exp_f32_e32 v47, v47
	v_exp_f32_e32 v55, v55
	v_cvt_f32_i32_e32 v39, v39
	v_cvt_f32_i32_e32 v38, v38
	v_pk_add_f32 v[46:47], v[46:47], 1.0 op_sel_hi:[1,0]
	v_pk_mul_f32 v[44:45], v[48:49], v[44:45]
	v_rcp_f32_e32 v46, v46
	v_rcp_f32_e32 v47, v47
	v_pk_mul_f32 v[48:49], v[154:155], v[56:57] op_sel_hi:[1,0]
	v_pk_add_f32 v[54:55], v[54:55], 1.0 op_sel_hi:[1,0]
	v_pk_mul_f32 v[44:45], v[44:45], v[48:49]
	v_rcp_f32_e32 v54, v54
	v_pk_mul_f32 v[44:45], v[44:45], v[46:47]
	v_pk_mul_f32 v[46:47], v[152:153], v[50:51] op_sel_hi:[1,0]
	v_rcp_f32_e32 v55, v55
	v_pk_mul_f32 v[46:47], v[46:47], v[38:39]
	v_cvt_f32_i32_e32 v35, v35
	v_exp_f32_e32 v46, v46
	v_exp_f32_e32 v47, v47
	v_cvt_f32_i32_e32 v34, v34
	v_cvt_f32_i32_e32 v41, v41
	v_cvt_f32_i32_e32 v40, v40
	v_pk_mul_f32 v[42:43], v[42:43], v[54:55]
	v_pk_mul_f32 v[34:35], v[38:39], v[34:35]
	v_cvt_pk_bf16_f32 v42, v42, v43
	v_cvt_pk_bf16_f32 v43, v44, v45
	v_pk_add_f32 v[44:45], v[46:47], 1.0 op_sel_hi:[1,0]
	v_pk_mul_f32 v[38:39], v[150:151], v[56:57] op_sel_hi:[1,0]
	v_rcp_f32_e32 v44, v44
	v_rcp_f32_e32 v45, v45
	v_pk_mul_f32 v[34:35], v[34:35], v[38:39]
	v_pk_mul_f32 v[38:39], v[148:149], v[50:51] op_sel_hi:[1,0]
	v_mad_i64_i32 v[52:53], s[28:29], v51, s49, v[162:163]
	v_pk_mul_f32 v[38:39], v[38:39], v[40:41]
	v_pk_mul_f32 v[34:35], v[34:35], v[44:45]
	v_exp_f32_e32 v38, v38
	v_exp_f32_e32 v39, v39
	v_cvt_pk_bf16_f32 v44, v34, v35
	v_cvt_f32_i32_e32 v35, v37
	v_cvt_f32_i32_e32 v34, v36
	v_pk_add_f32 v[36:37], v[38:39], 1.0 op_sel_hi:[1,0]
	v_pk_mul_f32 v[38:39], v[146:147], v[56:57] op_sel_hi:[1,0]
	v_rcp_f32_e32 v36, v36
	v_rcp_f32_e32 v37, v37
	v_pk_mul_f32 v[34:35], v[40:41], v[34:35]
	v_cvt_f32_i32_e32 v31, v31
	v_pk_mul_f32 v[34:35], v[34:35], v[38:39]
	v_cvt_f32_i32_e32 v30, v30
	v_pk_mul_f32 v[34:35], v[34:35], v[36:37]
	v_cvt_f32_i32_e32 v27, v27
	v_cvt_pk_bf16_f32 v45, v34, v35
	v_lshl_add_u64 v[34:35], v[52:53], 0, v[114:115]
	global_store_dwordx4 v[34:35], v[42:45], off sc0 sc1
	ds_read_b32 v34, v182 offset:640
	v_cvt_f32_i32_e32 v26, v26
	v_add_u32_e32 v35, s17, v175
	v_cvt_f32_i32_e32 v33, v33
	v_cvt_f32_i32_e32 v32, v32
	s_waitcnt lgkmcnt(0)
	v_pk_mul_f32 v[38:39], v[160:161], v[34:35] op_sel_hi:[1,0]
	v_mul_f32_e32 v40, v34, v34
	v_pk_mul_f32 v[38:39], v[38:39], v[30:31]
	v_pk_mul_f32 v[26:27], v[30:31], v[26:27]
	v_pk_mul_f32 v[30:31], v[158:159], v[40:41] op_sel_hi:[1,0]
	v_cvt_f32_i32_e32 v29, v29
	v_pk_mul_f32 v[26:27], v[26:27], v[30:31]
	v_pk_mul_f32 v[30:31], v[156:157], v[34:35] op_sel_hi:[1,0]
	v_cvt_f32_i32_e32 v28, v28
	v_pk_mul_f32 v[30:31], v[30:31], v[32:33]
	v_exp_f32_e32 v38, v38
	v_exp_f32_e32 v30, v30
	v_exp_f32_e32 v31, v31
	v_exp_f32_e32 v39, v39
	v_cvt_f32_i32_e32 v23, v23
	v_cvt_f32_i32_e32 v22, v22
	v_pk_add_f32 v[30:31], v[30:31], 1.0 op_sel_hi:[1,0]
	v_pk_mul_f32 v[28:29], v[32:33], v[28:29]
	v_rcp_f32_e32 v30, v30
	v_rcp_f32_e32 v31, v31
	v_pk_mul_f32 v[32:33], v[154:155], v[40:41] op_sel_hi:[1,0]
	v_pk_add_f32 v[38:39], v[38:39], 1.0 op_sel_hi:[1,0]
	v_pk_mul_f32 v[28:29], v[28:29], v[32:33]
	v_rcp_f32_e32 v38, v38
	v_pk_mul_f32 v[28:29], v[28:29], v[30:31]
	v_pk_mul_f32 v[30:31], v[152:153], v[34:35] op_sel_hi:[1,0]
	v_rcp_f32_e32 v39, v39
	v_pk_mul_f32 v[30:31], v[30:31], v[22:23]
	v_cvt_f32_i32_e32 v19, v19
	v_exp_f32_e32 v30, v30
	v_exp_f32_e32 v31, v31
	v_cvt_f32_i32_e32 v18, v18
	v_cvt_f32_i32_e32 v25, v25
	v_cvt_f32_i32_e32 v24, v24
	v_pk_mul_f32 v[26:27], v[26:27], v[38:39]
	v_pk_mul_f32 v[18:19], v[22:23], v[18:19]
	v_cvt_pk_bf16_f32 v26, v26, v27
	v_cvt_pk_bf16_f32 v27, v28, v29
	v_pk_add_f32 v[28:29], v[30:31], 1.0 op_sel_hi:[1,0]
	v_pk_mul_f32 v[22:23], v[150:151], v[40:41] op_sel_hi:[1,0]
	v_rcp_f32_e32 v28, v28
	v_rcp_f32_e32 v29, v29
	v_pk_mul_f32 v[18:19], v[18:19], v[22:23]
	v_pk_mul_f32 v[22:23], v[148:149], v[34:35] op_sel_hi:[1,0]
	v_mad_i64_i32 v[36:37], s[28:29], v35, s49, v[162:163]
	v_pk_mul_f32 v[22:23], v[22:23], v[24:25]
	v_pk_mul_f32 v[18:19], v[18:19], v[28:29]
	v_exp_f32_e32 v22, v22
	v_exp_f32_e32 v23, v23
	v_cvt_pk_bf16_f32 v28, v18, v19
	v_cvt_f32_i32_e32 v19, v21
	v_cvt_f32_i32_e32 v18, v20
	v_pk_add_f32 v[20:21], v[22:23], 1.0 op_sel_hi:[1,0]
	v_pk_mul_f32 v[22:23], v[146:147], v[40:41] op_sel_hi:[1,0]
	v_rcp_f32_e32 v20, v20
	v_rcp_f32_e32 v21, v21
	v_pk_mul_f32 v[18:19], v[24:25], v[18:19]
	v_cvt_f32_i32_e32 v15, v15
	v_pk_mul_f32 v[18:19], v[18:19], v[22:23]
	v_cvt_f32_i32_e32 v14, v14
	v_pk_mul_f32 v[18:19], v[18:19], v[20:21]
	v_cvt_f32_i32_e32 v11, v11
	v_cvt_pk_bf16_f32 v29, v18, v19
	v_lshl_add_u64 v[18:19], v[36:37], 0, v[114:115]
	global_store_dwordx4 v[18:19], v[26:29], off sc0 sc1
	ds_read_b32 v18, v182 offset:704
	v_cvt_f32_i32_e32 v10, v10
	v_add_u32_e32 v19, s17, v176
	v_cvt_f32_i32_e32 v17, v17
	v_cvt_f32_i32_e32 v16, v16
	s_waitcnt lgkmcnt(0)
	v_pk_mul_f32 v[22:23], v[160:161], v[18:19] op_sel_hi:[1,0]
	v_mul_f32_e32 v24, v18, v18
	v_pk_mul_f32 v[22:23], v[22:23], v[14:15]
	v_pk_mul_f32 v[10:11], v[14:15], v[10:11]
	v_pk_mul_f32 v[14:15], v[158:159], v[24:25] op_sel_hi:[1,0]
	v_cvt_f32_i32_e32 v13, v13
	v_pk_mul_f32 v[10:11], v[10:11], v[14:15]
	v_pk_mul_f32 v[14:15], v[156:157], v[18:19] op_sel_hi:[1,0]
	v_cvt_f32_i32_e32 v12, v12
	v_pk_mul_f32 v[14:15], v[14:15], v[16:17]
	v_exp_f32_e32 v22, v22
	v_exp_f32_e32 v14, v14
	v_exp_f32_e32 v15, v15
	v_exp_f32_e32 v23, v23
	v_cvt_f32_i32_e32 v7, v7
	v_cvt_f32_i32_e32 v6, v6
	v_pk_add_f32 v[14:15], v[14:15], 1.0 op_sel_hi:[1,0]
	v_pk_mul_f32 v[12:13], v[16:17], v[12:13]
	v_rcp_f32_e32 v14, v14
	v_rcp_f32_e32 v15, v15
	v_pk_mul_f32 v[16:17], v[154:155], v[24:25] op_sel_hi:[1,0]
	v_pk_add_f32 v[22:23], v[22:23], 1.0 op_sel_hi:[1,0]
	v_pk_mul_f32 v[12:13], v[12:13], v[16:17]
	v_rcp_f32_e32 v22, v22
	v_pk_mul_f32 v[12:13], v[12:13], v[14:15]
	v_pk_mul_f32 v[14:15], v[152:153], v[18:19] op_sel_hi:[1,0]
	v_rcp_f32_e32 v23, v23
	v_pk_mul_f32 v[14:15], v[14:15], v[6:7]
	v_cvt_f32_i32_e32 v3, v3
	v_exp_f32_e32 v14, v14
	v_exp_f32_e32 v15, v15
	v_cvt_f32_i32_e32 v2, v2
	v_cvt_f32_i32_e32 v9, v9
	v_cvt_f32_i32_e32 v8, v8
	v_pk_mul_f32 v[10:11], v[10:11], v[22:23]
	v_pk_mul_f32 v[2:3], v[6:7], v[2:3]
	v_cvt_pk_bf16_f32 v10, v10, v11
	v_cvt_pk_bf16_f32 v11, v12, v13
	v_pk_add_f32 v[12:13], v[14:15], 1.0 op_sel_hi:[1,0]
	v_pk_mul_f32 v[6:7], v[150:151], v[24:25] op_sel_hi:[1,0]
	v_rcp_f32_e32 v12, v12
	v_rcp_f32_e32 v13, v13
	v_pk_mul_f32 v[2:3], v[2:3], v[6:7]
	v_pk_mul_f32 v[6:7], v[148:149], v[18:19] op_sel_hi:[1,0]
	v_mad_i64_i32 v[20:21], s[28:29], v19, s49, v[162:163]
	v_pk_mul_f32 v[6:7], v[6:7], v[8:9]
	v_pk_mul_f32 v[2:3], v[2:3], v[12:13]
	v_exp_f32_e32 v6, v6
	v_exp_f32_e32 v7, v7
	v_cvt_pk_bf16_f32 v12, v2, v3
	v_cvt_f32_i32_e32 v3, v5
	v_cvt_f32_i32_e32 v2, v4
	v_pk_add_f32 v[4:5], v[6:7], 1.0 op_sel_hi:[1,0]
	v_pk_mul_f32 v[6:7], v[146:147], v[24:25] op_sel_hi:[1,0]
	v_rcp_f32_e32 v4, v4
	v_rcp_f32_e32 v5, v5
	v_pk_mul_f32 v[2:3], v[8:9], v[2:3]
	s_andn2_b64 vcc, exec, s[0:1]
	v_pk_mul_f32 v[2:3], v[2:3], v[6:7]
	s_mov_b64 s[0:1], -1
	v_pk_mul_f32 v[2:3], v[2:3], v[4:5]
	s_nop 0
	v_cvt_pk_bf16_f32 v13, v2, v3
	v_lshl_add_u64 v[2:3], v[20:21], 0, v[114:115]
	global_store_dwordx4 v[2:3], v[10:13], off sc0 sc1
	s_cbranch_vccnz .LBB0_2466
	s_andn2_b64 vcc, exec, s[10:11]
	s_cbranch_vccnz .LBB0_2465
	s_barrier
	s_branch .LBB0_2465

.LBB0_2483:
	s_ashr_i32 s0, s6, 31
	s_lshr_b32 s0, s0, 26
	s_add_i32 s0, s6, s0
	s_lshl_b32 s1, s0, 5
	s_and_b32 s4, s0, 0xffffffc0
	s_and_b32 s0, s1, 0xfffff800
	v_or_b32_e32 v24, s4, v6
	s_sub_i32 s0, s8, s0
	v_or_b32_e32 v26, 8, v24
	v_or_b32_e32 v28, 16, v24
	v_or_b32_e32 v30, 24, v24
	v_or_b32_e32 v32, 32, v24
	v_or_b32_e32 v34, 40, v24
	v_or_b32_e32 v36, 48, v24
	v_or_b32_e32 v38, 56, v24
	v_ashrrev_i32_e32 v25, 31, v24
	s_ashr_i32 s1, s0, 31
	v_ashrrev_i32_e32 v27, 31, v26
	v_ashrrev_i32_e32 v29, 31, v28
	v_ashrrev_i32_e32 v31, 31, v30
	v_ashrrev_i32_e32 v33, 31, v32
	v_ashrrev_i32_e32 v35, 31, v34
	v_ashrrev_i32_e32 v37, 31, v36
	v_ashrrev_i32_e32 v39, 31, v38
	v_lshlrev_b64 v[24:25], 13, v[24:25]
	v_lshl_add_u64 v[40:41], s[0:1], 2, v[2:3]
	v_lshlrev_b64 v[26:27], 13, v[26:27]
	v_lshlrev_b64 v[28:29], 13, v[28:29]
	v_lshlrev_b64 v[30:31], 13, v[30:31]
	v_lshlrev_b64 v[32:33], 13, v[32:33]
	v_lshlrev_b64 v[34:35], 13, v[34:35]
	v_lshlrev_b64 v[36:37], 13, v[36:37]
	v_lshlrev_b64 v[38:39], 13, v[38:39]
	v_lshl_add_u64 v[24:25], v[40:41], 0, v[24:25]
	v_lshl_add_u64 v[42:43], v[40:41], 0, v[26:27]
	v_lshl_add_u64 v[44:45], v[40:41], 0, v[28:29]
	v_lshl_add_u64 v[46:47], v[40:41], 0, v[30:31]
	v_lshl_add_u64 v[48:49], v[40:41], 0, v[32:33]
	v_lshl_add_u64 v[50:51], v[40:41], 0, v[34:35]
	v_lshl_add_u64 v[52:53], v[40:41], 0, v[36:37]
	v_lshl_add_u64 v[54:55], v[40:41], 0, v[38:39]
	global_load_dwordx4 v[24:27], v[24:25], off nt
	s_nop 0
	global_load_dwordx4 v[28:31], v[42:43], off nt
	global_load_dwordx4 v[32:35], v[44:45], off nt
	global_load_dwordx4 v[36:39], v[46:47], off nt
	s_nop 0
	global_load_dwordx4 v[40:43], v[48:49], off nt
	global_load_dwordx4 v[44:47], v[50:51], off nt
	s_nop 0
	global_load_dwordx4 v[48:51], v[52:53], off nt
	s_nop 0
	global_load_dwordx4 v[52:55], v[54:55], off nt
	s_ashr_i32 s5, s4, 31
	v_lshl_add_u64 v[56:57], s[4:5], 1, v[4:5]
	v_add_u32_e32 v64, s0, v6
	v_mad_i64_i32 v[58:59], s[0:1], v64, s10, v[56:57]
	v_add_u32_e32 v60, 8, v64
	v_mad_i64_i32 v[60:61], s[0:1], v60, s10, v[56:57]
	v_add_u32_e32 v62, 16, v64
	v_mad_i64_i32 v[62:63], s[0:1], v62, s10, v[56:57]
	s_add_i32 s6, s6, s7
	s_add_i32 s8, s8, s9
	s_cmpk_lt_i32 s6, 0x1600
	s_waitcnt vmcnt(0)
	ds_write2_b32 v9, v24, v25 offset1:1
	ds_write2_b32 v9, v26, v27 offset0:2 offset1:3
	ds_write2_b32 v10, v28, v29 offset1:1
	ds_write2_b32 v11, v30, v31 offset1:1
	ds_write2_b32 v12, v32, v33 offset1:1
	ds_write2_b32 v13, v34, v35 offset1:1
	ds_write2_b32 v14, v36, v37 offset1:1
	ds_write2_b32 v15, v38, v39 offset1:1
	ds_write2_b32 v16, v40, v41 offset1:1
	ds_write2_b32 v17, v42, v43 offset1:1
	ds_write2_b32 v18, v44, v45 offset1:1
	ds_write2_b32 v19, v46, v47 offset1:1
	ds_write2_b32 v20, v48, v49 offset1:1
	ds_write2_b32 v21, v50, v51 offset1:1
	ds_write2_b32 v22, v52, v53 offset1:1
	ds_write2_b32 v23, v54, v55 offset1:1
	s_waitcnt lgkmcnt(0)
	ds_read2_b32 v[24:25], v1 offset1:33
	s_waitcnt lgkmcnt(0)
	v_cvt_pk_bf16_f32 v24, v24, v25
	ds_read2_b32 v[26:27], v1 offset0:66 offset1:99
	s_waitcnt lgkmcnt(0)
	v_cvt_pk_bf16_f32 v25, v26, v27
	ds_read2_b32 v[26:27], v1 offset0:132 offset1:165
	s_waitcnt lgkmcnt(0)
	v_cvt_pk_bf16_f32 v26, v26, v27
	ds_read2_b32 v[28:29], v1 offset0:198 offset1:231
	s_waitcnt lgkmcnt(0)
	v_cvt_pk_bf16_f32 v27, v28, v29
	ds_read2_b32 v[28:29], v1 offset0:8 offset1:41
	global_store_dwordx4 v[58:59], v[24:27], off sc0 sc1
	s_waitcnt lgkmcnt(0)
	s_nop 0
	v_cvt_pk_bf16_f32 v24, v28, v29
	ds_read2_b32 v[26:27], v1 offset0:74 offset1:107
	s_waitcnt lgkmcnt(0)
	v_cvt_pk_bf16_f32 v25, v26, v27
	ds_read2_b32 v[26:27], v1 offset0:140 offset1:173
	s_waitcnt lgkmcnt(0)
	v_cvt_pk_bf16_f32 v26, v26, v27
	ds_read2_b32 v[28:29], v1 offset0:206 offset1:239
	s_waitcnt lgkmcnt(0)
	v_cvt_pk_bf16_f32 v27, v28, v29
	ds_read2_b32 v[28:29], v1 offset0:16 offset1:49
	global_store_dwordx4 v[60:61], v[24:27], off sc0 sc1
	s_waitcnt lgkmcnt(0)
	s_nop 0
	v_cvt_pk_bf16_f32 v24, v28, v29
	ds_read2_b32 v[26:27], v1 offset0:82 offset1:115
	s_waitcnt lgkmcnt(0)
	v_cvt_pk_bf16_f32 v25, v26, v27
	ds_read2_b32 v[26:27], v1 offset0:148 offset1:181
	s_waitcnt lgkmcnt(0)
	v_cvt_pk_bf16_f32 v26, v26, v27
	ds_read2_b32 v[28:29], v1 offset0:214 offset1:247
	s_waitcnt lgkmcnt(0)
	v_cvt_pk_bf16_f32 v27, v28, v29
	ds_read2_b32 v[28:29], v1 offset0:24 offset1:57
	global_store_dwordx4 v[62:63], v[24:27], off sc0 sc1
	s_waitcnt lgkmcnt(0)
	s_nop 0
	v_cvt_pk_bf16_f32 v24, v28, v29
	ds_read2_b32 v[26:27], v1 offset0:90 offset1:123
	s_waitcnt lgkmcnt(0)
	v_cvt_pk_bf16_f32 v25, v26, v27
	ds_read2_b32 v[26:27], v1 offset0:156 offset1:189
	s_waitcnt lgkmcnt(0)
	v_cvt_pk_bf16_f32 v26, v26, v27
	v_add_u32_e32 v27, 24, v64
	v_mad_i64_i32 v[30:31], s[0:1], v27, s10, v[56:57]
	ds_read2_b32 v[28:29], v1 offset0:222 offset1:255
	s_waitcnt lgkmcnt(0)
	v_cvt_pk_bf16_f32 v27, v28, v29
	global_store_dwordx4 v[30:31], v[24:27], off sc0 sc1
	s_waitcnt lgkmcnt(0)
	s_cbranch_scc1 .LBB0_2483

.LBB0_2488:
	s_ashr_i32 s0, s6, 31
	s_lshr_b32 s0, s0, 26
	s_add_i32 s0, s6, s0
	s_lshl_b32 s1, s0, 5
	s_and_b32 s4, s0, 0xffffffc0
	s_and_b32 s0, s1, 0xfffff800
	v_or_b32_e32 v22, s4, v6
	s_sub_i32 s0, s8, s0
	v_or_b32_e32 v24, 8, v22
	v_or_b32_e32 v26, 16, v22
	v_or_b32_e32 v28, 24, v22
	v_or_b32_e32 v30, 32, v22
	v_or_b32_e32 v32, 40, v22
	v_or_b32_e32 v34, 48, v22
	v_or_b32_e32 v36, 56, v22
	v_ashrrev_i32_e32 v23, 31, v22
	s_ashr_i32 s1, s0, 31
	v_ashrrev_i32_e32 v25, 31, v24
	v_ashrrev_i32_e32 v27, 31, v26
	v_ashrrev_i32_e32 v29, 31, v28
	v_ashrrev_i32_e32 v31, 31, v30
	v_ashrrev_i32_e32 v33, 31, v32
	v_ashrrev_i32_e32 v35, 31, v34
	v_ashrrev_i32_e32 v37, 31, v36
	v_lshlrev_b64 v[22:23], 13, v[22:23]
	v_lshl_add_u64 v[38:39], s[0:1], 2, v[2:3]
	v_lshlrev_b64 v[24:25], 13, v[24:25]
	v_lshlrev_b64 v[26:27], 13, v[26:27]
	v_lshlrev_b64 v[28:29], 13, v[28:29]
	v_lshlrev_b64 v[30:31], 13, v[30:31]
	v_lshlrev_b64 v[32:33], 13, v[32:33]
	v_lshlrev_b64 v[34:35], 13, v[34:35]
	v_lshlrev_b64 v[36:37], 13, v[36:37]
	v_lshl_add_u64 v[22:23], v[38:39], 0, v[22:23]
	v_lshl_add_u64 v[40:41], v[38:39], 0, v[24:25]
	v_lshl_add_u64 v[42:43], v[38:39], 0, v[26:27]
	v_lshl_add_u64 v[44:45], v[38:39], 0, v[28:29]
	v_lshl_add_u64 v[46:47], v[38:39], 0, v[30:31]
	v_lshl_add_u64 v[48:49], v[38:39], 0, v[32:33]
	v_lshl_add_u64 v[50:51], v[38:39], 0, v[34:35]
	v_lshl_add_u64 v[52:53], v[38:39], 0, v[36:37]
	global_load_dwordx4 v[22:25], v[22:23], off nt
	s_nop 0
	global_load_dwordx4 v[26:29], v[40:41], off nt
	global_load_dwordx4 v[30:33], v[42:43], off nt
	global_load_dwordx4 v[34:37], v[44:45], off nt
	s_nop 0
	global_load_dwordx4 v[38:41], v[46:47], off nt
	global_load_dwordx4 v[42:45], v[48:49], off nt
	s_nop 0
	global_load_dwordx4 v[46:49], v[50:51], off nt
	s_nop 0
	global_load_dwordx4 v[50:53], v[52:53], off nt
	s_ashr_i32 s5, s4, 31
	v_lshl_add_u64 v[54:55], s[4:5], 1, v[4:5]
	v_add_u32_e32 v62, s0, v6
	v_mad_i64_i32 v[56:57], s[0:1], v62, s10, v[54:55]
	v_add_u32_e32 v58, 8, v62
	v_mad_i64_i32 v[58:59], s[0:1], v58, s10, v[54:55]
	v_add_u32_e32 v60, 16, v62
	v_mad_i64_i32 v[60:61], s[0:1], v60, s10, v[54:55]
	s_add_i32 s6, s6, s7
	s_add_i32 s8, s8, s9
	s_cmpk_gt_i32 s6, 0x15ff
	s_waitcnt vmcnt(0)
	ds_write2_b32 v7, v22, v23 offset1:1
	ds_write2_b32 v7, v24, v25 offset0:2 offset1:3
	ds_write2_b32 v8, v26, v27 offset1:1
	ds_write2_b32 v9, v28, v29 offset1:1
	ds_write2_b32 v10, v30, v31 offset1:1
	ds_write2_b32 v11, v32, v33 offset1:1
	ds_write2_b32 v12, v34, v35 offset1:1
	ds_write2_b32 v13, v36, v37 offset1:1
	ds_write2_b32 v14, v38, v39 offset1:1
	ds_write2_b32 v15, v40, v41 offset1:1
	ds_write2_b32 v16, v42, v43 offset1:1
	ds_write2_b32 v17, v44, v45 offset1:1
	ds_write2_b32 v18, v46, v47 offset1:1
	ds_write2_b32 v19, v48, v49 offset1:1
	ds_write2_b32 v20, v50, v51 offset1:1
	ds_write2_b32 v21, v52, v53 offset1:1
	s_waitcnt lgkmcnt(0)
	ds_read2_b32 v[22:23], v1 offset1:33
	s_waitcnt lgkmcnt(0)
	v_cvt_pk_bf16_f32 v22, v22, v23
	ds_read2_b32 v[24:25], v1 offset0:66 offset1:99
	s_waitcnt lgkmcnt(0)
	v_cvt_pk_bf16_f32 v23, v24, v25
	ds_read2_b32 v[24:25], v1 offset0:132 offset1:165
	s_waitcnt lgkmcnt(0)
	v_cvt_pk_bf16_f32 v24, v24, v25
	ds_read2_b32 v[26:27], v1 offset0:198 offset1:231
	s_waitcnt lgkmcnt(0)
	v_cvt_pk_bf16_f32 v25, v26, v27
	ds_read2_b32 v[26:27], v1 offset0:8 offset1:41
	global_store_dwordx4 v[56:57], v[22:25], off sc0 sc1
	s_waitcnt lgkmcnt(0)
	s_nop 0
	v_cvt_pk_bf16_f32 v22, v26, v27
	ds_read2_b32 v[24:25], v1 offset0:74 offset1:107
	s_waitcnt lgkmcnt(0)
	v_cvt_pk_bf16_f32 v23, v24, v25
	ds_read2_b32 v[24:25], v1 offset0:140 offset1:173
	s_waitcnt lgkmcnt(0)
	v_cvt_pk_bf16_f32 v24, v24, v25
	ds_read2_b32 v[26:27], v1 offset0:206 offset1:239
	s_waitcnt lgkmcnt(0)
	v_cvt_pk_bf16_f32 v25, v26, v27
	ds_read2_b32 v[26:27], v1 offset0:16 offset1:49
	global_store_dwordx4 v[58:59], v[22:25], off sc0 sc1
	s_waitcnt lgkmcnt(0)
	s_nop 0
	v_cvt_pk_bf16_f32 v22, v26, v27
	ds_read2_b32 v[24:25], v1 offset0:82 offset1:115
	s_waitcnt lgkmcnt(0)
	v_cvt_pk_bf16_f32 v23, v24, v25
	ds_read2_b32 v[24:25], v1 offset0:148 offset1:181
	s_waitcnt lgkmcnt(0)
	v_cvt_pk_bf16_f32 v24, v24, v25
	ds_read2_b32 v[26:27], v1 offset0:214 offset1:247
	s_waitcnt lgkmcnt(0)
	v_cvt_pk_bf16_f32 v25, v26, v27
	ds_read2_b32 v[26:27], v1 offset0:24 offset1:57
	global_store_dwordx4 v[60:61], v[22:25], off sc0 sc1
	s_waitcnt lgkmcnt(0)
	s_nop 0
	v_cvt_pk_bf16_f32 v22, v26, v27
	ds_read2_b32 v[24:25], v1 offset0:90 offset1:123
	s_waitcnt lgkmcnt(0)
	v_cvt_pk_bf16_f32 v23, v24, v25
	ds_read2_b32 v[24:25], v1 offset0:156 offset1:189
	s_waitcnt lgkmcnt(0)
	v_cvt_pk_bf16_f32 v24, v24, v25
	v_add_u32_e32 v25, 24, v62
	v_mad_i64_i32 v[28:29], s[0:1], v25, s10, v[54:55]
	ds_read2_b32 v[26:27], v1 offset0:222 offset1:255
	s_waitcnt lgkmcnt(0)
	v_cvt_pk_bf16_f32 v25, v26, v27
	global_store_dwordx4 v[28:29], v[22:25], off sc0 sc1
	s_waitcnt lgkmcnt(0)
	s_cbranch_scc0 .LBB0_2488

.LBB0_3390:
	s_lshl_b32 s17, s49, 11
	s_add_i32 s17, s17, 0
	s_add_i32 s19, s17, 0x20180
	s_lshl_b32 s17, s42, 2
	s_add_i32 s17, s19, s17
	v_lshl_add_u32 v154, v164, 2, s17
	ds_read_b128 v[146:149], v154 offset:1024
	ds_read_b128 v[150:153], v154 offset:1536
	ds_read_b128 v[182:185], v154 offset:1040
	ds_read_b128 v[186:189], v154 offset:1552
	v_lshl_add_u32 v181, v165, 2, s19
	s_waitcnt lgkmcnt(0)
	v_pk_mul_f32 v[160:161], v[146:147], s[14:15] op_sel_hi:[1,0]
	v_pk_mul_f32 v[156:157], v[148:149], s[14:15] op_sel_hi:[1,0]
	v_pk_mul_f32 v[154:155], v[148:149], v[152:153]
	v_pk_mul_f32 v[158:159], v[146:147], v[150:151]
	v_pk_mul_f32 v[148:149], v[184:185], s[14:15] op_sel_hi:[1,0]
	v_pk_mul_f32 v[146:147], v[184:185], v[188:189]
	ds_read_b32 v184, v181
	v_cvt_f32_i32_e32 v127, v127
	v_cvt_f32_i32_e32 v126, v126
	v_cvt_f32_i32_e32 v123, v123
	v_cvt_f32_i32_e32 v122, v122
	s_lshl_b32 s17, s24, 8
	v_add_u32_e32 v185, s17, v165
	v_cvt_f32_i32_e32 v129, v129
	v_cvt_f32_i32_e32 v128, v128
	s_waitcnt lgkmcnt(0)
	v_pk_mul_f32 v[188:189], v[160:161], v[184:185] op_sel_hi:[1,0]
	v_mul_f32_e32 v190, v184, v184
	v_pk_mul_f32 v[188:189], v[188:189], v[126:127]
	v_pk_mul_f32 v[122:123], v[126:127], v[122:123]
	v_pk_mul_f32 v[126:127], v[158:159], v[190:191] op_sel_hi:[1,0]
	v_cvt_f32_i32_e32 v125, v125
	v_pk_mul_f32 v[122:123], v[122:123], v[126:127]
	v_pk_mul_f32 v[126:127], v[156:157], v[184:185] op_sel_hi:[1,0]
	v_cvt_f32_i32_e32 v124, v124
	v_pk_mul_f32 v[126:127], v[126:127], v[128:129]
	v_exp_f32_e32 v188, v188
	v_exp_f32_e32 v126, v126
	v_exp_f32_e32 v127, v127
	v_exp_f32_e32 v189, v189
	v_cvt_f32_i32_e32 v119, v119
	v_cvt_f32_i32_e32 v118, v118
	v_pk_add_f32 v[126:127], v[126:127], 1.0 op_sel_hi:[1,0]
	v_pk_mul_f32 v[124:125], v[128:129], v[124:125]
	v_rcp_f32_e32 v126, v126
	v_rcp_f32_e32 v127, v127
	v_pk_mul_f32 v[128:129], v[154:155], v[190:191] op_sel_hi:[1,0]
	v_pk_mul_f32 v[152:153], v[182:183], s[14:15] op_sel_hi:[1,0]
	v_pk_mul_f32 v[124:125], v[124:125], v[128:129]
	v_pk_add_f32 v[188:189], v[188:189], 1.0 op_sel_hi:[1,0]
	v_pk_mul_f32 v[124:125], v[124:125], v[126:127]
	v_pk_mul_f32 v[126:127], v[152:153], v[184:185] op_sel_hi:[1,0]
	v_rcp_f32_e32 v188, v188
	v_rcp_f32_e32 v189, v189
	v_pk_mul_f32 v[126:127], v[126:127], v[118:119]
	v_cvt_f32_i32_e32 v115, v115
	v_exp_f32_e32 v126, v126
	v_exp_f32_e32 v127, v127
	v_cvt_f32_i32_e32 v114, v114
	v_cvt_f32_i32_e32 v121, v121
	v_cvt_f32_i32_e32 v120, v120
	v_pk_mul_f32 v[150:151], v[182:183], v[186:187]
	v_pk_mul_f32 v[122:123], v[122:123], v[188:189]
	v_pk_mul_f32 v[114:115], v[118:119], v[114:115]
	v_cvt_pk_bf16_f32 v122, v122, v123
	v_cvt_pk_bf16_f32 v123, v124, v125
	v_pk_add_f32 v[124:125], v[126:127], 1.0 op_sel_hi:[1,0]
	v_pk_mul_f32 v[118:119], v[150:151], v[190:191] op_sel_hi:[1,0]
	v_rcp_f32_e32 v124, v124
	v_rcp_f32_e32 v125, v125
	v_pk_mul_f32 v[114:115], v[114:115], v[118:119]
	v_pk_mul_f32 v[118:119], v[148:149], v[184:185] op_sel_hi:[1,0]
	v_lshl_or_b32 v182, s48, 7, v176
	v_pk_mul_f32 v[118:119], v[118:119], v[120:121]
	v_pk_mul_f32 v[114:115], v[114:115], v[124:125]
	v_exp_f32_e32 v118, v118
	v_exp_f32_e32 v119, v119
	v_cvt_pk_bf16_f32 v124, v114, v115
	v_cvt_f32_i32_e32 v115, v117
	v_cvt_f32_i32_e32 v114, v116
	v_pk_add_f32 v[116:117], v[118:119], 1.0 op_sel_hi:[1,0]
	v_pk_mul_f32 v[118:119], v[146:147], v[190:191] op_sel_hi:[1,0]
	v_rcp_f32_e32 v116, v116
	v_rcp_f32_e32 v117, v117
	v_pk_mul_f32 v[114:115], v[120:121], v[114:115]
	v_ashrrev_i32_e32 v183, 31, v182
	v_pk_mul_f32 v[114:115], v[114:115], v[118:119]
	v_mov_b64_e32 v[162:163], s[60:61]
	v_pk_mul_f32 v[114:115], v[114:115], v[116:117]
	v_mad_i64_i32 v[186:187], s[26:27], v185, s46, v[162:163]
	v_cvt_pk_bf16_f32 v125, v114, v115
	v_lshlrev_b64 v[114:115], 1, v[182:183]
	v_lshl_add_u64 v[116:117], v[186:187], 0, v[114:115]
	global_store_dwordx4 v[116:117], v[122:125], off sc0 sc1
	ds_read_b32 v116, v181 offset:64
	v_cvt_f32_i32_e32 v111, v111
	v_cvt_f32_i32_e32 v110, v110
	v_cvt_f32_i32_e32 v107, v107
	v_cvt_f32_i32_e32 v106, v106
	v_add_u32_e32 v117, s17, v169
	v_cvt_f32_i32_e32 v113, v113
	v_cvt_f32_i32_e32 v112, v112
	s_waitcnt lgkmcnt(0)
	v_pk_mul_f32 v[120:121], v[160:161], v[116:117] op_sel_hi:[1,0]
	v_mul_f32_e32 v122, v116, v116
	v_pk_mul_f32 v[120:121], v[120:121], v[110:111]
	v_pk_mul_f32 v[106:107], v[110:111], v[106:107]
	v_pk_mul_f32 v[110:111], v[158:159], v[122:123] op_sel_hi:[1,0]
	v_cvt_f32_i32_e32 v109, v109
	v_pk_mul_f32 v[106:107], v[106:107], v[110:111]
	v_pk_mul_f32 v[110:111], v[156:157], v[116:117] op_sel_hi:[1,0]
	v_cvt_f32_i32_e32 v108, v108
	v_pk_mul_f32 v[110:111], v[110:111], v[112:113]
	v_exp_f32_e32 v120, v120
	v_exp_f32_e32 v110, v110
	v_exp_f32_e32 v111, v111
	v_exp_f32_e32 v121, v121
	v_cvt_f32_i32_e32 v103, v103
	v_cvt_f32_i32_e32 v102, v102
	v_pk_add_f32 v[110:111], v[110:111], 1.0 op_sel_hi:[1,0]
	v_pk_mul_f32 v[108:109], v[112:113], v[108:109]
	v_rcp_f32_e32 v110, v110
	v_rcp_f32_e32 v111, v111
	v_pk_mul_f32 v[112:113], v[154:155], v[122:123] op_sel_hi:[1,0]
	v_pk_add_f32 v[120:121], v[120:121], 1.0 op_sel_hi:[1,0]
	v_pk_mul_f32 v[108:109], v[108:109], v[112:113]
	v_rcp_f32_e32 v120, v120
	v_pk_mul_f32 v[108:109], v[108:109], v[110:111]
	v_pk_mul_f32 v[110:111], v[152:153], v[116:117] op_sel_hi:[1,0]
	v_rcp_f32_e32 v121, v121
	v_pk_mul_f32 v[110:111], v[110:111], v[102:103]
	v_cvt_f32_i32_e32 v99, v99
	v_exp_f32_e32 v110, v110
	v_exp_f32_e32 v111, v111
	v_cvt_f32_i32_e32 v98, v98
	v_cvt_f32_i32_e32 v105, v105
	v_cvt_f32_i32_e32 v104, v104
	v_pk_mul_f32 v[106:107], v[106:107], v[120:121]
	v_pk_mul_f32 v[98:99], v[102:103], v[98:99]
	v_cvt_pk_bf16_f32 v106, v106, v107
	v_cvt_pk_bf16_f32 v107, v108, v109
	v_pk_add_f32 v[108:109], v[110:111], 1.0 op_sel_hi:[1,0]
	v_pk_mul_f32 v[102:103], v[150:151], v[122:123] op_sel_hi:[1,0]
	v_rcp_f32_e32 v108, v108
	v_rcp_f32_e32 v109, v109
	v_pk_mul_f32 v[98:99], v[98:99], v[102:103]
	v_pk_mul_f32 v[102:103], v[148:149], v[116:117] op_sel_hi:[1,0]
	v_mad_i64_i32 v[118:119], s[26:27], v117, s46, v[162:163]
	v_pk_mul_f32 v[102:103], v[102:103], v[104:105]
	v_pk_mul_f32 v[98:99], v[98:99], v[108:109]
	v_exp_f32_e32 v102, v102
	v_exp_f32_e32 v103, v103
	v_cvt_pk_bf16_f32 v108, v98, v99
	v_cvt_f32_i32_e32 v99, v101
	v_cvt_f32_i32_e32 v98, v100
	v_pk_add_f32 v[100:101], v[102:103], 1.0 op_sel_hi:[1,0]
	v_pk_mul_f32 v[102:103], v[146:147], v[122:123] op_sel_hi:[1,0]
	v_rcp_f32_e32 v100, v100
	v_rcp_f32_e32 v101, v101
	v_pk_mul_f32 v[98:99], v[104:105], v[98:99]
	v_cvt_f32_i32_e32 v95, v95
	v_pk_mul_f32 v[98:99], v[98:99], v[102:103]
	v_cvt_f32_i32_e32 v94, v94
	v_pk_mul_f32 v[98:99], v[98:99], v[100:101]
	v_cvt_f32_i32_e32 v91, v91
	v_cvt_pk_bf16_f32 v109, v98, v99
	v_lshl_add_u64 v[98:99], v[118:119], 0, v[114:115]
	global_store_dwordx4 v[98:99], v[106:109], off sc0 sc1
	ds_read_b32 v98, v181 offset:128
	v_cvt_f32_i32_e32 v90, v90
	v_add_u32_e32 v99, s17, v170
	v_cvt_f32_i32_e32 v97, v97
	v_cvt_f32_i32_e32 v96, v96
	s_waitcnt lgkmcnt(0)
	v_pk_mul_f32 v[102:103], v[160:161], v[98:99] op_sel_hi:[1,0]
	v_mul_f32_e32 v104, v98, v98
	v_pk_mul_f32 v[102:103], v[102:103], v[94:95]
	v_pk_mul_f32 v[90:91], v[94:95], v[90:91]
	v_pk_mul_f32 v[94:95], v[158:159], v[104:105] op_sel_hi:[1,0]
	v_cvt_f32_i32_e32 v93, v93
	v_pk_mul_f32 v[90:91], v[90:91], v[94:95]
	v_pk_mul_f32 v[94:95], v[156:157], v[98:99] op_sel_hi:[1,0]
	v_cvt_f32_i32_e32 v92, v92
	v_pk_mul_f32 v[94:95], v[94:95], v[96:97]
	v_exp_f32_e32 v102, v102
	v_exp_f32_e32 v94, v94
	v_exp_f32_e32 v95, v95
	v_exp_f32_e32 v103, v103
	v_cvt_f32_i32_e32 v87, v87
	v_cvt_f32_i32_e32 v86, v86
	v_pk_add_f32 v[94:95], v[94:95], 1.0 op_sel_hi:[1,0]
	v_pk_mul_f32 v[92:93], v[96:97], v[92:93]
	v_rcp_f32_e32 v94, v94
	v_rcp_f32_e32 v95, v95
	v_pk_mul_f32 v[96:97], v[154:155], v[104:105] op_sel_hi:[1,0]
	v_pk_add_f32 v[102:103], v[102:103], 1.0 op_sel_hi:[1,0]
	v_pk_mul_f32 v[92:93], v[92:93], v[96:97]
	v_rcp_f32_e32 v102, v102
	v_pk_mul_f32 v[92:93], v[92:93], v[94:95]
	v_pk_mul_f32 v[94:95], v[152:153], v[98:99] op_sel_hi:[1,0]
	v_rcp_f32_e32 v103, v103
	v_pk_mul_f32 v[94:95], v[94:95], v[86:87]
	v_cvt_f32_i32_e32 v83, v83
	v_exp_f32_e32 v94, v94
	v_exp_f32_e32 v95, v95
	v_cvt_f32_i32_e32 v82, v82
	v_cvt_f32_i32_e32 v89, v89
	v_cvt_f32_i32_e32 v88, v88
	v_pk_mul_f32 v[90:91], v[90:91], v[102:103]
	v_pk_mul_f32 v[82:83], v[86:87], v[82:83]
	v_cvt_pk_bf16_f32 v90, v90, v91
	v_cvt_pk_bf16_f32 v91, v92, v93
	v_pk_add_f32 v[92:93], v[94:95], 1.0 op_sel_hi:[1,0]
	v_pk_mul_f32 v[86:87], v[150:151], v[104:105] op_sel_hi:[1,0]
	v_rcp_f32_e32 v92, v92
	v_rcp_f32_e32 v93, v93
	v_pk_mul_f32 v[82:83], v[82:83], v[86:87]
	v_pk_mul_f32 v[86:87], v[148:149], v[98:99] op_sel_hi:[1,0]
	v_mad_i64_i32 v[100:101], s[26:27], v99, s46, v[162:163]
	v_pk_mul_f32 v[86:87], v[86:87], v[88:89]
	v_pk_mul_f32 v[82:83], v[82:83], v[92:93]
	v_exp_f32_e32 v86, v86
	v_exp_f32_e32 v87, v87
	v_cvt_pk_bf16_f32 v92, v82, v83
	v_cvt_f32_i32_e32 v83, v85
	v_cvt_f32_i32_e32 v82, v84
	v_pk_add_f32 v[84:85], v[86:87], 1.0 op_sel_hi:[1,0]
	v_pk_mul_f32 v[86:87], v[146:147], v[104:105] op_sel_hi:[1,0]
	v_rcp_f32_e32 v84, v84
	v_rcp_f32_e32 v85, v85
	v_pk_mul_f32 v[82:83], v[88:89], v[82:83]
	v_cvt_f32_i32_e32 v79, v79
	v_pk_mul_f32 v[82:83], v[82:83], v[86:87]
	v_cvt_f32_i32_e32 v78, v78
	v_pk_mul_f32 v[82:83], v[82:83], v[84:85]
	v_cvt_f32_i32_e32 v75, v75
	v_cvt_pk_bf16_f32 v93, v82, v83
	v_lshl_add_u64 v[82:83], v[100:101], 0, v[114:115]
	global_store_dwordx4 v[82:83], v[90:93], off sc0 sc1
	ds_read_b32 v82, v181 offset:192
	v_cvt_f32_i32_e32 v74, v74
	v_add_u32_e32 v83, s17, v171
	v_cvt_f32_i32_e32 v81, v81
	v_cvt_f32_i32_e32 v80, v80
	s_waitcnt lgkmcnt(0)
	v_pk_mul_f32 v[86:87], v[160:161], v[82:83] op_sel_hi:[1,0]
	v_mul_f32_e32 v88, v82, v82
	v_pk_mul_f32 v[86:87], v[86:87], v[78:79]
	v_pk_mul_f32 v[74:75], v[78:79], v[74:75]
	v_pk_mul_f32 v[78:79], v[158:159], v[88:89] op_sel_hi:[1,0]
	v_cvt_f32_i32_e32 v77, v77
	v_pk_mul_f32 v[74:75], v[74:75], v[78:79]
	v_pk_mul_f32 v[78:79], v[156:157], v[82:83] op_sel_hi:[1,0]
	v_cvt_f32_i32_e32 v76, v76
	v_pk_mul_f32 v[78:79], v[78:79], v[80:81]
	v_exp_f32_e32 v86, v86
	v_exp_f32_e32 v78, v78
	v_exp_f32_e32 v79, v79
	v_exp_f32_e32 v87, v87
	v_cvt_f32_i32_e32 v71, v71
	v_cvt_f32_i32_e32 v70, v70
	v_pk_add_f32 v[78:79], v[78:79], 1.0 op_sel_hi:[1,0]
	v_pk_mul_f32 v[76:77], v[80:81], v[76:77]
	v_rcp_f32_e32 v78, v78
	v_rcp_f32_e32 v79, v79
	v_pk_mul_f32 v[80:81], v[154:155], v[88:89] op_sel_hi:[1,0]
	v_pk_add_f32 v[86:87], v[86:87], 1.0 op_sel_hi:[1,0]
	v_pk_mul_f32 v[76:77], v[76:77], v[80:81]
	v_rcp_f32_e32 v86, v86
	v_pk_mul_f32 v[76:77], v[76:77], v[78:79]
	v_pk_mul_f32 v[78:79], v[152:153], v[82:83] op_sel_hi:[1,0]
	v_rcp_f32_e32 v87, v87
	v_pk_mul_f32 v[78:79], v[78:79], v[70:71]
	v_cvt_f32_i32_e32 v67, v67
	v_exp_f32_e32 v78, v78
	v_exp_f32_e32 v79, v79
	v_cvt_f32_i32_e32 v66, v66
	v_cvt_f32_i32_e32 v73, v73
	v_cvt_f32_i32_e32 v72, v72
	v_pk_mul_f32 v[74:75], v[74:75], v[86:87]
	v_pk_mul_f32 v[66:67], v[70:71], v[66:67]
	v_cvt_pk_bf16_f32 v74, v74, v75
	v_cvt_pk_bf16_f32 v75, v76, v77
	v_pk_add_f32 v[76:77], v[78:79], 1.0 op_sel_hi:[1,0]
	v_pk_mul_f32 v[70:71], v[150:151], v[88:89] op_sel_hi:[1,0]
	v_rcp_f32_e32 v76, v76
	v_rcp_f32_e32 v77, v77
	v_pk_mul_f32 v[66:67], v[66:67], v[70:71]
	v_pk_mul_f32 v[70:71], v[148:149], v[82:83] op_sel_hi:[1,0]
	v_mad_i64_i32 v[84:85], s[26:27], v83, s46, v[162:163]
	v_pk_mul_f32 v[70:71], v[70:71], v[72:73]
	v_pk_mul_f32 v[66:67], v[66:67], v[76:77]
	v_exp_f32_e32 v70, v70
	v_exp_f32_e32 v71, v71
	v_cvt_pk_bf16_f32 v76, v66, v67
	v_cvt_f32_i32_e32 v67, v69
	v_cvt_f32_i32_e32 v66, v68
	v_pk_add_f32 v[68:69], v[70:71], 1.0 op_sel_hi:[1,0]
	v_pk_mul_f32 v[70:71], v[146:147], v[88:89] op_sel_hi:[1,0]
	v_rcp_f32_e32 v68, v68
	v_rcp_f32_e32 v69, v69
	v_pk_mul_f32 v[66:67], v[72:73], v[66:67]
	v_cvt_f32_i32_e32 v63, v63
	v_pk_mul_f32 v[66:67], v[66:67], v[70:71]
	v_cvt_f32_i32_e32 v62, v62
	v_pk_mul_f32 v[66:67], v[66:67], v[68:69]
	v_cvt_f32_i32_e32 v59, v59
	v_cvt_pk_bf16_f32 v77, v66, v67
	v_lshl_add_u64 v[66:67], v[84:85], 0, v[114:115]
	global_store_dwordx4 v[66:67], v[74:77], off sc0 sc1
	ds_read_b32 v66, v181 offset:512
	v_cvt_f32_i32_e32 v58, v58
	v_add_u32_e32 v67, s17, v172
	v_cvt_f32_i32_e32 v65, v65
	v_cvt_f32_i32_e32 v64, v64
	s_waitcnt lgkmcnt(0)
	v_pk_mul_f32 v[70:71], v[160:161], v[66:67] op_sel_hi:[1,0]
	v_mul_f32_e32 v72, v66, v66
	v_pk_mul_f32 v[70:71], v[70:71], v[62:63]
	v_pk_mul_f32 v[58:59], v[62:63], v[58:59]
	v_pk_mul_f32 v[62:63], v[158:159], v[72:73] op_sel_hi:[1,0]
	v_cvt_f32_i32_e32 v61, v61
	v_pk_mul_f32 v[58:59], v[58:59], v[62:63]
	v_pk_mul_f32 v[62:63], v[156:157], v[66:67] op_sel_hi:[1,0]
	v_cvt_f32_i32_e32 v60, v60
	v_pk_mul_f32 v[62:63], v[62:63], v[64:65]
	v_exp_f32_e32 v70, v70
	v_exp_f32_e32 v62, v62
	v_exp_f32_e32 v63, v63
	v_exp_f32_e32 v71, v71
	v_cvt_f32_i32_e32 v55, v55
	v_cvt_f32_i32_e32 v54, v54
	v_pk_add_f32 v[62:63], v[62:63], 1.0 op_sel_hi:[1,0]
	v_pk_mul_f32 v[60:61], v[64:65], v[60:61]
	v_rcp_f32_e32 v62, v62
	v_rcp_f32_e32 v63, v63
	v_pk_mul_f32 v[64:65], v[154:155], v[72:73] op_sel_hi:[1,0]
	v_pk_add_f32 v[70:71], v[70:71], 1.0 op_sel_hi:[1,0]
	v_pk_mul_f32 v[60:61], v[60:61], v[64:65]
	v_rcp_f32_e32 v70, v70
	v_pk_mul_f32 v[60:61], v[60:61], v[62:63]
	v_pk_mul_f32 v[62:63], v[152:153], v[66:67] op_sel_hi:[1,0]
	v_rcp_f32_e32 v71, v71
	v_pk_mul_f32 v[62:63], v[62:63], v[54:55]
	v_cvt_f32_i32_e32 v51, v51
	v_exp_f32_e32 v62, v62
	v_exp_f32_e32 v63, v63
	v_cvt_f32_i32_e32 v50, v50
	v_cvt_f32_i32_e32 v57, v57
	v_cvt_f32_i32_e32 v56, v56
	v_pk_mul_f32 v[58:59], v[58:59], v[70:71]
	v_pk_mul_f32 v[50:51], v[54:55], v[50:51]
	v_cvt_pk_bf16_f32 v58, v58, v59
	v_cvt_pk_bf16_f32 v59, v60, v61
	v_pk_add_f32 v[60:61], v[62:63], 1.0 op_sel_hi:[1,0]
	v_pk_mul_f32 v[54:55], v[150:151], v[72:73] op_sel_hi:[1,0]
	v_rcp_f32_e32 v60, v60
	v_rcp_f32_e32 v61, v61
	v_pk_mul_f32 v[50:51], v[50:51], v[54:55]
	v_pk_mul_f32 v[54:55], v[148:149], v[66:67] op_sel_hi:[1,0]
	v_mad_i64_i32 v[68:69], s[26:27], v67, s46, v[162:163]
	v_pk_mul_f32 v[54:55], v[54:55], v[56:57]
	v_pk_mul_f32 v[50:51], v[50:51], v[60:61]
	v_exp_f32_e32 v54, v54
	v_exp_f32_e32 v55, v55
	v_cvt_pk_bf16_f32 v60, v50, v51
	v_cvt_f32_i32_e32 v51, v53
	v_cvt_f32_i32_e32 v50, v52
	v_pk_add_f32 v[52:53], v[54:55], 1.0 op_sel_hi:[1,0]
	v_pk_mul_f32 v[54:55], v[146:147], v[72:73] op_sel_hi:[1,0]
	v_rcp_f32_e32 v52, v52
	v_rcp_f32_e32 v53, v53
	v_pk_mul_f32 v[50:51], v[56:57], v[50:51]
	v_cvt_f32_i32_e32 v47, v47
	v_pk_mul_f32 v[50:51], v[50:51], v[54:55]
	v_cvt_f32_i32_e32 v46, v46
	v_pk_mul_f32 v[50:51], v[50:51], v[52:53]
	v_cvt_f32_i32_e32 v43, v43
	v_cvt_pk_bf16_f32 v61, v50, v51
	v_lshl_add_u64 v[50:51], v[68:69], 0, v[114:115]
	global_store_dwordx4 v[50:51], v[58:61], off sc0 sc1
	ds_read_b32 v50, v181 offset:576
	v_cvt_f32_i32_e32 v42, v42
	v_add_u32_e32 v51, s17, v173
	v_cvt_f32_i32_e32 v49, v49
	v_cvt_f32_i32_e32 v48, v48
	s_waitcnt lgkmcnt(0)
	v_pk_mul_f32 v[54:55], v[160:161], v[50:51] op_sel_hi:[1,0]
	v_mul_f32_e32 v56, v50, v50
	v_pk_mul_f32 v[54:55], v[54:55], v[46:47]
	v_pk_mul_f32 v[42:43], v[46:47], v[42:43]
	v_pk_mul_f32 v[46:47], v[158:159], v[56:57] op_sel_hi:[1,0]
	v_cvt_f32_i32_e32 v45, v45
	v_pk_mul_f32 v[42:43], v[42:43], v[46:47]
	v_pk_mul_f32 v[46:47], v[156:157], v[50:51] op_sel_hi:[1,0]
	v_cvt_f32_i32_e32 v44, v44
	v_pk_mul_f32 v[46:47], v[46:47], v[48:49]
	v_exp_f32_e32 v54, v54
	v_exp_f32_e32 v46, v46
	v_exp_f32_e32 v47, v47
	v_exp_f32_e32 v55, v55
	v_cvt_f32_i32_e32 v39, v39
	v_cvt_f32_i32_e32 v38, v38
	v_pk_add_f32 v[46:47], v[46:47], 1.0 op_sel_hi:[1,0]
	v_pk_mul_f32 v[44:45], v[48:49], v[44:45]
	v_rcp_f32_e32 v46, v46
	v_rcp_f32_e32 v47, v47
	v_pk_mul_f32 v[48:49], v[154:155], v[56:57] op_sel_hi:[1,0]
	v_pk_add_f32 v[54:55], v[54:55], 1.0 op_sel_hi:[1,0]
	v_pk_mul_f32 v[44:45], v[44:45], v[48:49]
	v_rcp_f32_e32 v54, v54
	v_pk_mul_f32 v[44:45], v[44:45], v[46:47]
	v_pk_mul_f32 v[46:47], v[152:153], v[50:51] op_sel_hi:[1,0]
	v_rcp_f32_e32 v55, v55
	v_pk_mul_f32 v[46:47], v[46:47], v[38:39]
	v_cvt_f32_i32_e32 v35, v35
	v_exp_f32_e32 v46, v46
	v_exp_f32_e32 v47, v47
	v_cvt_f32_i32_e32 v34, v34
	v_cvt_f32_i32_e32 v41, v41
	v_cvt_f32_i32_e32 v40, v40
	v_pk_mul_f32 v[42:43], v[42:43], v[54:55]
	v_pk_mul_f32 v[34:35], v[38:39], v[34:35]
	v_cvt_pk_bf16_f32 v42, v42, v43
	v_cvt_pk_bf16_f32 v43, v44, v45
	v_pk_add_f32 v[44:45], v[46:47], 1.0 op_sel_hi:[1,0]
	v_pk_mul_f32 v[38:39], v[150:151], v[56:57] op_sel_hi:[1,0]
	v_rcp_f32_e32 v44, v44
	v_rcp_f32_e32 v45, v45
	v_pk_mul_f32 v[34:35], v[34:35], v[38:39]
	v_pk_mul_f32 v[38:39], v[148:149], v[50:51] op_sel_hi:[1,0]
	v_mad_i64_i32 v[52:53], s[26:27], v51, s46, v[162:163]
	v_pk_mul_f32 v[38:39], v[38:39], v[40:41]
	v_pk_mul_f32 v[34:35], v[34:35], v[44:45]
	v_exp_f32_e32 v38, v38
	v_exp_f32_e32 v39, v39
	v_cvt_pk_bf16_f32 v44, v34, v35
	v_cvt_f32_i32_e32 v35, v37
	v_cvt_f32_i32_e32 v34, v36
	v_pk_add_f32 v[36:37], v[38:39], 1.0 op_sel_hi:[1,0]
	v_pk_mul_f32 v[38:39], v[146:147], v[56:57] op_sel_hi:[1,0]
	v_rcp_f32_e32 v36, v36
	v_rcp_f32_e32 v37, v37
	v_pk_mul_f32 v[34:35], v[40:41], v[34:35]
	v_cvt_f32_i32_e32 v31, v31
	v_pk_mul_f32 v[34:35], v[34:35], v[38:39]
	v_cvt_f32_i32_e32 v30, v30
	v_pk_mul_f32 v[34:35], v[34:35], v[36:37]
	v_cvt_f32_i32_e32 v27, v27
	v_cvt_pk_bf16_f32 v45, v34, v35
	v_lshl_add_u64 v[34:35], v[52:53], 0, v[114:115]
	global_store_dwordx4 v[34:35], v[42:45], off sc0 sc1
	ds_read_b32 v34, v181 offset:640
	v_cvt_f32_i32_e32 v26, v26
	v_add_u32_e32 v35, s17, v174
	v_cvt_f32_i32_e32 v33, v33
	v_cvt_f32_i32_e32 v32, v32
	s_waitcnt lgkmcnt(0)
	v_pk_mul_f32 v[38:39], v[160:161], v[34:35] op_sel_hi:[1,0]
	v_mul_f32_e32 v40, v34, v34
	v_pk_mul_f32 v[38:39], v[38:39], v[30:31]
	v_pk_mul_f32 v[26:27], v[30:31], v[26:27]
	v_pk_mul_f32 v[30:31], v[158:159], v[40:41] op_sel_hi:[1,0]
	v_cvt_f32_i32_e32 v29, v29
	v_pk_mul_f32 v[26:27], v[26:27], v[30:31]
	v_pk_mul_f32 v[30:31], v[156:157], v[34:35] op_sel_hi:[1,0]
	v_cvt_f32_i32_e32 v28, v28
	v_pk_mul_f32 v[30:31], v[30:31], v[32:33]
	v_exp_f32_e32 v38, v38
	v_exp_f32_e32 v30, v30
	v_exp_f32_e32 v31, v31
	v_exp_f32_e32 v39, v39
	v_cvt_f32_i32_e32 v23, v23
	v_cvt_f32_i32_e32 v22, v22
	v_pk_add_f32 v[30:31], v[30:31], 1.0 op_sel_hi:[1,0]
	v_pk_mul_f32 v[28:29], v[32:33], v[28:29]
	v_rcp_f32_e32 v30, v30
	v_rcp_f32_e32 v31, v31
	v_pk_mul_f32 v[32:33], v[154:155], v[40:41] op_sel_hi:[1,0]
	v_pk_add_f32 v[38:39], v[38:39], 1.0 op_sel_hi:[1,0]
	v_pk_mul_f32 v[28:29], v[28:29], v[32:33]
	v_rcp_f32_e32 v38, v38
	v_pk_mul_f32 v[28:29], v[28:29], v[30:31]
	v_pk_mul_f32 v[30:31], v[152:153], v[34:35] op_sel_hi:[1,0]
	v_rcp_f32_e32 v39, v39
	v_pk_mul_f32 v[30:31], v[30:31], v[22:23]
	v_cvt_f32_i32_e32 v19, v19
	v_exp_f32_e32 v30, v30
	v_exp_f32_e32 v31, v31
	v_cvt_f32_i32_e32 v18, v18
	v_cvt_f32_i32_e32 v25, v25
	v_cvt_f32_i32_e32 v24, v24
	v_pk_mul_f32 v[26:27], v[26:27], v[38:39]
	v_pk_mul_f32 v[18:19], v[22:23], v[18:19]
	v_cvt_pk_bf16_f32 v26, v26, v27
	v_cvt_pk_bf16_f32 v27, v28, v29
	v_pk_add_f32 v[28:29], v[30:31], 1.0 op_sel_hi:[1,0]
	v_pk_mul_f32 v[22:23], v[150:151], v[40:41] op_sel_hi:[1,0]
	v_rcp_f32_e32 v28, v28
	v_rcp_f32_e32 v29, v29
	v_pk_mul_f32 v[18:19], v[18:19], v[22:23]
	v_pk_mul_f32 v[22:23], v[148:149], v[34:35] op_sel_hi:[1,0]
	v_mad_i64_i32 v[36:37], s[26:27], v35, s46, v[162:163]
	v_pk_mul_f32 v[22:23], v[22:23], v[24:25]
	v_pk_mul_f32 v[18:19], v[18:19], v[28:29]
	v_exp_f32_e32 v22, v22
	v_exp_f32_e32 v23, v23
	v_cvt_pk_bf16_f32 v28, v18, v19
	v_cvt_f32_i32_e32 v19, v21
	v_cvt_f32_i32_e32 v18, v20
	v_pk_add_f32 v[20:21], v[22:23], 1.0 op_sel_hi:[1,0]
	v_pk_mul_f32 v[22:23], v[146:147], v[40:41] op_sel_hi:[1,0]
	v_rcp_f32_e32 v20, v20
	v_rcp_f32_e32 v21, v21
	v_pk_mul_f32 v[18:19], v[24:25], v[18:19]
	v_cvt_f32_i32_e32 v15, v15
	v_pk_mul_f32 v[18:19], v[18:19], v[22:23]
	v_cvt_f32_i32_e32 v14, v14
	v_pk_mul_f32 v[18:19], v[18:19], v[20:21]
	v_cvt_f32_i32_e32 v11, v11
	v_cvt_pk_bf16_f32 v29, v18, v19
	v_lshl_add_u64 v[18:19], v[36:37], 0, v[114:115]
	global_store_dwordx4 v[18:19], v[26:29], off sc0 sc1
	ds_read_b32 v18, v181 offset:704
	v_cvt_f32_i32_e32 v10, v10
	v_add_u32_e32 v19, s17, v175
	v_cvt_f32_i32_e32 v17, v17
	v_cvt_f32_i32_e32 v16, v16
	s_waitcnt lgkmcnt(0)
	v_pk_mul_f32 v[22:23], v[160:161], v[18:19] op_sel_hi:[1,0]
	v_mul_f32_e32 v24, v18, v18
	v_pk_mul_f32 v[22:23], v[22:23], v[14:15]
	v_pk_mul_f32 v[10:11], v[14:15], v[10:11]
	v_pk_mul_f32 v[14:15], v[158:159], v[24:25] op_sel_hi:[1,0]
	v_cvt_f32_i32_e32 v13, v13
	v_pk_mul_f32 v[10:11], v[10:11], v[14:15]
	v_pk_mul_f32 v[14:15], v[156:157], v[18:19] op_sel_hi:[1,0]
	v_cvt_f32_i32_e32 v12, v12
	v_pk_mul_f32 v[14:15], v[14:15], v[16:17]
	v_exp_f32_e32 v22, v22
	v_exp_f32_e32 v14, v14
	v_exp_f32_e32 v15, v15
	v_exp_f32_e32 v23, v23
	v_cvt_f32_i32_e32 v7, v7
	v_cvt_f32_i32_e32 v6, v6
	v_pk_add_f32 v[14:15], v[14:15], 1.0 op_sel_hi:[1,0]
	v_pk_mul_f32 v[12:13], v[16:17], v[12:13]
	v_rcp_f32_e32 v14, v14
	v_rcp_f32_e32 v15, v15
	v_pk_mul_f32 v[16:17], v[154:155], v[24:25] op_sel_hi:[1,0]
	v_pk_add_f32 v[22:23], v[22:23], 1.0 op_sel_hi:[1,0]
	v_pk_mul_f32 v[12:13], v[12:13], v[16:17]
	v_rcp_f32_e32 v22, v22
	v_pk_mul_f32 v[12:13], v[12:13], v[14:15]
	v_pk_mul_f32 v[14:15], v[152:153], v[18:19] op_sel_hi:[1,0]
	v_rcp_f32_e32 v23, v23
	v_pk_mul_f32 v[14:15], v[14:15], v[6:7]
	v_cvt_f32_i32_e32 v3, v3
	v_exp_f32_e32 v14, v14
	v_exp_f32_e32 v15, v15
	v_cvt_f32_i32_e32 v2, v2
	v_cvt_f32_i32_e32 v9, v9
	v_cvt_f32_i32_e32 v8, v8
	v_pk_mul_f32 v[10:11], v[10:11], v[22:23]
	v_pk_mul_f32 v[2:3], v[6:7], v[2:3]
	v_cvt_pk_bf16_f32 v10, v10, v11
	v_cvt_pk_bf16_f32 v11, v12, v13
	v_pk_add_f32 v[12:13], v[14:15], 1.0 op_sel_hi:[1,0]
	v_pk_mul_f32 v[6:7], v[150:151], v[24:25] op_sel_hi:[1,0]
	v_rcp_f32_e32 v12, v12
	v_rcp_f32_e32 v13, v13
	v_pk_mul_f32 v[2:3], v[2:3], v[6:7]
	v_pk_mul_f32 v[6:7], v[148:149], v[18:19] op_sel_hi:[1,0]
	v_mad_i64_i32 v[20:21], s[26:27], v19, s46, v[162:163]
	v_pk_mul_f32 v[6:7], v[6:7], v[8:9]
	v_pk_mul_f32 v[2:3], v[2:3], v[12:13]
	v_exp_f32_e32 v6, v6
	v_exp_f32_e32 v7, v7
	v_cvt_pk_bf16_f32 v12, v2, v3
	v_cvt_f32_i32_e32 v3, v5
	v_cvt_f32_i32_e32 v2, v4
	v_pk_add_f32 v[4:5], v[6:7], 1.0 op_sel_hi:[1,0]
	v_pk_mul_f32 v[6:7], v[146:147], v[24:25] op_sel_hi:[1,0]
	v_rcp_f32_e32 v4, v4
	v_rcp_f32_e32 v5, v5
	v_pk_mul_f32 v[2:3], v[8:9], v[2:3]
	s_andn2_b64 vcc, exec, s[0:1]
	v_pk_mul_f32 v[2:3], v[2:3], v[6:7]
	s_mov_b64 s[0:1], -1
	v_pk_mul_f32 v[2:3], v[2:3], v[4:5]
	s_nop 0
	v_cvt_pk_bf16_f32 v13, v2, v3
	v_lshl_add_u64 v[2:3], v[20:21], 0, v[114:115]
	global_store_dwordx4 v[2:3], v[10:13], off sc0 sc1
	s_cbranch_vccnz .LBB0_3383
	s_andn2_b64 vcc, exec, s[10:11]
	s_cbranch_vccnz .LBB0_3382
	s_barrier
	s_branch .LBB0_3382

.LBB0_3400:
	s_ashr_i32 s0, s6, 31
	s_lshr_b32 s0, s0, 26
	s_add_i32 s0, s6, s0
	s_lshl_b32 s1, s0, 5
	s_and_b32 s4, s0, 0xffffffc0
	s_and_b32 s0, s1, 0xfffff800
	v_or_b32_e32 v24, s4, v6
	s_sub_i32 s0, s8, s0
	v_ashrrev_i32_e32 v25, 31, v24
	v_or_b32_e32 v26, 8, v24
	v_or_b32_e32 v28, 16, v24
	v_or_b32_e32 v30, 24, v24
	v_or_b32_e32 v32, 32, v24
	v_or_b32_e32 v34, 40, v24
	v_or_b32_e32 v36, 48, v24
	v_or_b32_e32 v38, 56, v24
	s_ashr_i32 s1, s0, 31
	v_lshlrev_b64 v[24:25], 13, v[24:25]
	v_ashrrev_i32_e32 v27, 31, v26
	v_ashrrev_i32_e32 v29, 31, v28
	v_ashrrev_i32_e32 v31, 31, v30
	v_ashrrev_i32_e32 v33, 31, v32
	v_ashrrev_i32_e32 v35, 31, v34
	v_ashrrev_i32_e32 v37, 31, v36
	v_ashrrev_i32_e32 v39, 31, v38
	v_lshl_add_u64 v[40:41], s[0:1], 2, v[2:3]
	v_lshlrev_b64 v[26:27], 13, v[26:27]
	v_lshlrev_b64 v[28:29], 13, v[28:29]
	v_lshlrev_b64 v[30:31], 13, v[30:31]
	v_lshlrev_b64 v[32:33], 13, v[32:33]
	v_lshlrev_b64 v[34:35], 13, v[34:35]
	v_lshlrev_b64 v[36:37], 13, v[36:37]
	v_lshlrev_b64 v[38:39], 13, v[38:39]
	v_lshl_add_u64 v[56:57], v[40:41], 0, v[24:25]
	v_lshl_add_u64 v[58:59], v[40:41], 0, v[26:27]
	v_lshl_add_u64 v[60:61], v[40:41], 0, v[28:29]
	v_lshl_add_u64 v[62:63], v[40:41], 0, v[30:31]
	v_lshl_add_u64 v[64:65], v[40:41], 0, v[32:33]
	v_lshl_add_u64 v[66:67], v[40:41], 0, v[34:35]
	v_lshl_add_u64 v[68:69], v[40:41], 0, v[36:37]
	v_lshl_add_u64 v[70:71], v[40:41], 0, v[38:39]
	global_load_dwordx4 v[24:27], v[56:57], off nt
	global_load_dwordx4 v[28:31], v[58:59], off nt
	global_load_dwordx4 v[32:35], v[60:61], off nt
	global_load_dwordx4 v[36:39], v[62:63], off nt
	global_load_dwordx4 v[40:43], v[64:65], off nt
	global_load_dwordx4 v[44:47], v[66:67], off nt
	global_load_dwordx4 v[48:51], v[68:69], off nt
	global_load_dwordx4 v[52:55], v[70:71], off nt
	s_ashr_i32 s5, s4, 31
	v_lshl_add_u64 v[56:57], s[4:5], 1, v[4:5]
	v_add_u32_e32 v64, s0, v6
	v_mad_i64_i32 v[58:59], s[0:1], v64, s10, v[56:57]
	v_add_u32_e32 v60, 8, v64
	v_mad_i64_i32 v[60:61], s[0:1], v60, s10, v[56:57]
	v_add_u32_e32 v62, 16, v64
	v_mad_i64_i32 v[62:63], s[0:1], v62, s10, v[56:57]
	s_add_i32 s6, s6, s7
	s_add_i32 s8, s8, s9
	s_cmpk_lt_i32 s6, 0x1600
	s_waitcnt vmcnt(0)
	ds_write2_b32 v9, v24, v25 offset1:1
	ds_write2_b32 v9, v26, v27 offset0:2 offset1:3
	ds_write2_b32 v10, v28, v29 offset1:1
	ds_write2_b32 v11, v30, v31 offset1:1
	ds_write2_b32 v12, v32, v33 offset1:1
	ds_write2_b32 v13, v34, v35 offset1:1
	ds_write2_b32 v14, v36, v37 offset1:1
	ds_write2_b32 v15, v38, v39 offset1:1
	ds_write2_b32 v16, v40, v41 offset1:1
	ds_write2_b32 v17, v42, v43 offset1:1
	ds_write2_b32 v18, v44, v45 offset1:1
	ds_write2_b32 v19, v46, v47 offset1:1
	ds_write2_b32 v20, v48, v49 offset1:1
	ds_write2_b32 v21, v50, v51 offset1:1
	ds_write2_b32 v22, v52, v53 offset1:1
	ds_write2_b32 v23, v54, v55 offset1:1
	s_waitcnt lgkmcnt(0)
	ds_read2_b32 v[24:25], v1 offset1:33
	s_waitcnt lgkmcnt(0)
	v_cvt_pk_bf16_f32 v24, v24, v25
	ds_read2_b32 v[26:27], v1 offset0:66 offset1:99
	s_waitcnt lgkmcnt(0)
	v_cvt_pk_bf16_f32 v25, v26, v27
	ds_read2_b32 v[26:27], v1 offset0:132 offset1:165
	s_waitcnt lgkmcnt(0)
	v_cvt_pk_bf16_f32 v26, v26, v27
	ds_read2_b32 v[28:29], v1 offset0:198 offset1:231
	s_waitcnt lgkmcnt(0)
	v_cvt_pk_bf16_f32 v27, v28, v29
	ds_read2_b32 v[28:29], v1 offset0:8 offset1:41
	global_store_dwordx4 v[58:59], v[24:27], off sc0 sc1
	s_waitcnt lgkmcnt(0)
	s_nop 0
	v_cvt_pk_bf16_f32 v24, v28, v29
	ds_read2_b32 v[26:27], v1 offset0:74 offset1:107
	s_waitcnt lgkmcnt(0)
	v_cvt_pk_bf16_f32 v25, v26, v27
	ds_read2_b32 v[26:27], v1 offset0:140 offset1:173
	s_waitcnt lgkmcnt(0)
	v_cvt_pk_bf16_f32 v26, v26, v27
	ds_read2_b32 v[28:29], v1 offset0:206 offset1:239
	s_waitcnt lgkmcnt(0)
	v_cvt_pk_bf16_f32 v27, v28, v29
	ds_read2_b32 v[28:29], v1 offset0:16 offset1:49
	global_store_dwordx4 v[60:61], v[24:27], off sc0 sc1
	s_waitcnt lgkmcnt(0)
	s_nop 0
	v_cvt_pk_bf16_f32 v24, v28, v29
	ds_read2_b32 v[26:27], v1 offset0:82 offset1:115
	s_waitcnt lgkmcnt(0)
	v_cvt_pk_bf16_f32 v25, v26, v27
	ds_read2_b32 v[26:27], v1 offset0:148 offset1:181
	s_waitcnt lgkmcnt(0)
	v_cvt_pk_bf16_f32 v26, v26, v27
	ds_read2_b32 v[28:29], v1 offset0:214 offset1:247
	s_waitcnt lgkmcnt(0)
	v_cvt_pk_bf16_f32 v27, v28, v29
	ds_read2_b32 v[28:29], v1 offset0:24 offset1:57
	global_store_dwordx4 v[62:63], v[24:27], off sc0 sc1
	s_waitcnt lgkmcnt(0)
	s_nop 0
	v_cvt_pk_bf16_f32 v24, v28, v29
	ds_read2_b32 v[26:27], v1 offset0:90 offset1:123
	s_waitcnt lgkmcnt(0)
	v_cvt_pk_bf16_f32 v25, v26, v27
	ds_read2_b32 v[26:27], v1 offset0:156 offset1:189
	s_waitcnt lgkmcnt(0)
	v_cvt_pk_bf16_f32 v26, v26, v27
	v_add_u32_e32 v27, 24, v64
	v_mad_i64_i32 v[30:31], s[0:1], v27, s10, v[56:57]
	ds_read2_b32 v[28:29], v1 offset0:222 offset1:255
	s_waitcnt lgkmcnt(0)
	v_cvt_pk_bf16_f32 v27, v28, v29
	global_store_dwordx4 v[30:31], v[24:27], off sc0 sc1
	s_waitcnt lgkmcnt(0)
	s_cbranch_scc1 .LBB0_3400

.LBB0_3405:
	s_ashr_i32 s0, s6, 31
	s_lshr_b32 s0, s0, 26
	s_add_i32 s0, s6, s0
	s_lshl_b32 s1, s0, 5
	s_and_b32 s4, s0, 0xffffffc0
	s_and_b32 s0, s1, 0xfffff800
	v_or_b32_e32 v22, s4, v6
	s_sub_i32 s0, s8, s0
	v_ashrrev_i32_e32 v23, 31, v22
	v_or_b32_e32 v24, 8, v22
	v_or_b32_e32 v26, 16, v22
	v_or_b32_e32 v28, 24, v22
	v_or_b32_e32 v30, 32, v22
	v_or_b32_e32 v32, 40, v22
	v_or_b32_e32 v34, 48, v22
	v_or_b32_e32 v36, 56, v22
	s_ashr_i32 s1, s0, 31
	v_lshlrev_b64 v[22:23], 13, v[22:23]
	v_ashrrev_i32_e32 v25, 31, v24
	v_ashrrev_i32_e32 v27, 31, v26
	v_ashrrev_i32_e32 v29, 31, v28
	v_ashrrev_i32_e32 v31, 31, v30
	v_ashrrev_i32_e32 v33, 31, v32
	v_ashrrev_i32_e32 v35, 31, v34
	v_ashrrev_i32_e32 v37, 31, v36
	v_lshl_add_u64 v[38:39], s[0:1], 2, v[2:3]
	v_lshlrev_b64 v[24:25], 13, v[24:25]
	v_lshlrev_b64 v[26:27], 13, v[26:27]
	v_lshlrev_b64 v[28:29], 13, v[28:29]
	v_lshlrev_b64 v[30:31], 13, v[30:31]
	v_lshlrev_b64 v[32:33], 13, v[32:33]
	v_lshlrev_b64 v[34:35], 13, v[34:35]
	v_lshlrev_b64 v[36:37], 13, v[36:37]
	v_lshl_add_u64 v[54:55], v[38:39], 0, v[22:23]
	v_lshl_add_u64 v[56:57], v[38:39], 0, v[24:25]
	v_lshl_add_u64 v[58:59], v[38:39], 0, v[26:27]
	v_lshl_add_u64 v[60:61], v[38:39], 0, v[28:29]
	v_lshl_add_u64 v[62:63], v[38:39], 0, v[30:31]
	v_lshl_add_u64 v[64:65], v[38:39], 0, v[32:33]
	v_lshl_add_u64 v[66:67], v[38:39], 0, v[34:35]
	v_lshl_add_u64 v[68:69], v[38:39], 0, v[36:37]
	global_load_dwordx4 v[22:25], v[54:55], off nt
	global_load_dwordx4 v[26:29], v[56:57], off nt
	global_load_dwordx4 v[30:33], v[58:59], off nt
	global_load_dwordx4 v[34:37], v[60:61], off nt
	global_load_dwordx4 v[38:41], v[62:63], off nt
	global_load_dwordx4 v[42:45], v[64:65], off nt
	global_load_dwordx4 v[46:49], v[66:67], off nt
	global_load_dwordx4 v[50:53], v[68:69], off nt
	s_ashr_i32 s5, s4, 31
	v_lshl_add_u64 v[54:55], s[4:5], 1, v[4:5]
	v_add_u32_e32 v62, s0, v6
	v_mad_i64_i32 v[56:57], s[0:1], v62, s9, v[54:55]
	v_add_u32_e32 v58, 8, v62
	v_mad_i64_i32 v[58:59], s[0:1], v58, s9, v[54:55]
	v_add_u32_e32 v60, 16, v62
	v_mad_i64_i32 v[60:61], s[0:1], v60, s9, v[54:55]
	s_add_i32 s6, s6, s7
	s_add_i32 s8, s8, s3
	s_cmpk_gt_i32 s6, 0x15ff
	s_waitcnt vmcnt(0)
	ds_write2_b32 v7, v22, v23 offset1:1
	ds_write2_b32 v7, v24, v25 offset0:2 offset1:3
	ds_write2_b32 v8, v26, v27 offset1:1
	ds_write2_b32 v9, v28, v29 offset1:1
	ds_write2_b32 v10, v30, v31 offset1:1
	ds_write2_b32 v11, v32, v33 offset1:1
	ds_write2_b32 v12, v34, v35 offset1:1
	ds_write2_b32 v13, v36, v37 offset1:1
	ds_write2_b32 v14, v38, v39 offset1:1
	ds_write2_b32 v15, v40, v41 offset1:1
	ds_write2_b32 v16, v42, v43 offset1:1
	ds_write2_b32 v17, v44, v45 offset1:1
	ds_write2_b32 v18, v46, v47 offset1:1
	ds_write2_b32 v19, v48, v49 offset1:1
	ds_write2_b32 v20, v50, v51 offset1:1
	ds_write2_b32 v21, v52, v53 offset1:1
	s_waitcnt lgkmcnt(0)
	ds_read2_b32 v[22:23], v1 offset1:33
	s_waitcnt lgkmcnt(0)
	v_cvt_pk_bf16_f32 v22, v22, v23
	ds_read2_b32 v[24:25], v1 offset0:66 offset1:99
	s_waitcnt lgkmcnt(0)
	v_cvt_pk_bf16_f32 v23, v24, v25
	ds_read2_b32 v[24:25], v1 offset0:132 offset1:165
	s_waitcnt lgkmcnt(0)
	v_cvt_pk_bf16_f32 v24, v24, v25
	ds_read2_b32 v[26:27], v1 offset0:198 offset1:231
	s_waitcnt lgkmcnt(0)
	v_cvt_pk_bf16_f32 v25, v26, v27
	ds_read2_b32 v[26:27], v1 offset0:8 offset1:41
	global_store_dwordx4 v[56:57], v[22:25], off sc0 sc1
	s_waitcnt lgkmcnt(0)
	s_nop 0
	v_cvt_pk_bf16_f32 v22, v26, v27
	ds_read2_b32 v[24:25], v1 offset0:74 offset1:107
	s_waitcnt lgkmcnt(0)
	v_cvt_pk_bf16_f32 v23, v24, v25
	ds_read2_b32 v[24:25], v1 offset0:140 offset1:173
	s_waitcnt lgkmcnt(0)
	v_cvt_pk_bf16_f32 v24, v24, v25
	ds_read2_b32 v[26:27], v1 offset0:206 offset1:239
	s_waitcnt lgkmcnt(0)
	v_cvt_pk_bf16_f32 v25, v26, v27
	ds_read2_b32 v[26:27], v1 offset0:16 offset1:49
	global_store_dwordx4 v[58:59], v[22:25], off sc0 sc1
	s_waitcnt lgkmcnt(0)
	s_nop 0
	v_cvt_pk_bf16_f32 v22, v26, v27
	ds_read2_b32 v[24:25], v1 offset0:82 offset1:115
	s_waitcnt lgkmcnt(0)
	v_cvt_pk_bf16_f32 v23, v24, v25
	ds_read2_b32 v[24:25], v1 offset0:148 offset1:181
	s_waitcnt lgkmcnt(0)
	v_cvt_pk_bf16_f32 v24, v24, v25
	ds_read2_b32 v[26:27], v1 offset0:214 offset1:247
	s_waitcnt lgkmcnt(0)
	v_cvt_pk_bf16_f32 v25, v26, v27
	ds_read2_b32 v[26:27], v1 offset0:24 offset1:57
	global_store_dwordx4 v[60:61], v[22:25], off sc0 sc1
	s_waitcnt lgkmcnt(0)
	s_nop 0
	v_cvt_pk_bf16_f32 v22, v26, v27
	ds_read2_b32 v[24:25], v1 offset0:90 offset1:123
	s_waitcnt lgkmcnt(0)
	v_cvt_pk_bf16_f32 v23, v24, v25
	ds_read2_b32 v[24:25], v1 offset0:156 offset1:189
	s_waitcnt lgkmcnt(0)
	v_cvt_pk_bf16_f32 v24, v24, v25
	v_add_u32_e32 v25, 24, v62
	v_mad_i64_i32 v[28:29], s[0:1], v25, s9, v[54:55]
	ds_read2_b32 v[26:27], v1 offset0:222 offset1:255
	s_waitcnt lgkmcnt(0)
	v_cvt_pk_bf16_f32 v25, v26, v27
	global_store_dwordx4 v[28:29], v[22:25], off sc0 sc1
	s_waitcnt lgkmcnt(0)
	s_cbranch_scc0 .LBB0_3405
